# conv-gelu GEMM epilogue: weight-load waits hoisted out of the 16 exec-guarded blocks (no per-block vmcnt0), dead zero-inits before full-lane DPP movs removed
# speedup vs baseline: 1.0686x; 1.0081x over previous
; __device__ __forceinline__ float sigmoidf_(float x) { return __builtin_amdgcn_rcpf(1.0f + __expf(-x)); }
;     __device__ __forceinline__ void operator()(const f32x4 (&acc)[2][2][4][2], const Unit& u, int wr, int wc, int fr, int fq) const {
;         unsigned char* ws = kp->ws;
;         const float* cw = kp->in[27] + (size_t)l * 3 * 5632; const float* cb = kp->in[28] + (size_t)l * 5632;
; #pragma unroll
;         for (int bj = 0; bj < 2; ++bj) { const int J = u.pn * 128 + bj * 64 + wc * 16 + 4 * fq;
;             const f32x4 wg0 = *(const f32x4*)(cw + J), wg1 = *(const f32x4*)(cw + 5632 + J), wg2 = *(const f32x4*)(cw + 11264 + J), bgv = *(const f32x4*)(cb + J);
;             const f32x4 wv0 = *(const f32x4*)(cw + DFF + J), wv1 = *(const f32x4*)(cw + 5632 + DFF + J), wv2 = *(const f32x4*)(cw + 11264 + DFF + J), bvv = *(const f32x4*)(cb + DFF + J);
; #pragma unroll
;             for (int ai = 0; ai < 2; ++ai) { const int tb = u.pm * 248 + 62 * (ai * 2 + wr) - 1;
; #pragma unroll
;                 for (int m = 0; m < 4; ++m) { const int r = 16 * m + fr, t = tb + r, pos = t & (L - 1);
;                     const bool hp = pos != 0, hn = pos != L - 1, valid = (r >= 1) & (r <= 62) & (t < TCH);
;                     float out[4];
; #pragma unroll
;                     for (int e = 0; e < 4; ++e) {
;                         const float xg = acc[ai][bj][m][0][e], xv = acc[ai][bj][m][1][e];
;                         float pg = dppf(m > 0 ? dppf(0.f, acc[ai][bj][m > 0 ? m - 1 : 0][0][e], 2) : 0.f, xg, 0);
;                         float ng = dppf(m < 3 ? dppf(0.f, acc[ai][bj][m < 3 ? m + 1 : 3][0][e], 3) : 0.f, xg, 1);
;                         float pv = dppf(m > 0 ? dppf(0.f, acc[ai][bj][m > 0 ? m - 1 : 0][1][e], 2) : 0.f, xv, 0);
;                         float nv = dppf(m < 3 ? dppf(0.f, acc[ai][bj][m < 3 ? m + 1 : 3][1][e], 3) : 0.f, xv, 1);
;                         if (!hp) { pg = 0.f; pv = 0.f; }
;                         if (!hn) { ng = 0.f; nv = 0.f; }
;                         const float hg = wg0[e] * pg + wg1[e] * xg + wg2[e] * ng + bgv[e], hv = wv0[e] * pv + wv1[e] * xv + wv2[e] * nv + bvv[e];
;                         out[e] = hg * sigmoidf_(1.5957691216f * (hg + 0.044715f * hg * hg * hg)) * hv; }
.LBB0_288:
	s_and_b64 vcc, exec, s[14:15]
	s_cbranch_vccz .LBB0_327
	s_cmp_gt_i32 s53, 9
	s_mov_b64 s[14:15], -1
	s_cbranch_scc0 .LBB0_325
	s_cmp_eq_u32 s53, 10
	s_mov_b64 s[12:13], -1
	s_cbranch_scc0 .LBB0_324
	v_readlane_b32 s16, v249, 54
	v_readlane_b32 s17, v249, 55
	s_load_dwordx4 s[12:15], s[16:17], 0xd8
	v_readlane_b32 s16, v249, 49
	v_lshl_or_b32 v2, s44, 7, v199
	v_ashrrev_i32_e32 v3, 31, v2
	v_lshlrev_b64 v[132:133], 2, v[2:3]
	s_waitcnt lgkmcnt(0)
	s_add_u32 s12, s12, s16
	s_addc_u32 s13, s13, 0
	v_readlane_b32 s16, v249, 50
	s_add_u32 s14, s14, s16
	s_addc_u32 s15, s15, 0
	s_add_u32 s56, s12, 0x5800
	s_addc_u32 s57, s13, 0
	s_add_u32 s58, s12, 0xb000
	s_addc_u32 s59, s13, 0
	s_add_u32 s76, s12, 0x2c00
	s_addc_u32 s77, s13, 0
	s_add_u32 s88, s12, 0x8400
	s_addc_u32 s89, s13, 0
	s_add_u32 s72, s12, 0xdc00
	s_addc_u32 s73, s13, 0
	v_lshl_add_u64 v[176:177], s[12:13], 0, v[132:133]
	s_add_u32 s74, s14, 0x2c00
	v_lshl_add_u64 v[134:135], s[56:57], 0, v[132:133]
	s_addc_u32 s75, s15, 0
	global_load_dwordx4 v[152:155], v[176:177], off
	v_lshl_add_u64 v[136:137], s[58:59], 0, v[132:133]
	global_load_dwordx4 v[160:163], v[134:135], off
	global_load_dwordx4 v[148:151], v[136:137], off
	v_lshl_add_u64 v[178:179], s[14:15], 0, v[132:133]
	v_lshl_add_u64 v[134:135], s[76:77], 0, v[132:133]
	global_load_dwordx4 v[144:147], v[178:179], off
	v_lshl_add_u64 v[136:137], s[88:89], 0, v[132:133]
	global_load_dwordx4 v[140:143], v[134:135], off
	global_load_dwordx4 v[156:159], v[136:137], off
	v_lshl_add_u64 v[134:135], s[72:73], 0, v[132:133]
	v_lshl_add_u64 v[132:133], s[74:75], 0, v[132:133]
	global_load_dwordx4 v[136:139], v[134:135], off
	s_mul_i32 s20, s61, 0xf8
	global_load_dwordx4 v[132:135], v[132:133], off
	v_readlane_b32 s12, v249, 60
	s_add_i32 s20, s20, s12
	s_add_i32 s21, s20, -1
	v_add_u32_e32 v219, s21, v195
	s_mov_b32 s12, 0x8000
	v_cmp_gt_i32_e32 vcc, s12, v219
	v_readlane_b32 s12, v249, 61
	v_readlane_b32 s13, v249, 62
	v_mov_b32_e32 v216, 0
	v_mov_b32_dpp v214, v56 row_ror:15 row_mask:0xf bank_mask:0xf
	v_mov_b32_e32 v209, 0
	v_mov_b32_dpp v207, v60 row_ror:15 row_mask:0xf bank_mask:0xf
	v_mov_b32_e32 v213, 0
	v_mov_b32_dpp v212, v57 row_ror:15 row_mask:0xf bank_mask:0xf
	v_mov_b32_e32 v3, 0
	v_mov_b32_dpp v0, v61 row_ror:15 row_mask:0xf bank_mask:0xf
	v_mov_b32_e32 v221, 0
	v_mov_b32_dpp v218, v58 row_ror:15 row_mask:0xf bank_mask:0xf
	v_mov_b32_e32 v211, 0
	v_mov_b32_dpp v210, v62 row_ror:15 row_mask:0xf bank_mask:0xf
	v_mov_b32_e32 v217, 0
	v_mov_b32_dpp v215, v59 row_ror:15 row_mask:0xf bank_mask:0xf
	v_mov_b32_e32 v208, 0
	v_mov_b32_dpp v206, v63 row_ror:15 row_mask:0xf bank_mask:0xf
	s_and_b64 s[78:79], s[12:13], vcc
	s_movk_i32 s12, 0xb00
	v_mov_b32_dpp v216, v48 row_shr:1 row_mask:0xf bank_mask:0xf
	v_mov_b32_dpp v214, v48 row_shl:1 row_mask:0xf bank_mask:0xf
	v_mov_b32_dpp v209, v52 row_shr:1 row_mask:0xf bank_mask:0xf
	v_mov_b32_dpp v207, v52 row_shl:1 row_mask:0xf bank_mask:0xf
	v_mov_b32_dpp v213, v49 row_shr:1 row_mask:0xf bank_mask:0xf
	v_mov_b32_dpp v212, v49 row_shl:1 row_mask:0xf bank_mask:0xf
	v_mov_b32_dpp v3, v53 row_shr:1 row_mask:0xf bank_mask:0xf
	v_mov_b32_dpp v0, v53 row_shl:1 row_mask:0xf bank_mask:0xf
	v_mov_b32_dpp v221, v50 row_shr:1 row_mask:0xf bank_mask:0xf
	v_mov_b32_dpp v218, v50 row_shl:1 row_mask:0xf bank_mask:0xf
	v_mov_b32_dpp v211, v54 row_shr:1 row_mask:0xf bank_mask:0xf
	v_mov_b32_dpp v210, v54 row_shl:1 row_mask:0xf bank_mask:0xf
	v_mov_b32_dpp v217, v51 row_shr:1 row_mask:0xf bank_mask:0xf
	v_mov_b32_dpp v215, v51 row_shl:1 row_mask:0xf bank_mask:0xf
	v_mov_b32_dpp v208, v55 row_shr:1 row_mask:0xf bank_mask:0xf
	v_mov_b32_dpp v206, v55 row_shl:1 row_mask:0xf bank_mask:0xf
	v_and_b32_e32 v220, s52, v219
	v_mul_lo_u32 v219, v219, s12
	s_waitcnt vmcnt(0)
	s_and_saveexec_b64 s[14:15], s[78:79]
	s_cbranch_execz .LBB0_293
	v_pk_mul_f32 v[222:223], v[50:51], v[162:163]
	v_pk_mul_f32 v[224:225], v[48:49], v[160:161]
	v_cmp_eq_u32_e32 vcc, 0, v220
	v_mov_b32_e32 v226, v224
	v_mov_b32_e32 v227, v222
	v_cndmask_b32_e64 v229, v221, 0, vcc
	v_mov_b32_e32 v222, v225
	v_cndmask_b32_e64 v228, v216, 0, vcc
	v_mov_b32_e32 v224, v152
	v_mov_b32_e32 v225, v154
	v_cmp_eq_u32_e64 s[12:13], s52, v220
	v_pk_fma_f32 v[224:225], v[224:225], v[228:229], v[226:227]
	v_mov_b32_e32 v228, v148
	v_cndmask_b32_e64 v227, v218, 0, s[12:13]
	v_cndmask_b32_e64 v226, v214, 0, s[12:13]
	v_mov_b32_e32 v229, v150
	v_pk_fma_f32 v[224:225], v[228:229], v[226:227], v[224:225]
	v_mov_b32_e32 v226, v144
	v_mov_b32_e32 v227, v146
	v_pk_add_f32 v[224:225], v[226:227], v[224:225]
	v_cndmask_b32_e64 v216, v213, 0, vcc
	v_mul_f32_e32 v214, 0x3d372713, v225
	v_mul_f32_e32 v214, v225, v214
	v_fma_f32 v214, v225, v214, v225
	v_mul_f32_e32 v214, 0x3fcc422a, v214
	v_mul_f32_e32 v214, 0xbfb8aa3b, v214
	v_exp_f32_e32 v214, v214
	v_cndmask_b32_e64 v217, v217, 0, vcc
	v_mov_b32_e32 v226, v153
	v_mov_b32_e32 v227, v155
	v_add_f32_e32 v213, 1.0, v214
	v_pk_fma_f32 v[216:217], v[226:227], v[216:217], v[222:223]
	v_cndmask_b32_e64 v215, v215, 0, s[12:13]
	v_cndmask_b32_e64 v214, v212, 0, s[12:13]
	v_mov_b32_e32 v222, v149
	v_mov_b32_e32 v223, v151
	v_pk_fma_f32 v[214:215], v[222:223], v[214:215], v[216:217]
	v_mov_b32_e32 v216, v145
	v_mov_b32_e32 v217, v147
	v_pk_add_f32 v[214:215], v[216:217], v[214:215]
	v_mul_f32_e32 v216, 0x3d372713, v224
	v_mul_f32_e32 v216, v224, v216
	v_fma_f32 v216, v224, v216, v224
	v_mul_f32_e32 v216, 0x3fcc422a, v216
	v_mul_f32_e32 v212, 0x3d372713, v214
	v_mul_f32_e32 v216, 0xbfb8aa3b, v216
	v_cndmask_b32_e64 v223, v211, 0, vcc
	v_cndmask_b32_e64 v211, v210, 0, s[12:13]
	v_cndmask_b32_e64 v210, v207, 0, s[12:13]
; __device__ __forceinline__ unsigned pack2(float lo, float hi) { return (unsigned)f2bf(lo) | ((unsigned)f2bf(hi) << 16); }
; __device__ __forceinline__ float sigmoidf_(float x) { return __builtin_amdgcn_rcpf(1.0f + __expf(-x)); }
;     __device__ __forceinline__ void operator()(const f32x4 (&acc)[2][2][4][2], const Unit& u, int wr, int wc, int fr, int fq) const {
;     ...
;                 for (int m = 0; m < 4; ++m) { const int r = 16 * m + fr, t = tb + r, pos = t & (L - 1);
;                     const bool hp = pos != 0, hn = pos != L - 1, valid = (r >= 1) & (r <= 62) & (t < TCH);
;                     float out[4];
; #pragma unroll
;                     for (int e = 0; e < 4; ++e) {
;                         const float xg = acc[ai][bj][m][0][e], xv = acc[ai][bj][m][1][e];
;                         float pg = dppf(m > 0 ? dppf(0.f, acc[ai][bj][m > 0 ? m - 1 : 0][0][e], 2) : 0.f, xg, 0);
;                         float ng = dppf(m < 3 ? dppf(0.f, acc[ai][bj][m < 3 ? m + 1 : 3][0][e], 3) : 0.f, xg, 1);
;                         float pv = dppf(m > 0 ? dppf(0.f, acc[ai][bj][m > 0 ? m - 1 : 0][1][e], 2) : 0.f, xv, 0);
;                         float nv = dppf(m < 3 ? dppf(0.f, acc[ai][bj][m < 3 ? m + 1 : 3][1][e], 3) : 0.f, xv, 1);
;                         if (!hp) { pg = 0.f; pv = 0.f; }
;                         if (!hn) { ng = 0.f; nv = 0.f; }
;                         const float hg = wg0[e] * pg + wg1[e] * xg + wg2[e] * ng + bgv[e], hv = wv0[e] * pv + wv1[e] * xv + wv2[e] * nv + bvv[e];
;                         out[e] = hg * sigmoidf_(1.5957691216f * (hg + 0.044715f * hg * hg * hg)) * hv; }
;                     if (valid) { uint2 o; o.x = pack2(out[0], out[1]); o.y = pack2(out[2], out[3]); *(uint2*)(ws + (unsigned)OFF_S + ((unsigned)t * (unsigned)DFF + (unsigned)J) * 2u) = o; }
;                     __builtin_amdgcn_sched_barrier(0); } } }
	v_mul_f32_e32 v207, 0x3d372713, v215
	v_mul_f32_e32 v212, v214, v212
	v_exp_f32_e32 v216, v216
	v_mul_f32_e32 v207, v215, v207
	v_fma_f32 v212, v214, v212, v214
	v_fma_f32 v207, v215, v207, v215
	v_mul_f32_e32 v212, 0x3fcc422a, v212
	v_mul_f32_e32 v207, 0x3fcc422a, v207
	v_mul_f32_e32 v212, 0xbfb8aa3b, v212
	v_mul_f32_e32 v207, 0xbfb8aa3b, v207
	v_exp_f32_e32 v217, v212
	v_add_f32_e32 v212, 1.0, v216
	v_exp_f32_e32 v207, v207
	v_rcp_f32_e32 v213, v213
	v_rcp_f32_e32 v212, v212
	v_pk_mul_f32 v[230:231], v[54:55], v[158:159]
	v_pk_mul_f32 v[232:233], v[52:53], v[156:157]
	v_add_f32_e32 v216, 1.0, v217
	v_add_f32_e32 v207, 1.0, v207
	v_mov_b32_e32 v234, v232
	v_mov_b32_e32 v235, v230
	v_rcp_f32_e32 v216, v216
	v_pk_mul_f32 v[212:213], v[224:225], v[212:213]
	v_cndmask_b32_e64 v222, v209, 0, vcc
	v_mov_b32_e32 v224, v140
	v_mov_b32_e32 v225, v142
	v_rcp_f32_e32 v217, v207
	v_pk_fma_f32 v[222:223], v[224:225], v[222:223], v[234:235]
	v_mov_b32_e32 v224, v136
	v_mov_b32_e32 v225, v138
	v_pk_fma_f32 v[210:211], v[224:225], v[210:211], v[222:223]
	v_mov_b32_e32 v222, v132
	v_mov_b32_e32 v223, v134
	v_pk_add_f32 v[210:211], v[222:223], v[210:211]
	v_mov_b32_e32 v230, v233
	v_pk_mul_f32 v[210:211], v[210:211], v[212:213]
	v_pk_mul_f32 v[212:213], v[214:215], v[216:217]
	v_cndmask_b32_e64 v209, v208, 0, vcc
	v_cndmask_b32_e64 v208, v3, 0, vcc
	v_mov_b32_e32 v214, v141
	v_mov_b32_e32 v215, v143
	v_pk_fma_f32 v[208:209], v[214:215], v[208:209], v[230:231]
	v_cndmask_b32_e64 v207, v206, 0, s[12:13]
	v_cndmask_b32_e64 v206, v0, 0, s[12:13]
	v_mov_b32_e32 v214, v137
	v_mov_b32_e32 v215, v139
	v_pk_fma_f32 v[206:207], v[214:215], v[206:207], v[208:209]
	v_mov_b32_e32 v208, v133
	v_mov_b32_e32 v209, v135
	v_pk_add_f32 v[206:207], v[208:209], v[206:207]
	v_and_b32_sdwa v0, v211, v185 dst_sel:DWORD dst_unused:UNUSED_PAD src0_sel:WORD_1 src1_sel:DWORD
	v_pk_mul_f32 v[206:207], v[206:207], v[212:213]
	v_and_b32_sdwa v3, v210, v185 dst_sel:DWORD dst_unused:UNUSED_PAD src0_sel:WORD_1 src1_sel:DWORD
	v_and_b32_sdwa v208, v207, v185 dst_sel:DWORD dst_unused:UNUSED_PAD src0_sel:WORD_1 src1_sel:DWORD
	v_and_b32_sdwa v209, v206, v185 dst_sel:DWORD dst_unused:UNUSED_PAD src0_sel:WORD_1 src1_sel:DWORD
	v_add3_u32 v207, v207, v208, s46
	v_add3_u32 v206, v206, v209, s46
	v_add3_u32 v3, v210, v3, s46
	v_add3_u32 v0, v211, v0, s46
	v_and_b32_e32 v207, 0xffff0000, v207
	v_and_b32_e32 v206, 0xffff0000, v206
	v_readlane_b32 s12, v249, 20
	v_add_lshl_u32 v218, v219, v2, 1
	v_or_b32_sdwa v207, v207, v0 dst_sel:DWORD dst_unused:UNUSED_PAD src0_sel:DWORD src1_sel:WORD_1
	v_or_b32_sdwa v206, v206, v3 dst_sel:DWORD dst_unused:UNUSED_PAD src0_sel:DWORD src1_sel:WORD_1
	v_readlane_b32 s13, v249, 21
	s_nop 4
	global_store_dwordx2 v218, v[206:207], s[12:13]
.LBB0_293:
	s_or_b64 exec, exec, s[14:15]
	v_add_u32_e32 v217, s21, v200
	s_mov_b32 s12, 0x8000
	v_cmp_gt_i32_e64 s[16:17], s12, v217
	v_mov_b32_dpp v215, v48 row_ror:1 row_mask:0xf bank_mask:0xf
	v_mov_b32_dpp v214, v64 row_ror:15 row_mask:0xf bank_mask:0xf
	v_mov_b32_dpp v207, v52 row_ror:1 row_mask:0xf bank_mask:0xf
	v_mov_b32_dpp v206, v68 row_ror:15 row_mask:0xf bank_mask:0xf
	v_mov_b32_dpp v213, v49 row_ror:1 row_mask:0xf bank_mask:0xf
	v_mov_b32_dpp v212, v65 row_ror:15 row_mask:0xf bank_mask:0xf
	v_mov_b32_dpp v3, v53 row_ror:1 row_mask:0xf bank_mask:0xf
	v_mov_b32_dpp v0, v69 row_ror:15 row_mask:0xf bank_mask:0xf
	v_mov_b32_dpp v223, v50 row_ror:1 row_mask:0xf bank_mask:0xf
	v_mov_b32_dpp v222, v66 row_ror:15 row_mask:0xf bank_mask:0xf
	v_mov_b32_dpp v211, v54 row_ror:1 row_mask:0xf bank_mask:0xf
	v_mov_b32_dpp v210, v70 row_ror:15 row_mask:0xf bank_mask:0xf
	v_mov_b32_dpp v221, v51 row_ror:1 row_mask:0xf bank_mask:0xf
	v_mov_b32_dpp v216, v67 row_ror:15 row_mask:0xf bank_mask:0xf
	v_mov_b32_dpp v209, v55 row_ror:1 row_mask:0xf bank_mask:0xf
	v_mov_b32_dpp v208, v71 row_ror:15 row_mask:0xf bank_mask:0xf
	s_movk_i32 s12, 0xb00
	v_mov_b32_dpp v215, v56 row_shr:1 row_mask:0xf bank_mask:0xf
	v_mov_b32_dpp v214, v56 row_shl:1 row_mask:0xf bank_mask:0xf
	v_mov_b32_dpp v207, v60 row_shr:1 row_mask:0xf bank_mask:0xf
	v_mov_b32_dpp v206, v60 row_shl:1 row_mask:0xf bank_mask:0xf
	v_mov_b32_dpp v213, v57 row_shr:1 row_mask:0xf bank_mask:0xf
	v_mov_b32_dpp v212, v57 row_shl:1 row_mask:0xf bank_mask:0xf
	v_mov_b32_dpp v3, v61 row_shr:1 row_mask:0xf bank_mask:0xf
	v_mov_b32_dpp v0, v61 row_shl:1 row_mask:0xf bank_mask:0xf
	v_mov_b32_dpp v223, v58 row_shr:1 row_mask:0xf bank_mask:0xf
	v_mov_b32_dpp v222, v58 row_shl:1 row_mask:0xf bank_mask:0xf
	v_mov_b32_dpp v211, v62 row_shr:1 row_mask:0xf bank_mask:0xf
	v_mov_b32_dpp v210, v62 row_shl:1 row_mask:0xf bank_mask:0xf
	v_mov_b32_dpp v221, v59 row_shr:1 row_mask:0xf bank_mask:0xf
	v_mov_b32_dpp v216, v59 row_shl:1 row_mask:0xf bank_mask:0xf
	v_mov_b32_dpp v209, v63 row_shr:1 row_mask:0xf bank_mask:0xf
	v_mov_b32_dpp v208, v63 row_shl:1 row_mask:0xf bank_mask:0xf
	v_and_b32_e32 v218, s52, v217
	v_mul_lo_u32 v217, v217, s12
	s_and_saveexec_b64 s[14:15], s[16:17]
	s_cbranch_execz .LBB0_295
; __device__ __forceinline__ unsigned pack2(float lo, float hi) { return (unsigned)f2bf(lo) | ((unsigned)f2bf(hi) << 16); }
; __device__ __forceinline__ float sigmoidf_(float x) { return __builtin_amdgcn_rcpf(1.0f + __expf(-x)); }
;     __device__ __forceinline__ void operator()(const f32x4 (&acc)[2][2][4][2], const Unit& u, int wr, int wc, int fr, int fq) const {
;     ...
;                 for (int m = 0; m < 4; ++m) { const int r = 16 * m + fr, t = tb + r, pos = t & (L - 1);
;                     const bool hp = pos != 0, hn = pos != L - 1, valid = (r >= 1) & (r <= 62) & (t < TCH);
;                     float out[4];
; #pragma unroll
;                     for (int e = 0; e < 4; ++e) {
;                         const float xg = acc[ai][bj][m][0][e], xv = acc[ai][bj][m][1][e];
;                         float pg = dppf(m > 0 ? dppf(0.f, acc[ai][bj][m > 0 ? m - 1 : 0][0][e], 2) : 0.f, xg, 0);
;                         float ng = dppf(m < 3 ? dppf(0.f, acc[ai][bj][m < 3 ? m + 1 : 3][0][e], 3) : 0.f, xg, 1);
;                         float pv = dppf(m > 0 ? dppf(0.f, acc[ai][bj][m > 0 ? m - 1 : 0][1][e], 2) : 0.f, xv, 0);
;                         float nv = dppf(m < 3 ? dppf(0.f, acc[ai][bj][m < 3 ? m + 1 : 3][1][e], 3) : 0.f, xv, 1);
;                         if (!hp) { pg = 0.f; pv = 0.f; }
;                         if (!hn) { ng = 0.f; nv = 0.f; }
;                         const float hg = wg0[e] * pg + wg1[e] * xg + wg2[e] * ng + bgv[e], hv = wv0[e] * pv + wv1[e] * xv + wv2[e] * nv + bvv[e];
;                         out[e] = hg * sigmoidf_(1.5957691216f * (hg + 0.044715f * hg * hg * hg)) * hv; }
;                     if (valid) { uint2 o; o.x = pack2(out[0], out[1]); o.y = pack2(out[2], out[3]); *(uint2*)(ws + (unsigned)OFF_S + ((unsigned)t * (unsigned)DFF + (unsigned)J) * 2u) = o; }
	v_pk_mul_f32 v[224:225], v[58:59], v[162:163]
	v_pk_mul_f32 v[226:227], v[56:57], v[160:161]
	v_cmp_eq_u32_e32 vcc, 0, v218
	v_mov_b32_e32 v228, v226
	v_mov_b32_e32 v229, v224
	v_cndmask_b32_e64 v231, v223, 0, vcc
	v_mov_b32_e32 v224, v227
	v_cndmask_b32_e64 v230, v215, 0, vcc
	v_mov_b32_e32 v226, v152
	v_mov_b32_e32 v227, v154
	v_cmp_eq_u32_e64 s[12:13], s52, v218
	v_pk_fma_f32 v[226:227], v[226:227], v[230:231], v[228:229]
	v_mov_b32_e32 v223, v150
	v_cndmask_b32_e64 v215, v222, 0, s[12:13]
	v_cndmask_b32_e64 v214, v214, 0, s[12:13]
	v_mov_b32_e32 v222, v148
	v_pk_fma_f32 v[214:215], v[222:223], v[214:215], v[226:227]
	v_mov_b32_e32 v222, v144
	v_mov_b32_e32 v223, v146
	v_pk_add_f32 v[214:215], v[222:223], v[214:215]
	v_cndmask_b32_e64 v223, v221, 0, vcc
	v_mul_f32_e32 v222, 0x3d372713, v215
	v_mul_f32_e32 v222, v215, v222
	v_fma_f32 v222, v215, v222, v215
	v_mul_f32_e32 v222, 0x3fcc422a, v222
	v_mul_f32_e32 v222, 0xbfb8aa3b, v222
	v_exp_f32_e32 v226, v222
	v_cndmask_b32_e64 v222, v213, 0, vcc
	v_mov_b32_e32 v227, v155
	v_pk_mul_f32 v[232:233], v[62:63], v[158:159]
	v_add_f32_e32 v213, 1.0, v226
	v_mov_b32_e32 v226, v153
	v_pk_fma_f32 v[222:223], v[226:227], v[222:223], v[224:225]
	v_cndmask_b32_e64 v225, v216, 0, s[12:13]
	v_mul_f32_e32 v216, 0x3d372713, v214
	v_cndmask_b32_e64 v224, v212, 0, s[12:13]
	v_mov_b32_e32 v226, v149
	v_mov_b32_e32 v227, v151
	v_mul_f32_e32 v216, v214, v216
	v_pk_fma_f32 v[222:223], v[226:227], v[224:225], v[222:223]
	v_mov_b32_e32 v224, v145
	v_mov_b32_e32 v225, v147
	v_fma_f32 v216, v214, v216, v214
	v_pk_add_f32 v[222:223], v[224:225], v[222:223]
	v_mul_f32_e32 v216, 0x3fcc422a, v216
	v_mul_f32_e32 v212, 0x3d372713, v222
	v_mul_f32_e32 v216, 0xbfb8aa3b, v216
	v_mul_f32_e32 v212, v222, v212
	v_exp_f32_e32 v216, v216
	v_fma_f32 v212, v222, v212, v222
	v_mul_f32_e32 v212, 0x3fcc422a, v212
	v_mul_f32_e32 v212, 0xbfb8aa3b, v212
	v_exp_f32_e32 v221, v212
	v_add_f32_e32 v212, 1.0, v216
	v_rcp_f32_e32 v213, v213
	v_rcp_f32_e32 v212, v212
	v_add_f32_e32 v221, 1.0, v221
	v_rcp_f32_e32 v224, v221
	v_pk_mul_f32 v[234:235], v[60:61], v[156:157]
	v_pk_mul_f32 v[212:213], v[214:215], v[212:213]
	v_cndmask_b32_e64 v215, v211, 0, vcc
	v_mul_f32_e32 v211, 0x3d372713, v223
	v_mul_f32_e32 v211, v223, v211
	v_fma_f32 v211, v223, v211, v223
	v_mul_f32_e32 v211, 0x3fcc422a, v211
	v_mul_f32_e32 v211, 0xbfb8aa3b, v211
	v_exp_f32_e32 v221, v211
	v_mov_b32_e32 v236, v234
	v_mov_b32_e32 v237, v232
	v_cndmask_b32_e64 v214, v207, 0, vcc
	v_mov_b32_e32 v226, v140
	v_mov_b32_e32 v227, v142
	v_pk_fma_f32 v[214:215], v[226:227], v[214:215], v[236:237]
	v_cndmask_b32_e64 v207, v210, 0, s[12:13]
	v_cndmask_b32_e64 v206, v206, 0, s[12:13]
	v_mov_b32_e32 v210, v136
	v_mov_b32_e32 v211, v138
	v_pk_fma_f32 v[206:207], v[210:211], v[206:207], v[214:215]
	v_add_f32_e32 v211, 1.0, v221
	v_mov_b32_e32 v210, v132
	v_rcp_f32_e32 v225, v211
	v_mov_b32_e32 v211, v134
	v_pk_add_f32 v[206:207], v[210:211], v[206:207]
	v_mov_b32_e32 v232, v235
	v_pk_mul_f32 v[206:207], v[206:207], v[212:213]
	v_cndmask_b32_e64 v213, v209, 0, vcc
	v_cndmask_b32_e64 v212, v3, 0, vcc
	v_mov_b32_e32 v214, v141
	v_mov_b32_e32 v215, v143
	v_pk_fma_f32 v[212:213], v[214:215], v[212:213], v[232:233]
	v_cndmask_b32_e64 v209, v208, 0, s[12:13]
	v_cndmask_b32_e64 v208, v0, 0, s[12:13]
	v_mov_b32_e32 v214, v137
	v_mov_b32_e32 v215, v139
	v_pk_fma_f32 v[208:209], v[214:215], v[208:209], v[212:213]
	v_mov_b32_e32 v212, v133
	v_mov_b32_e32 v213, v135
	v_pk_mul_f32 v[210:211], v[222:223], v[224:225]
	v_pk_add_f32 v[208:209], v[212:213], v[208:209]
	v_and_b32_sdwa v0, v207, v185 dst_sel:DWORD dst_unused:UNUSED_PAD src0_sel:WORD_1 src1_sel:DWORD
	v_pk_mul_f32 v[208:209], v[208:209], v[210:211]
	v_and_b32_sdwa v3, v206, v185 dst_sel:DWORD dst_unused:UNUSED_PAD src0_sel:WORD_1 src1_sel:DWORD
	v_add3_u32 v3, v206, v3, s46
	v_add3_u32 v0, v207, v0, s46
	v_and_b32_sdwa v206, v209, v185 dst_sel:DWORD dst_unused:UNUSED_PAD src0_sel:WORD_1 src1_sel:DWORD
	v_and_b32_sdwa v207, v208, v185 dst_sel:DWORD dst_unused:UNUSED_PAD src0_sel:WORD_1 src1_sel:DWORD
	v_add3_u32 v206, v209, v206, s46
	v_add3_u32 v207, v208, v207, s46
	v_and_b32_e32 v206, 0xffff0000, v206
	v_and_b32_e32 v208, 0xffff0000, v207
	v_readlane_b32 s12, v249, 20
	v_add_lshl_u32 v216, v217, v2, 1
	v_or_b32_sdwa v207, v206, v0 dst_sel:DWORD dst_unused:UNUSED_PAD src0_sel:DWORD src1_sel:WORD_1
	v_or_b32_sdwa v206, v208, v3 dst_sel:DWORD dst_unused:UNUSED_PAD src0_sel:DWORD src1_sel:WORD_1
	v_readlane_b32 s13, v249, 21
	s_nop 4
	global_store_dwordx2 v216, v[206:207], s[12:13]
; __device__ __forceinline__ unsigned pack2(float lo, float hi) { return (unsigned)f2bf(lo) | ((unsigned)f2bf(hi) << 16); }
; __device__ __forceinline__ float sigmoidf_(float x) { return __builtin_amdgcn_rcpf(1.0f + __expf(-x)); }
;     __device__ __forceinline__ void operator()(const f32x4 (&acc)[2][2][4][2], const Unit& u, int wr, int wc, int fr, int fq) const {
;     ...
;                 for (int m = 0; m < 4; ++m) { const int r = 16 * m + fr, t = tb + r, pos = t & (L - 1);
;                     const bool hp = pos != 0, hn = pos != L - 1, valid = (r >= 1) & (r <= 62) & (t < TCH);
;                     float out[4];
; #pragma unroll
;                     for (int e = 0; e < 4; ++e) {
;                         const float xg = acc[ai][bj][m][0][e], xv = acc[ai][bj][m][1][e];
;                         float pg = dppf(m > 0 ? dppf(0.f, acc[ai][bj][m > 0 ? m - 1 : 0][0][e], 2) : 0.f, xg, 0);
;                         float ng = dppf(m < 3 ? dppf(0.f, acc[ai][bj][m < 3 ? m + 1 : 3][0][e], 3) : 0.f, xg, 1);
;                         float pv = dppf(m > 0 ? dppf(0.f, acc[ai][bj][m > 0 ? m - 1 : 0][1][e], 2) : 0.f, xv, 0);
;                         float nv = dppf(m < 3 ? dppf(0.f, acc[ai][bj][m < 3 ? m + 1 : 3][1][e], 3) : 0.f, xv, 1);
;                         if (!hp) { pg = 0.f; pv = 0.f; }
;                         if (!hn) { ng = 0.f; nv = 0.f; }
;                         const float hg = wg0[e] * pg + wg1[e] * xg + wg2[e] * ng + bgv[e], hv = wv0[e] * pv + wv1[e] * xv + wv2[e] * nv + bvv[e];
;                         out[e] = hg * sigmoidf_(1.5957691216f * (hg + 0.044715f * hg * hg * hg)) * hv; }
;                     if (valid) { uint2 o; o.x = pack2(out[0], out[1]); o.y = pack2(out[2], out[3]); *(uint2*)(ws + (unsigned)OFF_S + ((unsigned)t * (unsigned)DFF + (unsigned)J) * 2u) = o; }
.LBB0_295:
	s_or_b64 exec, exec, s[14:15]
	v_add_u32_e32 v215, s21, v201
	s_mov_b32 s12, 0x8000
	v_cmp_gt_i32_e64 s[14:15], s12, v215
	v_mov_b32_dpp v221, v56 row_ror:1 row_mask:0xf bank_mask:0xf
	v_mov_b32_dpp v214, v72 row_ror:15 row_mask:0xf bank_mask:0xf
	v_mov_b32_dpp v207, v60 row_ror:1 row_mask:0xf bank_mask:0xf
	v_mov_b32_dpp v206, v76 row_ror:15 row_mask:0xf bank_mask:0xf
	v_mov_b32_dpp v213, v57 row_ror:1 row_mask:0xf bank_mask:0xf
	v_mov_b32_dpp v212, v73 row_ror:15 row_mask:0xf bank_mask:0xf
	v_mov_b32_dpp v3, v61 row_ror:1 row_mask:0xf bank_mask:0xf
	v_mov_b32_dpp v0, v77 row_ror:15 row_mask:0xf bank_mask:0xf
	v_mov_b32_dpp v225, v58 row_ror:1 row_mask:0xf bank_mask:0xf
	v_mov_b32_dpp v224, v74 row_ror:15 row_mask:0xf bank_mask:0xf
	v_mov_b32_dpp v211, v62 row_ror:1 row_mask:0xf bank_mask:0xf
	v_mov_b32_dpp v210, v78 row_ror:15 row_mask:0xf bank_mask:0xf
	v_mov_b32_dpp v223, v59 row_ror:1 row_mask:0xf bank_mask:0xf
	v_mov_b32_dpp v222, v75 row_ror:15 row_mask:0xf bank_mask:0xf
	v_mov_b32_dpp v209, v63 row_ror:1 row_mask:0xf bank_mask:0xf
	v_mov_b32_dpp v208, v79 row_ror:15 row_mask:0xf bank_mask:0xf
	s_movk_i32 s12, 0xb00
	v_mov_b32_dpp v221, v64 row_shr:1 row_mask:0xf bank_mask:0xf
	v_mov_b32_dpp v214, v64 row_shl:1 row_mask:0xf bank_mask:0xf
	v_mov_b32_dpp v207, v68 row_shr:1 row_mask:0xf bank_mask:0xf
	v_mov_b32_dpp v206, v68 row_shl:1 row_mask:0xf bank_mask:0xf
	v_mov_b32_dpp v213, v65 row_shr:1 row_mask:0xf bank_mask:0xf
	v_mov_b32_dpp v212, v65 row_shl:1 row_mask:0xf bank_mask:0xf
	v_mov_b32_dpp v3, v69 row_shr:1 row_mask:0xf bank_mask:0xf
	v_mov_b32_dpp v0, v69 row_shl:1 row_mask:0xf bank_mask:0xf
	v_mov_b32_dpp v225, v66 row_shr:1 row_mask:0xf bank_mask:0xf
	v_mov_b32_dpp v224, v66 row_shl:1 row_mask:0xf bank_mask:0xf
	v_mov_b32_dpp v211, v70 row_shr:1 row_mask:0xf bank_mask:0xf
	v_mov_b32_dpp v210, v70 row_shl:1 row_mask:0xf bank_mask:0xf
	v_mov_b32_dpp v223, v67 row_shr:1 row_mask:0xf bank_mask:0xf
	v_mov_b32_dpp v222, v67 row_shl:1 row_mask:0xf bank_mask:0xf
	v_mov_b32_dpp v209, v71 row_shr:1 row_mask:0xf bank_mask:0xf
	v_mov_b32_dpp v208, v71 row_shl:1 row_mask:0xf bank_mask:0xf
	v_and_b32_e32 v216, s52, v215
	v_mul_lo_u32 v215, v215, s12
	s_and_saveexec_b64 s[18:19], s[14:15]
	s_cbranch_execz .LBB0_297
	v_pk_mul_f32 v[226:227], v[66:67], v[162:163]
	v_pk_mul_f32 v[228:229], v[64:65], v[160:161]
	v_cmp_eq_u32_e32 vcc, 0, v216
	v_mov_b32_e32 v230, v228
	v_mov_b32_e32 v231, v226
	v_cndmask_b32_e64 v233, v225, 0, vcc
	v_mov_b32_e32 v226, v229
	v_cndmask_b32_e64 v232, v221, 0, vcc
	v_mov_b32_e32 v228, v152
	v_mov_b32_e32 v229, v154
	v_cmp_eq_u32_e64 s[12:13], s52, v216
	v_pk_fma_f32 v[228:229], v[228:229], v[232:233], v[230:231]
	v_mov_b32_e32 v230, v148
	v_cndmask_b32_e64 v225, v224, 0, s[12:13]
	v_cndmask_b32_e64 v224, v214, 0, s[12:13]
	v_mov_b32_e32 v231, v150
	v_pk_fma_f32 v[224:225], v[230:231], v[224:225], v[228:229]
	v_mov_b32_e32 v228, v144
	v_mov_b32_e32 v229, v146
	v_pk_add_f32 v[224:225], v[228:229], v[224:225]
	v_cndmask_b32_e64 v228, v213, 0, vcc
	v_mul_f32_e32 v214, 0x3d372713, v225
	v_mul_f32_e32 v214, v225, v214
	v_fma_f32 v214, v225, v214, v225
	v_mul_f32_e32 v214, 0x3fcc422a, v214
	v_mul_f32_e32 v214, 0xbfb8aa3b, v214
	v_exp_f32_e32 v214, v214
	v_cndmask_b32_e64 v229, v223, 0, vcc
	v_mov_b32_e32 v230, v153
	v_mov_b32_e32 v231, v155
	v_add_f32_e32 v213, 1.0, v214
	v_mul_f32_e32 v214, 0x3d372713, v224
	v_pk_fma_f32 v[226:227], v[230:231], v[228:229], v[226:227]
	v_cndmask_b32_e64 v223, v222, 0, s[12:13]
	v_cndmask_b32_e64 v222, v212, 0, s[12:13]
	v_mov_b32_e32 v228, v149
	v_mov_b32_e32 v229, v151
	v_mul_f32_e32 v214, v224, v214
	v_pk_fma_f32 v[222:223], v[228:229], v[222:223], v[226:227]
	v_mov_b32_e32 v226, v145
	v_mov_b32_e32 v227, v147
	v_fma_f32 v214, v224, v214, v224
	v_pk_add_f32 v[222:223], v[226:227], v[222:223]
	v_mul_f32_e32 v214, 0x3fcc422a, v214
	v_mul_f32_e32 v212, 0x3d372713, v222
	v_mul_f32_e32 v214, 0xbfb8aa3b, v214
	v_mul_f32_e32 v212, v222, v212
	v_exp_f32_e32 v214, v214
	v_fma_f32 v212, v222, v212, v222
	v_mul_f32_e32 v212, 0x3fcc422a, v212
	v_mul_f32_e32 v212, 0xbfb8aa3b, v212
	v_exp_f32_e32 v221, v212
	v_add_f32_e32 v212, 1.0, v214
	v_rcp_f32_e32 v213, v213
	v_rcp_f32_e32 v212, v212
	v_add_f32_e32 v221, 1.0, v221
	v_rcp_f32_e32 v226, v221
	v_pk_mul_f32 v[234:235], v[70:71], v[158:159]
	v_pk_mul_f32 v[212:213], v[224:225], v[212:213]
	v_cndmask_b32_e64 v225, v211, 0, vcc
	v_mul_f32_e32 v211, 0x3d372713, v223
	v_mul_f32_e32 v211, v223, v211
	v_fma_f32 v211, v223, v211, v223
	v_mul_f32_e32 v211, 0x3fcc422a, v211
	v_mul_f32_e32 v211, 0xbfb8aa3b, v211
	v_exp_f32_e32 v221, v211
	v_pk_mul_f32 v[236:237], v[68:69], v[156:157]
	v_mov_b32_e32 v239, v234
	v_mov_b32_e32 v238, v236
	v_cndmask_b32_e64 v224, v207, 0, vcc
	v_mov_b32_e32 v228, v140
	v_mov_b32_e32 v229, v142
	v_pk_fma_f32 v[224:225], v[228:229], v[224:225], v[238:239]
	v_cndmask_b32_e64 v207, v210, 0, s[12:13]
	v_cndmask_b32_e64 v206, v206, 0, s[12:13]
	v_mov_b32_e32 v210, v136
	v_mov_b32_e32 v211, v138
	v_pk_fma_f32 v[206:207], v[210:211], v[206:207], v[224:225]
	v_add_f32_e32 v211, 1.0, v221
	v_rcp_f32_e32 v227, v211
	v_mov_b32_e32 v210, v132
	v_mov_b32_e32 v211, v134
	v_pk_add_f32 v[206:207], v[210:211], v[206:207]
	v_mov_b32_e32 v234, v237
	v_pk_mul_f32 v[206:207], v[206:207], v[212:213]
	v_pk_mul_f32 v[210:211], v[222:223], v[226:227]
	v_cndmask_b32_e64 v213, v209, 0, vcc
	v_cndmask_b32_e64 v212, v3, 0, vcc
	v_mov_b32_e32 v222, v141
	v_mov_b32_e32 v223, v143
	v_pk_fma_f32 v[212:213], v[222:223], v[212:213], v[234:235]
	v_cndmask_b32_e64 v209, v208, 0, s[12:13]
	v_cndmask_b32_e64 v208, v0, 0, s[12:13]
	v_mov_b32_e32 v222, v137
	v_mov_b32_e32 v223, v139
	v_pk_fma_f32 v[208:209], v[222:223], v[208:209], v[212:213]
	v_mov_b32_e32 v212, v133
	v_mov_b32_e32 v213, v135
	v_pk_add_f32 v[208:209], v[212:213], v[208:209]
	v_and_b32_sdwa v0, v207, v185 dst_sel:DWORD dst_unused:UNUSED_PAD src0_sel:WORD_1 src1_sel:DWORD
	v_pk_mul_f32 v[208:209], v[208:209], v[210:211]
	v_and_b32_sdwa v3, v206, v185 dst_sel:DWORD dst_unused:UNUSED_PAD src0_sel:WORD_1 src1_sel:DWORD
	v_add3_u32 v3, v206, v3, s46
	v_add3_u32 v0, v207, v0, s46
	v_and_b32_sdwa v206, v209, v185 dst_sel:DWORD dst_unused:UNUSED_PAD src0_sel:WORD_1 src1_sel:DWORD
	v_and_b32_sdwa v207, v208, v185 dst_sel:DWORD dst_unused:UNUSED_PAD src0_sel:WORD_1 src1_sel:DWORD
	v_add3_u32 v206, v209, v206, s46
	v_add3_u32 v207, v208, v207, s46
	v_and_b32_e32 v206, 0xffff0000, v206
	v_and_b32_e32 v208, 0xffff0000, v207
	v_readlane_b32 s12, v249, 20
	v_add_lshl_u32 v214, v215, v2, 1
	v_or_b32_sdwa v207, v206, v0 dst_sel:DWORD dst_unused:UNUSED_PAD src0_sel:DWORD src1_sel:WORD_1
	v_or_b32_sdwa v206, v208, v3 dst_sel:DWORD dst_unused:UNUSED_PAD src0_sel:DWORD src1_sel:WORD_1
	v_readlane_b32 s13, v249, 21
	s_nop 4
	global_store_dwordx2 v214, v[206:207], s[12:13]
; __device__ __forceinline__ unsigned pack2(float lo, float hi) { return (unsigned)f2bf(lo) | ((unsigned)f2bf(hi) << 16); }
; __device__ __forceinline__ float sigmoidf_(float x) { return __builtin_amdgcn_rcpf(1.0f + __expf(-x)); }
;     __device__ __forceinline__ void operator()(const f32x4 (&acc)[2][2][4][2], const Unit& u, int wr, int wc, int fr, int fq) const {
;     ...
;                 for (int m = 0; m < 4; ++m) { const int r = 16 * m + fr, t = tb + r, pos = t & (L - 1);
;                     const bool hp = pos != 0, hn = pos != L - 1, valid = (r >= 1) & (r <= 62) & (t < TCH);
;                     float out[4];
; #pragma unroll
;                     for (int e = 0; e < 4; ++e) {
;                         const float xg = acc[ai][bj][m][0][e], xv = acc[ai][bj][m][1][e];
;                         float pg = dppf(m > 0 ? dppf(0.f, acc[ai][bj][m > 0 ? m - 1 : 0][0][e], 2) : 0.f, xg, 0);
;                         float ng = dppf(m < 3 ? dppf(0.f, acc[ai][bj][m < 3 ? m + 1 : 3][0][e], 3) : 0.f, xg, 1);
;                         float pv = dppf(m > 0 ? dppf(0.f, acc[ai][bj][m > 0 ? m - 1 : 0][1][e], 2) : 0.f, xv, 0);
;                         float nv = dppf(m < 3 ? dppf(0.f, acc[ai][bj][m < 3 ? m + 1 : 3][1][e], 3) : 0.f, xv, 1);
;                         if (!hp) { pg = 0.f; pv = 0.f; }
;                         if (!hn) { ng = 0.f; nv = 0.f; }
;                         const float hg = wg0[e] * pg + wg1[e] * xg + wg2[e] * ng + bgv[e], hv = wv0[e] * pv + wv1[e] * xv + wv2[e] * nv + bvv[e];
;                         out[e] = hg * sigmoidf_(1.5957691216f * (hg + 0.044715f * hg * hg * hg)) * hv; }
;                     if (valid) { uint2 o; o.x = pack2(out[0], out[1]); o.y = pack2(out[2], out[3]); *(uint2*)(ws + (unsigned)OFF_S + ((unsigned)t * (unsigned)DFF + (unsigned)J) * 2u) = o; }
.LBB0_297:
	s_or_b64 exec, exec, s[18:19]
	v_add_u32_e32 v213, s21, v202
	s_mov_b32 s12, 0x8000
	v_cmp_gt_i32_e32 vcc, s12, v213
	v_readlane_b32 s12, v249, 63
	v_readlane_b32 s13, v248, 0
	v_mov_b32_dpp v223, v64 row_ror:1 row_mask:0xf bank_mask:0xf
	v_mov_b32_e32 v222, 0
	v_mov_b32_dpp v209, v68 row_ror:1 row_mask:0xf bank_mask:0xf
	v_mov_b32_e32 v207, 0
	v_mov_b32_dpp v221, v65 row_ror:1 row_mask:0xf bank_mask:0xf
	v_mov_b32_e32 v212, 0
	v_mov_b32_dpp v3, v69 row_ror:1 row_mask:0xf bank_mask:0xf
	v_mov_b32_e32 v0, 0
	v_mov_b32_dpp v227, v66 row_ror:1 row_mask:0xf bank_mask:0xf
	v_mov_b32_e32 v226, 0
	v_mov_b32_dpp v211, v70 row_ror:1 row_mask:0xf bank_mask:0xf
	v_mov_b32_e32 v210, 0
	v_mov_b32_dpp v225, v67 row_ror:1 row_mask:0xf bank_mask:0xf
	v_mov_b32_e32 v224, 0
	v_mov_b32_dpp v208, v71 row_ror:1 row_mask:0xf bank_mask:0xf
	v_mov_b32_e32 v206, 0
	s_and_b64 s[68:69], s[12:13], vcc
	s_movk_i32 s12, 0xb00
	v_mov_b32_dpp v223, v72 row_shr:1 row_mask:0xf bank_mask:0xf
	v_mov_b32_dpp v222, v72 row_shl:1 row_mask:0xf bank_mask:0xf
	v_mov_b32_dpp v209, v76 row_shr:1 row_mask:0xf bank_mask:0xf
	v_mov_b32_dpp v207, v76 row_shl:1 row_mask:0xf bank_mask:0xf
	v_mov_b32_dpp v221, v73 row_shr:1 row_mask:0xf bank_mask:0xf
	v_mov_b32_dpp v212, v73 row_shl:1 row_mask:0xf bank_mask:0xf
	v_mov_b32_dpp v3, v77 row_shr:1 row_mask:0xf bank_mask:0xf
	v_mov_b32_dpp v0, v77 row_shl:1 row_mask:0xf bank_mask:0xf
	v_mov_b32_dpp v227, v74 row_shr:1 row_mask:0xf bank_mask:0xf
	v_mov_b32_dpp v226, v74 row_shl:1 row_mask:0xf bank_mask:0xf
	v_mov_b32_dpp v211, v78 row_shr:1 row_mask:0xf bank_mask:0xf
	v_mov_b32_dpp v210, v78 row_shl:1 row_mask:0xf bank_mask:0xf
	v_mov_b32_dpp v225, v75 row_shr:1 row_mask:0xf bank_mask:0xf
	v_mov_b32_dpp v224, v75 row_shl:1 row_mask:0xf bank_mask:0xf
	v_mov_b32_dpp v208, v79 row_shr:1 row_mask:0xf bank_mask:0xf
	v_mov_b32_dpp v206, v79 row_shl:1 row_mask:0xf bank_mask:0xf
	v_and_b32_e32 v214, s52, v213
	v_mul_lo_u32 v213, v213, s12
	s_and_saveexec_b64 s[18:19], s[68:69]
	s_cbranch_execz .LBB0_299
	v_pk_mul_f32 v[228:229], v[74:75], v[162:163]
	v_pk_mul_f32 v[230:231], v[72:73], v[160:161]
	v_cmp_eq_u32_e32 vcc, 0, v214
	v_mov_b32_e32 v232, v230
	v_mov_b32_e32 v233, v228
	v_cndmask_b32_e64 v235, v227, 0, vcc
	v_mov_b32_e32 v228, v231
	v_cndmask_b32_e64 v234, v223, 0, vcc
	v_mov_b32_e32 v230, v152
	v_mov_b32_e32 v231, v154
	v_cmp_eq_u32_e64 s[12:13], s52, v214
	v_pk_fma_f32 v[230:231], v[230:231], v[234:235], v[232:233]
	v_mov_b32_e32 v227, v150
	v_cndmask_b32_e64 v223, v226, 0, s[12:13]
	v_cndmask_b32_e64 v222, v222, 0, s[12:13]
	v_mov_b32_e32 v226, v148
	v_pk_fma_f32 v[222:223], v[226:227], v[222:223], v[230:231]
	v_mov_b32_e32 v226, v144
	v_mov_b32_e32 v227, v146
	v_pk_add_f32 v[222:223], v[226:227], v[222:223]
	v_cndmask_b32_e64 v227, v225, 0, vcc
	v_mul_f32_e32 v226, 0x3d372713, v223
	v_mul_f32_e32 v226, v223, v226
	v_fma_f32 v226, v223, v226, v223
	v_mul_f32_e32 v226, 0x3fcc422a, v226
	v_mul_f32_e32 v226, 0xbfb8aa3b, v226
	v_exp_f32_e32 v230, v226
	v_cndmask_b32_e64 v226, v221, 0, vcc
	v_mov_b32_e32 v231, v155
	v_pk_mul_f32 v[236:237], v[78:79], v[158:159]
	v_add_f32_e32 v221, 1.0, v230
	v_rcp_f32_e32 v225, v221
	v_mul_f32_e32 v221, 0x3d372713, v222
	v_mul_f32_e32 v221, v222, v221
	v_fma_f32 v221, v222, v221, v222
	v_mul_f32_e32 v221, 0x3fcc422a, v221
	v_mul_f32_e32 v221, 0xbfb8aa3b, v221
	v_exp_f32_e32 v221, v221
	v_mov_b32_e32 v230, v153
	v_pk_fma_f32 v[226:227], v[230:231], v[226:227], v[228:229]
	v_cndmask_b32_e64 v229, v224, 0, s[12:13]
	v_add_f32_e32 v221, 1.0, v221
	v_rcp_f32_e32 v224, v221
	v_cndmask_b32_e64 v228, v212, 0, s[12:13]
	v_mov_b32_e32 v230, v149
	v_mov_b32_e32 v231, v151
	v_pk_fma_f32 v[226:227], v[230:231], v[228:229], v[226:227]
	v_mov_b32_e32 v228, v145
	v_mov_b32_e32 v229, v147
	v_pk_add_f32 v[226:227], v[228:229], v[226:227]
	v_pk_mul_f32 v[222:223], v[222:223], v[224:225]
	v_mul_f32_e32 v212, 0x3d372713, v226
	v_cndmask_b32_e64 v225, v211, 0, vcc
	v_cndmask_b32_e64 v211, v210, 0, s[12:13]
	v_cndmask_b32_e64 v210, v207, 0, s[12:13]
	v_mul_f32_e32 v207, 0x3d372713, v227
	v_mul_f32_e32 v212, v226, v212
	v_mul_f32_e32 v207, v227, v207
	v_fma_f32 v212, v226, v212, v226
	v_fma_f32 v207, v227, v207, v227
	v_mul_f32_e32 v212, 0x3fcc422a, v212
	v_mul_f32_e32 v207, 0x3fcc422a, v207
	v_mul_f32_e32 v212, 0xbfb8aa3b, v212
	v_mul_f32_e32 v207, 0xbfb8aa3b, v207
	v_exp_f32_e32 v212, v212
	v_exp_f32_e32 v207, v207
	v_pk_mul_f32 v[238:239], v[76:77], v[156:157]
	v_mov_b32_e32 v241, v236
	v_mov_b32_e32 v240, v238
	v_cndmask_b32_e64 v224, v209, 0, vcc
	v_mov_b32_e32 v230, v140
	v_mov_b32_e32 v231, v142
	v_add_f32_e32 v212, 1.0, v212
	v_pk_fma_f32 v[224:225], v[230:231], v[224:225], v[240:241]
	v_mov_b32_e32 v230, v136
	v_mov_b32_e32 v231, v138
	v_add_f32_e32 v207, 1.0, v207
	v_rcp_f32_e32 v228, v212
	v_pk_fma_f32 v[210:211], v[230:231], v[210:211], v[224:225]
	v_mov_b32_e32 v224, v132
	v_rcp_f32_e32 v229, v207
	v_mov_b32_e32 v225, v134
	v_mov_b32_e32 v236, v239
	v_pk_add_f32 v[210:211], v[224:225], v[210:211]
	v_cndmask_b32_e64 v209, v208, 0, vcc
	v_cndmask_b32_e64 v208, v3, 0, vcc
	v_mov_b32_e32 v224, v141
	v_mov_b32_e32 v225, v143
	v_pk_fma_f32 v[208:209], v[224:225], v[208:209], v[236:237]
	v_cndmask_b32_e64 v207, v206, 0, s[12:13]
	v_cndmask_b32_e64 v206, v0, 0, s[12:13]
	v_mov_b32_e32 v224, v137
	v_mov_b32_e32 v225, v139
	v_pk_fma_f32 v[206:207], v[224:225], v[206:207], v[208:209]
	v_mov_b32_e32 v208, v133
	v_mov_b32_e32 v209, v135
	v_pk_mul_f32 v[210:211], v[210:211], v[222:223]
	v_pk_mul_f32 v[222:223], v[226:227], v[228:229]
	v_pk_add_f32 v[206:207], v[208:209], v[206:207]
	v_and_b32_sdwa v0, v211, v185 dst_sel:DWORD dst_unused:UNUSED_PAD src0_sel:WORD_1 src1_sel:DWORD
	v_pk_mul_f32 v[206:207], v[206:207], v[222:223]
	v_and_b32_sdwa v3, v210, v185 dst_sel:DWORD dst_unused:UNUSED_PAD src0_sel:WORD_1 src1_sel:DWORD
	v_and_b32_sdwa v208, v207, v185 dst_sel:DWORD dst_unused:UNUSED_PAD src0_sel:WORD_1 src1_sel:DWORD
	v_and_b32_sdwa v209, v206, v185 dst_sel:DWORD dst_unused:UNUSED_PAD src0_sel:WORD_1 src1_sel:DWORD
	v_add3_u32 v207, v207, v208, s46
	v_add3_u32 v206, v206, v209, s46
	v_add3_u32 v3, v210, v3, s46
	v_add3_u32 v0, v211, v0, s46
	v_and_b32_e32 v207, 0xffff0000, v207
	v_and_b32_e32 v206, 0xffff0000, v206
	v_readlane_b32 s12, v249, 20
	v_add_lshl_u32 v221, v213, v2, 1
	v_or_b32_sdwa v207, v207, v0 dst_sel:DWORD dst_unused:UNUSED_PAD src0_sel:DWORD src1_sel:WORD_1
	v_or_b32_sdwa v206, v206, v3 dst_sel:DWORD dst_unused:UNUSED_PAD src0_sel:DWORD src1_sel:WORD_1
	v_readlane_b32 s13, v249, 21
	s_nop 4
	global_store_dwordx2 v221, v[206:207], s[12:13]
; __device__ __forceinline__ unsigned pack2(float lo, float hi) { return (unsigned)f2bf(lo) | ((unsigned)f2bf(hi) << 16); }
; __device__ __forceinline__ float sigmoidf_(float x) { return __builtin_amdgcn_rcpf(1.0f + __expf(-x)); }
;     __device__ __forceinline__ void operator()(const f32x4 (&acc)[2][2][4][2], const Unit& u, int wr, int wc, int fr, int fq) const {
;     ...
;             for (int ai = 0; ai < 2; ++ai) { const int tb = u.pm * 248 + 62 * (ai * 2 + wr) - 1;
; #pragma unroll
;                 for (int m = 0; m < 4; ++m) { const int r = 16 * m + fr, t = tb + r, pos = t & (L - 1);
;                     const bool hp = pos != 0, hn = pos != L - 1, valid = (r >= 1) & (r <= 62) & (t < TCH);
;                     float out[4];
; #pragma unroll
;                     for (int e = 0; e < 4; ++e) {
;                         const float xg = acc[ai][bj][m][0][e], xv = acc[ai][bj][m][1][e];
;                         float pg = dppf(m > 0 ? dppf(0.f, acc[ai][bj][m > 0 ? m - 1 : 0][0][e], 2) : 0.f, xg, 0);
;                         float ng = dppf(m < 3 ? dppf(0.f, acc[ai][bj][m < 3 ? m + 1 : 3][0][e], 3) : 0.f, xg, 1);
;                         float pv = dppf(m > 0 ? dppf(0.f, acc[ai][bj][m > 0 ? m - 1 : 0][1][e], 2) : 0.f, xv, 0);
;                         float nv = dppf(m < 3 ? dppf(0.f, acc[ai][bj][m < 3 ? m + 1 : 3][1][e], 3) : 0.f, xv, 1);
;                         if (!hp) { pg = 0.f; pv = 0.f; }
;                         if (!hn) { ng = 0.f; nv = 0.f; }
;                         const float hg = wg0[e] * pg + wg1[e] * xg + wg2[e] * ng + bgv[e], hv = wv0[e] * pv + wv1[e] * xv + wv2[e] * nv + bvv[e];
;                         out[e] = hg * sigmoidf_(1.5957691216f * (hg + 0.044715f * hg * hg * hg)) * hv; }
;                     if (valid) { uint2 o; o.x = pack2(out[0], out[1]); o.y = pack2(out[2], out[3]); *(uint2*)(ws + (unsigned)OFF_S + ((unsigned)t * (unsigned)DFF + (unsigned)J) * 2u) = o; }
.LBB0_299:
	s_or_b64 exec, exec, s[18:19]
	s_add_i32 s80, s20, 0x7b
	v_add_u32_e32 v211, s80, v195
	s_mov_b32 s12, 0x8000
	v_cmp_gt_i32_e32 vcc, s12, v211
	v_readlane_b32 s12, v249, 61
	v_readlane_b32 s13, v249, 62
	v_mov_b32_e32 v226, 0
	v_mov_b32_dpp v224, v120 row_ror:15 row_mask:0xf bank_mask:0xf
	v_mov_b32_e32 v209, 0
	v_mov_b32_dpp v207, v124 row_ror:15 row_mask:0xf bank_mask:0xf
	v_mov_b32_e32 v223, 0
	v_mov_b32_dpp v222, v121 row_ror:15 row_mask:0xf bank_mask:0xf
	v_mov_b32_e32 v3, 0
	v_mov_b32_dpp v0, v125 row_ror:15 row_mask:0xf bank_mask:0xf
	v_mov_b32_e32 v229, 0
	v_mov_b32_dpp v228, v122 row_ror:15 row_mask:0xf bank_mask:0xf
	v_mov_b32_e32 v221, 0
	v_mov_b32_dpp v210, v126 row_ror:15 row_mask:0xf bank_mask:0xf
	v_mov_b32_e32 v227, 0
	v_mov_b32_dpp v225, v123 row_ror:15 row_mask:0xf bank_mask:0xf
	v_mov_b32_e32 v208, 0
	v_mov_b32_dpp v206, v127 row_ror:15 row_mask:0xf bank_mask:0xf
	s_and_b64 s[66:67], s[12:13], vcc
	s_movk_i32 s12, 0xb00
	v_mov_b32_dpp v226, v112 row_shr:1 row_mask:0xf bank_mask:0xf
	v_mov_b32_dpp v224, v112 row_shl:1 row_mask:0xf bank_mask:0xf
	v_mov_b32_dpp v209, v116 row_shr:1 row_mask:0xf bank_mask:0xf
	v_mov_b32_dpp v207, v116 row_shl:1 row_mask:0xf bank_mask:0xf
	v_mov_b32_dpp v223, v113 row_shr:1 row_mask:0xf bank_mask:0xf
	v_mov_b32_dpp v222, v113 row_shl:1 row_mask:0xf bank_mask:0xf
	v_mov_b32_dpp v3, v117 row_shr:1 row_mask:0xf bank_mask:0xf
	v_mov_b32_dpp v0, v117 row_shl:1 row_mask:0xf bank_mask:0xf
	v_mov_b32_dpp v229, v114 row_shr:1 row_mask:0xf bank_mask:0xf
	v_mov_b32_dpp v228, v114 row_shl:1 row_mask:0xf bank_mask:0xf
	v_mov_b32_dpp v221, v118 row_shr:1 row_mask:0xf bank_mask:0xf
	v_mov_b32_dpp v210, v118 row_shl:1 row_mask:0xf bank_mask:0xf
	v_mov_b32_dpp v227, v115 row_shr:1 row_mask:0xf bank_mask:0xf
	v_mov_b32_dpp v225, v115 row_shl:1 row_mask:0xf bank_mask:0xf
	v_mov_b32_dpp v208, v119 row_shr:1 row_mask:0xf bank_mask:0xf
	v_mov_b32_dpp v206, v119 row_shl:1 row_mask:0xf bank_mask:0xf
	v_and_b32_e32 v212, s52, v211
	v_mul_lo_u32 v211, v211, s12
	s_and_saveexec_b64 s[18:19], s[66:67]
	s_cbranch_execz .LBB0_301
	v_pk_mul_f32 v[230:231], v[114:115], v[162:163]
	v_pk_mul_f32 v[232:233], v[112:113], v[160:161]
	v_cmp_eq_u32_e32 vcc, 0, v212
	v_mov_b32_e32 v234, v232
	v_mov_b32_e32 v235, v230
	v_cndmask_b32_e64 v237, v229, 0, vcc
	v_mov_b32_e32 v230, v233
	v_cndmask_b32_e64 v236, v226, 0, vcc
	v_mov_b32_e32 v232, v152
	v_mov_b32_e32 v233, v154
	v_cmp_eq_u32_e64 s[12:13], s52, v212
	v_pk_fma_f32 v[232:233], v[232:233], v[236:237], v[234:235]
	v_mov_b32_e32 v234, v148
	v_cndmask_b32_e64 v229, v228, 0, s[12:13]
	v_cndmask_b32_e64 v228, v224, 0, s[12:13]
	v_mov_b32_e32 v235, v150
	v_pk_fma_f32 v[228:229], v[234:235], v[228:229], v[232:233]
	v_mov_b32_e32 v232, v144
	v_mov_b32_e32 v233, v146
	v_pk_add_f32 v[228:229], v[232:233], v[228:229]
	v_cndmask_b32_e64 v226, v223, 0, vcc
	v_mul_f32_e32 v224, 0x3d372713, v229
	v_mul_f32_e32 v224, v229, v224
	v_fma_f32 v224, v229, v224, v229
	v_mul_f32_e32 v224, 0x3fcc422a, v224
	v_mul_f32_e32 v224, 0xbfb8aa3b, v224
	v_exp_f32_e32 v224, v224
	v_cndmask_b32_e64 v227, v227, 0, vcc
	v_mov_b32_e32 v232, v153
	v_mov_b32_e32 v233, v155
	v_add_f32_e32 v223, 1.0, v224
	v_pk_fma_f32 v[226:227], v[232:233], v[226:227], v[230:231]
	v_cndmask_b32_e64 v225, v225, 0, s[12:13]
	v_cndmask_b32_e64 v224, v222, 0, s[12:13]
	v_mov_b32_e32 v230, v149
	v_mov_b32_e32 v231, v151
	v_pk_fma_f32 v[224:225], v[230:231], v[224:225], v[226:227]
	v_mov_b32_e32 v226, v145
	v_mov_b32_e32 v227, v147
	v_pk_add_f32 v[224:225], v[226:227], v[224:225]
	v_mul_f32_e32 v226, 0x3d372713, v228
	v_mul_f32_e32 v226, v228, v226
	v_fma_f32 v226, v228, v226, v228
	v_mul_f32_e32 v226, 0x3fcc422a, v226
	v_mul_f32_e32 v222, 0x3d372713, v224
	v_mul_f32_e32 v226, 0xbfb8aa3b, v226
	v_mul_f32_e32 v222, v224, v222
	v_exp_f32_e32 v226, v226
	v_fma_f32 v222, v224, v222, v224
	v_mul_f32_e32 v222, 0x3fcc422a, v222
	v_mul_f32_e32 v222, 0xbfb8aa3b, v222
	v_exp_f32_e32 v227, v222
	v_add_f32_e32 v222, 1.0, v226
	v_rcp_f32_e32 v223, v223
	v_rcp_f32_e32 v222, v222
	v_pk_mul_f32 v[238:239], v[118:119], v[158:159]
	v_pk_mul_f32 v[240:241], v[116:117], v[156:157]
	v_mov_b32_e32 v243, v238
	v_mov_b32_e32 v242, v240
	v_pk_mul_f32 v[222:223], v[228:229], v[222:223]
	v_cndmask_b32_e64 v229, v221, 0, vcc
	v_cndmask_b32_e64 v228, v209, 0, vcc
	v_mov_b32_e32 v230, v140
	v_mov_b32_e32 v231, v142
	v_pk_fma_f32 v[228:229], v[230:231], v[228:229], v[242:243]
	v_cndmask_b32_e64 v230, v207, 0, s[12:13]
	v_mul_f32_e32 v207, 0x3d372713, v225
	v_mul_f32_e32 v207, v225, v207
	v_fma_f32 v207, v225, v207, v225
	v_mul_f32_e32 v207, 0x3fcc422a, v207
	v_mul_f32_e32 v207, 0xbfb8aa3b, v207
	v_exp_f32_e32 v207, v207
	v_add_f32_e32 v226, 1.0, v227
	v_rcp_f32_e32 v226, v226
	v_mov_b32_e32 v238, v241
	v_add_f32_e32 v207, 1.0, v207
	v_rcp_f32_e32 v227, v207
	v_cndmask_b32_e64 v209, v208, 0, vcc
	v_cndmask_b32_e64 v208, v3, 0, vcc
	v_cndmask_b32_e64 v207, v206, 0, s[12:13]
	v_pk_mul_f32 v[224:225], v[224:225], v[226:227]
	v_mov_b32_e32 v226, v141
	v_mov_b32_e32 v227, v143
	v_pk_fma_f32 v[208:209], v[226:227], v[208:209], v[238:239]
	v_cndmask_b32_e64 v206, v0, 0, s[12:13]
	v_mov_b32_e32 v226, v137
	v_mov_b32_e32 v227, v139
	v_cndmask_b32_e64 v231, v210, 0, s[12:13]
	v_mov_b32_e32 v232, v136
	v_mov_b32_e32 v233, v138
	v_pk_fma_f32 v[206:207], v[226:227], v[206:207], v[208:209]
	v_mov_b32_e32 v208, v133
	v_mov_b32_e32 v209, v135
	v_pk_fma_f32 v[228:229], v[232:233], v[230:231], v[228:229]
	v_mov_b32_e32 v230, v132
	v_mov_b32_e32 v231, v134
	v_pk_add_f32 v[206:207], v[208:209], v[206:207]
	v_pk_add_f32 v[228:229], v[230:231], v[228:229]
	v_pk_mul_f32 v[206:207], v[206:207], v[224:225]
	v_pk_mul_f32 v[222:223], v[228:229], v[222:223]
	v_and_b32_sdwa v208, v207, v185 dst_sel:DWORD dst_unused:UNUSED_PAD src0_sel:WORD_1 src1_sel:DWORD
	v_and_b32_sdwa v209, v206, v185 dst_sel:DWORD dst_unused:UNUSED_PAD src0_sel:WORD_1 src1_sel:DWORD
	v_and_b32_sdwa v0, v223, v185 dst_sel:DWORD dst_unused:UNUSED_PAD src0_sel:WORD_1 src1_sel:DWORD
	v_and_b32_sdwa v3, v222, v185 dst_sel:DWORD dst_unused:UNUSED_PAD src0_sel:WORD_1 src1_sel:DWORD
	v_add3_u32 v207, v207, v208, s46
	v_add3_u32 v206, v206, v209, s46
	v_add3_u32 v3, v222, v3, s46
	v_add3_u32 v0, v223, v0, s46
	v_and_b32_e32 v207, 0xffff0000, v207
	v_and_b32_e32 v206, 0xffff0000, v206
	v_readlane_b32 s12, v249, 20
	v_add_lshl_u32 v234, v211, v2, 1
	v_or_b32_sdwa v207, v207, v0 dst_sel:DWORD dst_unused:UNUSED_PAD src0_sel:DWORD src1_sel:WORD_1
	v_or_b32_sdwa v206, v206, v3 dst_sel:DWORD dst_unused:UNUSED_PAD src0_sel:DWORD src1_sel:WORD_1
	v_readlane_b32 s13, v249, 21
	s_nop 4
	global_store_dwordx2 v234, v[206:207], s[12:13]
; __device__ __forceinline__ unsigned pack2(float lo, float hi) { return (unsigned)f2bf(lo) | ((unsigned)f2bf(hi) << 16); }
; __device__ __forceinline__ float sigmoidf_(float x) { return __builtin_amdgcn_rcpf(1.0f + __expf(-x)); }
;     __device__ __forceinline__ void operator()(const f32x4 (&acc)[2][2][4][2], const Unit& u, int wr, int wc, int fr, int fq) const {
;     ...
;                 for (int m = 0; m < 4; ++m) { const int r = 16 * m + fr, t = tb + r, pos = t & (L - 1);
;                     const bool hp = pos != 0, hn = pos != L - 1, valid = (r >= 1) & (r <= 62) & (t < TCH);
;                     float out[4];
; #pragma unroll
;                     for (int e = 0; e < 4; ++e) {
;                         const float xg = acc[ai][bj][m][0][e], xv = acc[ai][bj][m][1][e];
;                         float pg = dppf(m > 0 ? dppf(0.f, acc[ai][bj][m > 0 ? m - 1 : 0][0][e], 2) : 0.f, xg, 0);
;                         float ng = dppf(m < 3 ? dppf(0.f, acc[ai][bj][m < 3 ? m + 1 : 3][0][e], 3) : 0.f, xg, 1);
;                         float pv = dppf(m > 0 ? dppf(0.f, acc[ai][bj][m > 0 ? m - 1 : 0][1][e], 2) : 0.f, xv, 0);
;                         float nv = dppf(m < 3 ? dppf(0.f, acc[ai][bj][m < 3 ? m + 1 : 3][1][e], 3) : 0.f, xv, 1);
;                         if (!hp) { pg = 0.f; pv = 0.f; }
;                         if (!hn) { ng = 0.f; nv = 0.f; }
;                         const float hg = wg0[e] * pg + wg1[e] * xg + wg2[e] * ng + bgv[e], hv = wv0[e] * pv + wv1[e] * xv + wv2[e] * nv + bvv[e];
;                         out[e] = hg * sigmoidf_(1.5957691216f * (hg + 0.044715f * hg * hg * hg)) * hv; }
;                     if (valid) { uint2 o; o.x = pack2(out[0], out[1]); o.y = pack2(out[2], out[3]); *(uint2*)(ws + (unsigned)OFF_S + ((unsigned)t * (unsigned)DFF + (unsigned)J) * 2u) = o; }
.LBB0_301:
	s_or_b64 exec, exec, s[18:19]
	v_add_u32_e32 v209, s80, v200
	s_mov_b32 s12, 0x8000
	v_mov_b32_dpp v227, v112 row_ror:1 row_mask:0xf bank_mask:0xf
	v_mov_b32_dpp v226, v128 row_ror:15 row_mask:0xf bank_mask:0xf
	v_mov_b32_dpp v207, v116 row_ror:1 row_mask:0xf bank_mask:0xf
	v_mov_b32_dpp v206, v36 row_ror:15 row_mask:0xf bank_mask:0xf
	v_mov_b32_dpp v225, v113 row_ror:1 row_mask:0xf bank_mask:0xf
	v_mov_b32_dpp v224, v129 row_ror:15 row_mask:0xf bank_mask:0xf
	v_mov_b32_dpp v3, v117 row_ror:1 row_mask:0xf bank_mask:0xf
	v_mov_b32_dpp v0, v37 row_ror:15 row_mask:0xf bank_mask:0xf
	v_mov_b32_dpp v231, v114 row_ror:1 row_mask:0xf bank_mask:0xf
	v_mov_b32_dpp v230, v130 row_ror:15 row_mask:0xf bank_mask:0xf
	v_mov_b32_dpp v223, v118 row_ror:1 row_mask:0xf bank_mask:0xf
	v_mov_b32_dpp v222, v38 row_ror:15 row_mask:0xf bank_mask:0xf
	v_mov_b32_dpp v229, v115 row_ror:1 row_mask:0xf bank_mask:0xf
	v_mov_b32_dpp v228, v131 row_ror:15 row_mask:0xf bank_mask:0xf
	v_mov_b32_dpp v221, v119 row_ror:1 row_mask:0xf bank_mask:0xf
	v_mov_b32_dpp v208, v39 row_ror:15 row_mask:0xf bank_mask:0xf
	s_movk_i32 s18, 0xb00
	v_cmp_gt_i32_e64 s[12:13], s12, v209
	v_mov_b32_dpp v227, v120 row_shr:1 row_mask:0xf bank_mask:0xf
	v_mov_b32_dpp v226, v120 row_shl:1 row_mask:0xf bank_mask:0xf
	v_mov_b32_dpp v207, v124 row_shr:1 row_mask:0xf bank_mask:0xf
	v_mov_b32_dpp v206, v124 row_shl:1 row_mask:0xf bank_mask:0xf
	v_mov_b32_dpp v225, v121 row_shr:1 row_mask:0xf bank_mask:0xf
	v_mov_b32_dpp v224, v121 row_shl:1 row_mask:0xf bank_mask:0xf
	v_mov_b32_dpp v3, v125 row_shr:1 row_mask:0xf bank_mask:0xf
	v_mov_b32_dpp v0, v125 row_shl:1 row_mask:0xf bank_mask:0xf
	v_mov_b32_dpp v231, v122 row_shr:1 row_mask:0xf bank_mask:0xf
	v_mov_b32_dpp v230, v122 row_shl:1 row_mask:0xf bank_mask:0xf
	v_mov_b32_dpp v223, v126 row_shr:1 row_mask:0xf bank_mask:0xf
	v_mov_b32_dpp v222, v126 row_shl:1 row_mask:0xf bank_mask:0xf
	v_mov_b32_dpp v229, v123 row_shr:1 row_mask:0xf bank_mask:0xf
	v_mov_b32_dpp v228, v123 row_shl:1 row_mask:0xf bank_mask:0xf
	v_mov_b32_dpp v221, v127 row_shr:1 row_mask:0xf bank_mask:0xf
	v_mov_b32_dpp v208, v127 row_shl:1 row_mask:0xf bank_mask:0xf
	v_and_b32_e32 v210, s52, v209
	v_mul_lo_u32 v209, v209, s18
	s_and_saveexec_b64 s[20:21], s[12:13]
	s_cbranch_execz .LBB0_303
	v_pk_mul_f32 v[232:233], v[122:123], v[162:163]
	v_pk_mul_f32 v[234:235], v[120:121], v[160:161]
	v_cmp_eq_u32_e32 vcc, 0, v210
	v_mov_b32_e32 v236, v234
	v_mov_b32_e32 v237, v232
	v_cndmask_b32_e64 v239, v231, 0, vcc
	v_mov_b32_e32 v232, v235
	v_cndmask_b32_e64 v238, v227, 0, vcc
	v_mov_b32_e32 v234, v152
	v_mov_b32_e32 v235, v154
	v_cmp_eq_u32_e64 s[18:19], s52, v210
	v_pk_fma_f32 v[234:235], v[234:235], v[238:239], v[236:237]
	v_mov_b32_e32 v231, v150
	v_cndmask_b32_e64 v227, v230, 0, s[18:19]
	v_cndmask_b32_e64 v226, v226, 0, s[18:19]
	v_mov_b32_e32 v230, v148
	v_pk_fma_f32 v[226:227], v[230:231], v[226:227], v[234:235]
	v_mov_b32_e32 v230, v144
	v_mov_b32_e32 v231, v146
	v_pk_add_f32 v[226:227], v[230:231], v[226:227]
	v_cndmask_b32_e64 v231, v229, 0, vcc
	v_mul_f32_e32 v230, 0x3d372713, v227
	v_mul_f32_e32 v230, v227, v230
	v_fma_f32 v230, v227, v230, v227
	v_mul_f32_e32 v230, 0x3fcc422a, v230
	v_mul_f32_e32 v230, 0xbfb8aa3b, v230
	v_exp_f32_e32 v234, v230
	v_cndmask_b32_e64 v230, v225, 0, vcc
	v_mov_b32_e32 v235, v155
	v_cndmask_b32_e64 v229, v228, 0, s[18:19]
	v_add_f32_e32 v225, 1.0, v234
	v_mov_b32_e32 v234, v153
	v_pk_fma_f32 v[230:231], v[234:235], v[230:231], v[232:233]
	v_cndmask_b32_e64 v228, v224, 0, s[18:19]
	v_mov_b32_e32 v232, v149
	v_mov_b32_e32 v233, v151
	v_pk_fma_f32 v[228:229], v[232:233], v[228:229], v[230:231]
	v_mov_b32_e32 v230, v145
	v_mov_b32_e32 v231, v147
	v_pk_add_f32 v[228:229], v[230:231], v[228:229]
	v_mul_f32_e32 v230, 0x3d372713, v226
	v_mul_f32_e32 v230, v226, v230
	v_fma_f32 v230, v226, v230, v226
	v_mul_f32_e32 v230, 0x3fcc422a, v230
	v_mul_f32_e32 v224, 0x3d372713, v228
	v_mul_f32_e32 v230, 0xbfb8aa3b, v230
	v_mul_f32_e32 v224, v228, v224
	v_exp_f32_e32 v230, v230
	v_fma_f32 v224, v228, v224, v228
	v_mul_f32_e32 v224, 0x3fcc422a, v224
	v_mul_f32_e32 v224, 0xbfb8aa3b, v224
	v_exp_f32_e32 v231, v224
	v_add_f32_e32 v224, 1.0, v230
	v_rcp_f32_e32 v225, v225
	v_rcp_f32_e32 v224, v224
	v_add_f32_e32 v230, 1.0, v231
	v_pk_mul_f32 v[240:241], v[126:127], v[158:159]
	v_pk_mul_f32 v[242:243], v[124:125], v[156:157]
	v_pk_mul_f32 v[224:225], v[226:227], v[224:225]
	v_cndmask_b32_e64 v227, v223, 0, vcc
	v_mul_f32_e32 v223, 0x3d372713, v229
	v_mul_f32_e32 v223, v229, v223
	v_fma_f32 v223, v229, v223, v229
	v_mul_f32_e32 v223, 0x3fcc422a, v223
	v_mul_f32_e32 v223, 0xbfb8aa3b, v223
	v_exp_f32_e32 v231, v223
	v_mov_b32_e32 v244, v242
	v_mov_b32_e32 v245, v240
	v_cndmask_b32_e64 v226, v207, 0, vcc
	v_mov_b32_e32 v232, v140
	v_mov_b32_e32 v233, v142
	v_pk_fma_f32 v[226:227], v[232:233], v[226:227], v[244:245]
	v_cndmask_b32_e64 v207, v222, 0, s[18:19]
	v_cndmask_b32_e64 v206, v206, 0, s[18:19]
	v_mov_b32_e32 v222, v136
	v_mov_b32_e32 v223, v138
	v_pk_fma_f32 v[206:207], v[222:223], v[206:207], v[226:227]
	v_add_f32_e32 v223, 1.0, v231
	v_rcp_f32_e32 v230, v230
	v_rcp_f32_e32 v231, v223
	v_mov_b32_e32 v222, v132
	v_mov_b32_e32 v223, v134
	v_pk_add_f32 v[206:207], v[222:223], v[206:207]
	v_mov_b32_e32 v240, v243
	v_pk_mul_f32 v[206:207], v[206:207], v[224:225]
	v_cndmask_b32_e64 v225, v221, 0, vcc
	v_cndmask_b32_e64 v224, v3, 0, vcc
	v_mov_b32_e32 v226, v141
	v_mov_b32_e32 v227, v143
	v_pk_mul_f32 v[222:223], v[228:229], v[230:231]
	v_pk_fma_f32 v[224:225], v[226:227], v[224:225], v[240:241]
	v_cndmask_b32_e64 v227, v208, 0, s[18:19]
	v_cndmask_b32_e64 v226, v0, 0, s[18:19]
	v_mov_b32_e32 v228, v137
	v_mov_b32_e32 v229, v139
	v_pk_fma_f32 v[224:225], v[228:229], v[226:227], v[224:225]
	v_mov_b32_e32 v226, v133
	v_mov_b32_e32 v227, v135
	v_pk_add_f32 v[224:225], v[226:227], v[224:225]
	v_and_b32_sdwa v0, v207, v185 dst_sel:DWORD dst_unused:UNUSED_PAD src0_sel:WORD_1 src1_sel:DWORD
	v_pk_mul_f32 v[222:223], v[224:225], v[222:223]
	v_and_b32_sdwa v3, v206, v185 dst_sel:DWORD dst_unused:UNUSED_PAD src0_sel:WORD_1 src1_sel:DWORD
	v_add3_u32 v3, v206, v3, s46
	v_add3_u32 v0, v207, v0, s46
	v_and_b32_sdwa v206, v223, v185 dst_sel:DWORD dst_unused:UNUSED_PAD src0_sel:WORD_1 src1_sel:DWORD
	v_and_b32_sdwa v207, v222, v185 dst_sel:DWORD dst_unused:UNUSED_PAD src0_sel:WORD_1 src1_sel:DWORD
	v_add3_u32 v206, v223, v206, s46
	v_add3_u32 v207, v222, v207, s46
	v_and_b32_e32 v206, 0xffff0000, v206
	v_and_b32_e32 v208, 0xffff0000, v207
	v_readlane_b32 s18, v249, 20
	v_add_lshl_u32 v234, v209, v2, 1
	v_or_b32_sdwa v207, v206, v0 dst_sel:DWORD dst_unused:UNUSED_PAD src0_sel:DWORD src1_sel:WORD_1
	v_or_b32_sdwa v206, v208, v3 dst_sel:DWORD dst_unused:UNUSED_PAD src0_sel:DWORD src1_sel:WORD_1
	v_readlane_b32 s19, v249, 21
	s_nop 4
	global_store_dwordx2 v234, v[206:207], s[18:19]
; __device__ __forceinline__ unsigned pack2(float lo, float hi) { return (unsigned)f2bf(lo) | ((unsigned)f2bf(hi) << 16); }
; __device__ __forceinline__ float sigmoidf_(float x) { return __builtin_amdgcn_rcpf(1.0f + __expf(-x)); }
;     __device__ __forceinline__ void operator()(const f32x4 (&acc)[2][2][4][2], const Unit& u, int wr, int wc, int fr, int fq) const {
;     ...
;                 for (int m = 0; m < 4; ++m) { const int r = 16 * m + fr, t = tb + r, pos = t & (L - 1);
;                     const bool hp = pos != 0, hn = pos != L - 1, valid = (r >= 1) & (r <= 62) & (t < TCH);
;                     float out[4];
; #pragma unroll
;                     for (int e = 0; e < 4; ++e) {
;                         const float xg = acc[ai][bj][m][0][e], xv = acc[ai][bj][m][1][e];
;                         float pg = dppf(m > 0 ? dppf(0.f, acc[ai][bj][m > 0 ? m - 1 : 0][0][e], 2) : 0.f, xg, 0);
;                         float ng = dppf(m < 3 ? dppf(0.f, acc[ai][bj][m < 3 ? m + 1 : 3][0][e], 3) : 0.f, xg, 1);
;                         float pv = dppf(m > 0 ? dppf(0.f, acc[ai][bj][m > 0 ? m - 1 : 0][1][e], 2) : 0.f, xv, 0);
;                         float nv = dppf(m < 3 ? dppf(0.f, acc[ai][bj][m < 3 ? m + 1 : 3][1][e], 3) : 0.f, xv, 1);
;                         if (!hp) { pg = 0.f; pv = 0.f; }
;                         if (!hn) { ng = 0.f; nv = 0.f; }
;                         const float hg = wg0[e] * pg + wg1[e] * xg + wg2[e] * ng + bgv[e], hv = wv0[e] * pv + wv1[e] * xv + wv2[e] * nv + bvv[e];
;                         out[e] = hg * sigmoidf_(1.5957691216f * (hg + 0.044715f * hg * hg * hg)) * hv; }
;                     if (valid) { uint2 o; o.x = pack2(out[0], out[1]); o.y = pack2(out[2], out[3]); *(uint2*)(ws + (unsigned)OFF_S + ((unsigned)t * (unsigned)DFF + (unsigned)J) * 2u) = o; }
.LBB0_303:
	s_or_b64 exec, exec, s[20:21]
	v_add_u32_e32 v207, s80, v201
	s_mov_b32 s18, 0x8000
	v_cmp_gt_i32_e32 vcc, s18, v207
	v_mov_b32_dpp v229, v120 row_ror:1 row_mask:0xf bank_mask:0xf
	v_mov_b32_dpp v228, v40 row_ror:15 row_mask:0xf bank_mask:0xf
	v_mov_b32_dpp v221, v124 row_ror:1 row_mask:0xf bank_mask:0xf
	v_mov_b32_dpp v206, v44 row_ror:15 row_mask:0xf bank_mask:0xf
	v_mov_b32_dpp v227, v121 row_ror:1 row_mask:0xf bank_mask:0xf
	v_mov_b32_dpp v226, v41 row_ror:15 row_mask:0xf bank_mask:0xf
	v_mov_b32_dpp v3, v125 row_ror:1 row_mask:0xf bank_mask:0xf
	v_mov_b32_dpp v0, v45 row_ror:15 row_mask:0xf bank_mask:0xf
	v_mov_b32_dpp v233, v122 row_ror:1 row_mask:0xf bank_mask:0xf
	v_mov_b32_dpp v232, v42 row_ror:15 row_mask:0xf bank_mask:0xf
	v_mov_b32_dpp v225, v126 row_ror:1 row_mask:0xf bank_mask:0xf
	v_mov_b32_dpp v224, v46 row_ror:15 row_mask:0xf bank_mask:0xf
	v_mov_b32_dpp v231, v123 row_ror:1 row_mask:0xf bank_mask:0xf
	v_mov_b32_dpp v230, v43 row_ror:15 row_mask:0xf bank_mask:0xf
	v_mov_b32_dpp v223, v127 row_ror:1 row_mask:0xf bank_mask:0xf
	v_mov_b32_dpp v222, v47 row_ror:15 row_mask:0xf bank_mask:0xf
	s_movk_i32 s18, 0xb00
	v_mov_b32_dpp v229, v128 row_shr:1 row_mask:0xf bank_mask:0xf
	v_mov_b32_dpp v228, v128 row_shl:1 row_mask:0xf bank_mask:0xf
	v_mov_b32_dpp v221, v36 row_shr:1 row_mask:0xf bank_mask:0xf
	v_mov_b32_dpp v206, v36 row_shl:1 row_mask:0xf bank_mask:0xf
	v_mov_b32_dpp v227, v129 row_shr:1 row_mask:0xf bank_mask:0xf
	v_mov_b32_dpp v226, v129 row_shl:1 row_mask:0xf bank_mask:0xf
	v_mov_b32_dpp v3, v37 row_shr:1 row_mask:0xf bank_mask:0xf
	v_mov_b32_dpp v0, v37 row_shl:1 row_mask:0xf bank_mask:0xf
	v_mov_b32_dpp v233, v130 row_shr:1 row_mask:0xf bank_mask:0xf
	v_mov_b32_dpp v232, v130 row_shl:1 row_mask:0xf bank_mask:0xf
	v_mov_b32_dpp v225, v38 row_shr:1 row_mask:0xf bank_mask:0xf
	v_mov_b32_dpp v224, v38 row_shl:1 row_mask:0xf bank_mask:0xf
	v_mov_b32_dpp v231, v131 row_shr:1 row_mask:0xf bank_mask:0xf
	v_mov_b32_dpp v230, v131 row_shl:1 row_mask:0xf bank_mask:0xf
	v_mov_b32_dpp v223, v39 row_shr:1 row_mask:0xf bank_mask:0xf
	v_mov_b32_dpp v222, v39 row_shl:1 row_mask:0xf bank_mask:0xf
	v_and_b32_e32 v208, s52, v207
	v_mul_lo_u32 v207, v207, s18
	s_and_saveexec_b64 s[64:65], vcc
	s_cbranch_execz .LBB0_305
	v_pk_mul_f32 v[234:235], v[130:131], v[162:163]
	v_pk_mul_f32 v[236:237], v[128:129], v[160:161]
	v_cmp_eq_u32_e64 s[18:19], 0, v208
	v_mov_b32_e32 v238, v236
	v_mov_b32_e32 v239, v234
	v_cndmask_b32_e64 v241, v233, 0, s[18:19]
	v_mov_b32_e32 v234, v237
	v_cndmask_b32_e64 v240, v229, 0, s[18:19]
	v_mov_b32_e32 v236, v152
	v_mov_b32_e32 v237, v154
	v_cmp_eq_u32_e64 s[20:21], s52, v208
	v_pk_fma_f32 v[236:237], v[236:237], v[240:241], v[238:239]
	v_mov_b32_e32 v233, v150
	v_cndmask_b32_e64 v229, v232, 0, s[20:21]
	v_cndmask_b32_e64 v228, v228, 0, s[20:21]
	v_mov_b32_e32 v232, v148
	v_pk_fma_f32 v[228:229], v[232:233], v[228:229], v[236:237]
	v_mov_b32_e32 v232, v144
	v_mov_b32_e32 v233, v146
	v_pk_add_f32 v[228:229], v[232:233], v[228:229]
	v_cndmask_b32_e64 v233, v231, 0, s[18:19]
	v_mul_f32_e32 v232, 0x3d372713, v229
	v_mul_f32_e32 v232, v229, v232
	v_fma_f32 v232, v229, v232, v229
	v_mul_f32_e32 v232, 0x3fcc422a, v232
	v_mul_f32_e32 v232, 0xbfb8aa3b, v232
	v_exp_f32_e32 v236, v232
	v_cndmask_b32_e64 v232, v227, 0, s[18:19]
	v_mov_b32_e32 v237, v155
	v_cndmask_b32_e64 v231, v230, 0, s[20:21]
	v_add_f32_e32 v227, 1.0, v236
	v_mov_b32_e32 v236, v153
	v_pk_fma_f32 v[232:233], v[236:237], v[232:233], v[234:235]
	v_cndmask_b32_e64 v230, v226, 0, s[20:21]
	v_mov_b32_e32 v234, v149
	v_mov_b32_e32 v235, v151
	v_pk_fma_f32 v[230:231], v[234:235], v[230:231], v[232:233]
	v_mov_b32_e32 v232, v145
	v_mov_b32_e32 v233, v147
	v_pk_add_f32 v[230:231], v[232:233], v[230:231]
	v_mul_f32_e32 v232, 0x3d372713, v228
	v_mul_f32_e32 v232, v228, v232
	v_fma_f32 v232, v228, v232, v228
	v_mul_f32_e32 v232, 0x3fcc422a, v232
	v_mul_f32_e32 v226, 0x3d372713, v230
	v_mul_f32_e32 v232, 0xbfb8aa3b, v232
	v_mul_f32_e32 v226, v230, v226
	v_exp_f32_e32 v232, v232
	v_fma_f32 v226, v230, v226, v230
	v_mul_f32_e32 v226, 0x3fcc422a, v226
	v_mul_f32_e32 v226, 0xbfb8aa3b, v226
	v_exp_f32_e32 v233, v226
	v_add_f32_e32 v226, 1.0, v232
	v_rcp_f32_e32 v227, v227
	v_rcp_f32_e32 v226, v226
	v_pk_mul_f32 v[242:243], v[38:39], v[158:159]
	v_pk_mul_f32 v[244:245], v[36:37], v[156:157]
	v_add_f32_e32 v232, 1.0, v233
	v_pk_mul_f32 v[226:227], v[228:229], v[226:227]
	v_cndmask_b32_e64 v229, v225, 0, s[18:19]
	v_cndmask_b32_e64 v225, v224, 0, s[20:21]
	v_cndmask_b32_e64 v224, v206, 0, s[20:21]
	v_mul_f32_e32 v206, 0x3d372713, v231
	v_mul_f32_e32 v206, v231, v206
	v_fma_f32 v206, v231, v206, v231
	v_mul_f32_e32 v206, 0x3fcc422a, v206
	v_mul_f32_e32 v206, 0xbfb8aa3b, v206
	v_exp_f32_e32 v206, v206
	v_mov_b32_e32 v246, v244
	v_mov_b32_e32 v247, v242
	v_rcp_f32_e32 v232, v232
	v_add_f32_e32 v206, 1.0, v206
	v_cndmask_b32_e64 v228, v221, 0, s[18:19]
	v_mov_b32_e32 v234, v140
	v_mov_b32_e32 v235, v142
	v_rcp_f32_e32 v233, v206
	v_pk_fma_f32 v[228:229], v[234:235], v[228:229], v[246:247]
	v_mov_b32_e32 v234, v136
	v_mov_b32_e32 v235, v138
	v_pk_fma_f32 v[224:225], v[234:235], v[224:225], v[228:229]
	v_mov_b32_e32 v228, v132
	v_mov_b32_e32 v229, v134
	v_pk_add_f32 v[224:225], v[228:229], v[224:225]
	v_mov_b32_e32 v242, v245
	v_pk_mul_f32 v[224:225], v[224:225], v[226:227]
	v_pk_mul_f32 v[226:227], v[230:231], v[232:233]
	v_cndmask_b32_e64 v229, v223, 0, s[18:19]
	v_cndmask_b32_e64 v228, v3, 0, s[18:19]
	v_mov_b32_e32 v230, v141
	v_mov_b32_e32 v231, v143
	v_pk_fma_f32 v[228:229], v[230:231], v[228:229], v[242:243]
	v_cndmask_b32_e64 v223, v222, 0, s[20:21]
	v_cndmask_b32_e64 v222, v0, 0, s[20:21]
	v_mov_b32_e32 v230, v137
	v_mov_b32_e32 v231, v139
	v_pk_fma_f32 v[222:223], v[230:231], v[222:223], v[228:229]
	v_mov_b32_e32 v228, v133
	v_mov_b32_e32 v229, v135
	v_pk_add_f32 v[222:223], v[228:229], v[222:223]
	v_and_b32_sdwa v0, v225, v185 dst_sel:DWORD dst_unused:UNUSED_PAD src0_sel:WORD_1 src1_sel:DWORD
	v_pk_mul_f32 v[222:223], v[222:223], v[226:227]
	v_and_b32_sdwa v3, v224, v185 dst_sel:DWORD dst_unused:UNUSED_PAD src0_sel:WORD_1 src1_sel:DWORD
	v_and_b32_sdwa v206, v223, v185 dst_sel:DWORD dst_unused:UNUSED_PAD src0_sel:WORD_1 src1_sel:DWORD
	v_and_b32_sdwa v221, v222, v185 dst_sel:DWORD dst_unused:UNUSED_PAD src0_sel:WORD_1 src1_sel:DWORD
	v_add3_u32 v206, v223, v206, s46
	v_add3_u32 v221, v222, v221, s46
	v_add3_u32 v3, v224, v3, s46
	v_add3_u32 v0, v225, v0, s46
	v_and_b32_e32 v206, 0xffff0000, v206
	v_and_b32_e32 v221, 0xffff0000, v221
	v_readlane_b32 s18, v249, 20
	v_add_lshl_u32 v236, v207, v2, 1
	v_or_b32_sdwa v223, v206, v0 dst_sel:DWORD dst_unused:UNUSED_PAD src0_sel:DWORD src1_sel:WORD_1
	v_or_b32_sdwa v222, v221, v3 dst_sel:DWORD dst_unused:UNUSED_PAD src0_sel:DWORD src1_sel:WORD_1
	v_readlane_b32 s19, v249, 21
	s_nop 4
	global_store_dwordx2 v236, v[222:223], s[18:19]
; __device__ __forceinline__ unsigned pack2(float lo, float hi) { return (unsigned)f2bf(lo) | ((unsigned)f2bf(hi) << 16); }
; __device__ __forceinline__ float sigmoidf_(float x) { return __builtin_amdgcn_rcpf(1.0f + __expf(-x)); }
;     __device__ __forceinline__ void operator()(const f32x4 (&acc)[2][2][4][2], const Unit& u, int wr, int wc, int fr, int fq) const {
;     ...
;                 for (int m = 0; m < 4; ++m) { const int r = 16 * m + fr, t = tb + r, pos = t & (L - 1);
;                     const bool hp = pos != 0, hn = pos != L - 1, valid = (r >= 1) & (r <= 62) & (t < TCH);
;                     float out[4];
; #pragma unroll
;                     for (int e = 0; e < 4; ++e) {
;                         const float xg = acc[ai][bj][m][0][e], xv = acc[ai][bj][m][1][e];
;                         float pg = dppf(m > 0 ? dppf(0.f, acc[ai][bj][m > 0 ? m - 1 : 0][0][e], 2) : 0.f, xg, 0);
;                         float ng = dppf(m < 3 ? dppf(0.f, acc[ai][bj][m < 3 ? m + 1 : 3][0][e], 3) : 0.f, xg, 1);
;                         float pv = dppf(m > 0 ? dppf(0.f, acc[ai][bj][m > 0 ? m - 1 : 0][1][e], 2) : 0.f, xv, 0);
;                         float nv = dppf(m < 3 ? dppf(0.f, acc[ai][bj][m < 3 ? m + 1 : 3][1][e], 3) : 0.f, xv, 1);
;                         if (!hp) { pg = 0.f; pv = 0.f; }
;                         if (!hn) { ng = 0.f; nv = 0.f; }
;                         const float hg = wg0[e] * pg + wg1[e] * xg + wg2[e] * ng + bgv[e], hv = wv0[e] * pv + wv1[e] * xv + wv2[e] * nv + bvv[e];
;                         out[e] = hg * sigmoidf_(1.5957691216f * (hg + 0.044715f * hg * hg * hg)) * hv; }
;                     if (valid) { uint2 o; o.x = pack2(out[0], out[1]); o.y = pack2(out[2], out[3]); *(uint2*)(ws + (unsigned)OFF_S + ((unsigned)t * (unsigned)DFF + (unsigned)J) * 2u) = o; }
.LBB0_305:
	s_or_b64 exec, exec, s[64:65]
	v_add_u32_e32 v0, s80, v202
	s_mov_b32 s18, 0x8000
	v_readlane_b32 s20, v249, 63
	v_cmp_gt_i32_e64 s[18:19], s18, v0
	v_readlane_b32 s21, v248, 0
	v_mov_b32_dpp v231, v128 row_ror:1 row_mask:0xf bank_mask:0xf
	v_mov_b32_e32 v230, 0
	v_mov_b32_dpp v225, v36 row_ror:1 row_mask:0xf bank_mask:0xf
	v_mov_b32_e32 v223, 0
	v_mov_b32_dpp v229, v129 row_ror:1 row_mask:0xf bank_mask:0xf
	v_mov_b32_e32 v228, 0
	v_mov_b32_dpp v221, v37 row_ror:1 row_mask:0xf bank_mask:0xf
	v_mov_b32_e32 v3, 0
	v_mov_b32_dpp v235, v130 row_ror:1 row_mask:0xf bank_mask:0xf
	v_mov_b32_e32 v234, 0
	v_mov_b32_dpp v227, v38 row_ror:1 row_mask:0xf bank_mask:0xf
	v_mov_b32_e32 v226, 0
	v_mov_b32_dpp v233, v131 row_ror:1 row_mask:0xf bank_mask:0xf
	v_mov_b32_e32 v232, 0
	v_mov_b32_dpp v224, v39 row_ror:1 row_mask:0xf bank_mask:0xf
	v_mov_b32_e32 v222, 0
	s_and_b64 s[64:65], s[20:21], s[18:19]
	s_movk_i32 s18, 0xb00
	v_mov_b32_dpp v231, v40 row_shr:1 row_mask:0xf bank_mask:0xf
	v_mov_b32_dpp v230, v40 row_shl:1 row_mask:0xf bank_mask:0xf
	v_mov_b32_dpp v225, v44 row_shr:1 row_mask:0xf bank_mask:0xf
	v_mov_b32_dpp v223, v44 row_shl:1 row_mask:0xf bank_mask:0xf
	v_mov_b32_dpp v229, v41 row_shr:1 row_mask:0xf bank_mask:0xf
	v_mov_b32_dpp v228, v41 row_shl:1 row_mask:0xf bank_mask:0xf
	v_mov_b32_dpp v221, v45 row_shr:1 row_mask:0xf bank_mask:0xf
	v_mov_b32_dpp v3, v45 row_shl:1 row_mask:0xf bank_mask:0xf
	v_mov_b32_dpp v235, v42 row_shr:1 row_mask:0xf bank_mask:0xf
	v_mov_b32_dpp v234, v42 row_shl:1 row_mask:0xf bank_mask:0xf
	v_mov_b32_dpp v227, v46 row_shr:1 row_mask:0xf bank_mask:0xf
	v_mov_b32_dpp v226, v46 row_shl:1 row_mask:0xf bank_mask:0xf
	v_mov_b32_dpp v233, v43 row_shr:1 row_mask:0xf bank_mask:0xf
	v_mov_b32_dpp v232, v43 row_shl:1 row_mask:0xf bank_mask:0xf
	v_mov_b32_dpp v224, v47 row_shr:1 row_mask:0xf bank_mask:0xf
	v_mov_b32_dpp v222, v47 row_shl:1 row_mask:0xf bank_mask:0xf
	v_and_b32_e32 v206, s52, v0
	v_mul_lo_u32 v0, v0, s18
	s_and_saveexec_b64 s[80:81], s[64:65]
	s_cbranch_execz .LBB0_307
	v_pk_mul_f32 v[162:163], v[42:43], v[162:163]
	v_pk_mul_f32 v[160:161], v[40:41], v[160:161]
	v_cmp_eq_u32_e64 s[18:19], 0, v206
	v_mov_b32_e32 v236, v160
	v_mov_b32_e32 v237, v162
	v_cndmask_b32_e64 v239, v235, 0, s[18:19]
	v_mov_b32_e32 v162, v161
	v_cndmask_b32_e64 v238, v231, 0, s[18:19]
	v_mov_b32_e32 v160, v152
	v_mov_b32_e32 v161, v154
	v_cmp_eq_u32_e64 s[20:21], s52, v206
	v_pk_fma_f32 v[160:161], v[160:161], v[238:239], v[236:237]
	v_mov_b32_e32 v235, v150
	v_cndmask_b32_e64 v231, v234, 0, s[20:21]
	v_cndmask_b32_e64 v230, v230, 0, s[20:21]
	v_mov_b32_e32 v234, v148
	v_pk_fma_f32 v[160:161], v[234:235], v[230:231], v[160:161]
	v_mov_b32_e32 v230, v144
	v_mov_b32_e32 v231, v146
	v_pk_add_f32 v[160:161], v[230:231], v[160:161]
	v_pk_mul_f32 v[158:159], v[46:47], v[158:159]
	v_mul_f32_e32 v144, 0x3d372713, v161
	v_mul_f32_e32 v144, v161, v144
	v_fma_f32 v144, v161, v144, v161
	v_mul_f32_e32 v144, 0x3fcc422a, v144
	v_mul_f32_e32 v144, 0xbfb8aa3b, v144
	v_exp_f32_e32 v144, v144
	v_pk_mul_f32 v[156:157], v[44:45], v[156:157]
	v_mov_b32_e32 v241, v158
	v_mov_b32_e32 v240, v156
	v_cndmask_b32_e64 v156, v229, 0, s[18:19]
	v_mov_b32_e32 v158, v157
	v_cndmask_b32_e64 v157, v233, 0, s[18:19]
	v_mov_b32_e32 v154, v153
	v_pk_fma_f32 v[152:153], v[154:155], v[156:157], v[162:163]
	v_cndmask_b32_e64 v155, v232, 0, s[20:21]
	v_cndmask_b32_e64 v154, v228, 0, s[20:21]
	v_mov_b32_e32 v150, v149
	v_add_f32_e32 v144, 1.0, v144
	v_pk_fma_f32 v[148:149], v[150:151], v[154:155], v[152:153]
	v_mov_b32_e32 v146, v145
	v_rcp_f32_e32 v229, v144
	v_pk_add_f32 v[144:145], v[146:147], v[148:149]
	v_mul_f32_e32 v147, 0x3d372713, v160
	v_mul_f32_e32 v146, 0x3d372713, v144
	v_mov_b32_e32 v154, v136
	v_mul_f32_e32 v136, 0x3d372713, v145
	v_mul_f32_e32 v146, v144, v146
	v_mul_f32_e32 v147, v160, v147
	v_mul_f32_e32 v136, v145, v136
	v_fma_f32 v146, v144, v146, v144
	v_fma_f32 v147, v160, v147, v160
	v_fma_f32 v136, v145, v136, v145
	v_mul_f32_e32 v147, 0x3fcc422a, v147
	v_mul_f32_e32 v146, 0x3fcc422a, v146
	v_mul_f32_e32 v136, 0x3fcc422a, v136
	v_mul_f32_e32 v147, 0xbfb8aa3b, v147
	v_mul_f32_e32 v146, 0xbfb8aa3b, v146
	v_mul_f32_e32 v136, 0xbfb8aa3b, v136
	v_exp_f32_e32 v147, v147
	v_exp_f32_e32 v146, v146
	v_exp_f32_e32 v136, v136
	v_cndmask_b32_e64 v151, v227, 0, s[18:19]
	v_cndmask_b32_e64 v150, v225, 0, s[18:19]
	v_mov_b32_e32 v152, v140
	v_mov_b32_e32 v153, v142
	v_pk_fma_f32 v[150:151], v[152:153], v[150:151], v[240:241]
	v_cndmask_b32_e64 v153, v226, 0, s[20:21]
	v_cndmask_b32_e64 v152, v223, 0, s[20:21]
	v_mov_b32_e32 v155, v138
	v_add_f32_e32 v147, 1.0, v147
	v_add_f32_e32 v146, 1.0, v146
	v_pk_fma_f32 v[150:151], v[154:155], v[152:153], v[150:151]
	v_mov_b32_e32 v152, v132
	v_add_f32_e32 v132, 1.0, v136
	v_rcp_f32_e32 v228, v147
	v_rcp_f32_e32 v146, v146
	v_rcp_f32_e32 v147, v132
	v_mov_b32_e32 v142, v141
	v_mov_b32_e32 v138, v137
	v_mov_b32_e32 v153, v134
	v_pk_mul_f32 v[144:145], v[144:145], v[146:147]
	v_cndmask_b32_e64 v147, v224, 0, s[18:19]
	v_cndmask_b32_e64 v146, v221, 0, s[18:19]
	v_pk_fma_f32 v[140:141], v[142:143], v[146:147], v[158:159]
	v_cndmask_b32_e64 v143, v222, 0, s[20:21]
	v_cndmask_b32_e64 v142, v3, 0, s[20:21]
	v_pk_fma_f32 v[136:137], v[138:139], v[142:143], v[140:141]
	v_mov_b32_e32 v134, v133
	v_pk_add_f32 v[132:133], v[134:135], v[136:137]
	v_pk_mul_f32 v[148:149], v[160:161], v[228:229]
	v_pk_add_f32 v[150:151], v[152:153], v[150:151]
	v_pk_mul_f32 v[132:133], v[132:133], v[144:145]
	v_pk_mul_f32 v[148:149], v[150:151], v[148:149]
	v_and_b32_sdwa v135, v133, v185 dst_sel:DWORD dst_unused:UNUSED_PAD src0_sel:WORD_1 src1_sel:DWORD
	v_and_b32_sdwa v136, v132, v185 dst_sel:DWORD dst_unused:UNUSED_PAD src0_sel:WORD_1 src1_sel:DWORD
	v_and_b32_sdwa v3, v149, v185 dst_sel:DWORD dst_unused:UNUSED_PAD src0_sel:WORD_1 src1_sel:DWORD
	v_and_b32_sdwa v134, v148, v185 dst_sel:DWORD dst_unused:UNUSED_PAD src0_sel:WORD_1 src1_sel:DWORD
	v_add3_u32 v133, v133, v135, s46
	v_add3_u32 v132, v132, v136, s46
	v_add3_u32 v134, v148, v134, s46
	v_add3_u32 v3, v149, v3, s46
	v_and_b32_e32 v133, 0xffff0000, v133
	v_and_b32_e32 v132, 0xffff0000, v132
	v_readlane_b32 s18, v249, 20
	v_add_lshl_u32 v156, v0, v2, 1
	v_or_b32_sdwa v133, v133, v3 dst_sel:DWORD dst_unused:UNUSED_PAD src0_sel:DWORD src1_sel:WORD_1
	v_or_b32_sdwa v132, v132, v134 dst_sel:DWORD dst_unused:UNUSED_PAD src0_sel:DWORD src1_sel:WORD_1
	v_readlane_b32 s19, v249, 21
	s_nop 4
	global_store_dwordx2 v156, v[132:133], s[18:19]
; __device__ __forceinline__ float sigmoidf_(float x) { return __builtin_amdgcn_rcpf(1.0f + __expf(-x)); }
;     __device__ __forceinline__ void operator()(const f32x4 (&acc)[2][2][4][2], const Unit& u, int wr, int wc, int fr, int fq) const {
;     ...
;         for (int bj = 0; bj < 2; ++bj) { const int J = u.pn * 128 + bj * 64 + wc * 16 + 4 * fq;
;             const f32x4 wg0 = *(const f32x4*)(cw + J), wg1 = *(const f32x4*)(cw + 5632 + J), wg2 = *(const f32x4*)(cw + 11264 + J), bgv = *(const f32x4*)(cb + J);
;             const f32x4 wv0 = *(const f32x4*)(cw + DFF + J), wv1 = *(const f32x4*)(cw + 5632 + DFF + J), wv2 = *(const f32x4*)(cw + 11264 + DFF + J), bvv = *(const f32x4*)(cb + DFF + J);
; #pragma unroll
;             for (int ai = 0; ai < 2; ++ai) { const int tb = u.pm * 248 + 62 * (ai * 2 + wr) - 1;
; #pragma unroll
;                 for (int m = 0; m < 4; ++m) { const int r = 16 * m + fr, t = tb + r, pos = t & (L - 1);
;                     const bool hp = pos != 0, hn = pos != L - 1, valid = (r >= 1) & (r <= 62) & (t < TCH);
;                     float out[4];
; #pragma unroll
;                     for (int e = 0; e < 4; ++e) {
;                         const float xg = acc[ai][bj][m][0][e], xv = acc[ai][bj][m][1][e];
;                         float pg = dppf(m > 0 ? dppf(0.f, acc[ai][bj][m > 0 ? m - 1 : 0][0][e], 2) : 0.f, xg, 0);
;                         float ng = dppf(m < 3 ? dppf(0.f, acc[ai][bj][m < 3 ? m + 1 : 3][0][e], 3) : 0.f, xg, 1);
;                         float pv = dppf(m > 0 ? dppf(0.f, acc[ai][bj][m > 0 ? m - 1 : 0][1][e], 2) : 0.f, xv, 0);
;                         float nv = dppf(m < 3 ? dppf(0.f, acc[ai][bj][m < 3 ? m + 1 : 3][1][e], 3) : 0.f, xv, 1);
;                         if (!hp) { pg = 0.f; pv = 0.f; }
;                         if (!hn) { ng = 0.f; nv = 0.f; }
;                         const float hg = wg0[e] * pg + wg1[e] * xg + wg2[e] * ng + bgv[e], hv = wv0[e] * pv + wv1[e] * xv + wv2[e] * nv + bvv[e];
;                         out[e] = hg * sigmoidf_(1.5957691216f * (hg + 0.044715f * hg * hg * hg)) * hv; }
.LBB0_307:
	s_or_b64 exec, exec, s[80:81]
	v_or_b32_e32 v2, 64, v2
	v_ashrrev_i32_e32 v3, 31, v2
	s_waitcnt vmcnt(0)
	v_lshlrev_b64 v[132:133], 2, v[2:3]
	v_lshl_add_u64 v[134:135], s[56:57], 0, v[132:133]
	global_load_dwordx4 v[152:155], v[176:177], off offset:256
	v_lshl_add_u64 v[136:137], s[58:59], 0, v[132:133]
	global_load_dwordx4 v[160:163], v[134:135], off
	global_load_dwordx4 v[148:151], v[136:137], off
	global_load_dwordx4 v[144:147], v[178:179], off offset:256
	v_lshl_add_u64 v[134:135], s[76:77], 0, v[132:133]
	v_lshl_add_u64 v[136:137], s[88:89], 0, v[132:133]
	global_load_dwordx4 v[140:143], v[134:135], off
	global_load_dwordx4 v[156:159], v[136:137], off
	v_lshl_add_u64 v[134:135], s[72:73], 0, v[132:133]
	v_lshl_add_u64 v[132:133], s[74:75], 0, v[132:133]
	global_load_dwordx4 v[136:139], v[134:135], off
	global_load_dwordx4 v[132:135], v[132:133], off
	v_mov_b32_e32 v227, 0
	v_mov_b32_dpp v226, v88 row_ror:15 row_mask:0xf bank_mask:0xf
	v_mov_b32_e32 v221, 0
	v_mov_b32_dpp v179, v92 row_ror:15 row_mask:0xf bank_mask:0xf
	v_mov_b32_e32 v229, 0
	v_mov_b32_dpp v224, v89 row_ror:15 row_mask:0xf bank_mask:0xf
	v_mov_b32_e32 v176, 0
	v_mov_b32_dpp v3, v93 row_ror:15 row_mask:0xf bank_mask:0xf
	v_mov_b32_e32 v231, 0
	v_mov_b32_dpp v228, v90 row_ror:15 row_mask:0xf bank_mask:0xf
	v_mov_b32_e32 v223, 0
	v_mov_b32_dpp v222, v94 row_ror:15 row_mask:0xf bank_mask:0xf
	v_mov_b32_e32 v230, 0
	v_mov_b32_dpp v225, v91 row_ror:15 row_mask:0xf bank_mask:0xf
	v_mov_b32_e32 v178, 0
	v_mov_b32_dpp v177, v95 row_ror:15 row_mask:0xf bank_mask:0xf
	v_mov_b32_dpp v227, v80 row_shr:1 row_mask:0xf bank_mask:0xf
	v_mov_b32_dpp v226, v80 row_shl:1 row_mask:0xf bank_mask:0xf
	v_mov_b32_dpp v221, v84 row_shr:1 row_mask:0xf bank_mask:0xf
	v_mov_b32_dpp v179, v84 row_shl:1 row_mask:0xf bank_mask:0xf
	v_mov_b32_dpp v229, v81 row_shr:1 row_mask:0xf bank_mask:0xf
	v_mov_b32_dpp v224, v81 row_shl:1 row_mask:0xf bank_mask:0xf
	v_mov_b32_dpp v176, v85 row_shr:1 row_mask:0xf bank_mask:0xf
	v_mov_b32_dpp v3, v85 row_shl:1 row_mask:0xf bank_mask:0xf
	v_mov_b32_dpp v231, v82 row_shr:1 row_mask:0xf bank_mask:0xf
	v_mov_b32_dpp v228, v82 row_shl:1 row_mask:0xf bank_mask:0xf
	v_mov_b32_dpp v223, v86 row_shr:1 row_mask:0xf bank_mask:0xf
	v_mov_b32_dpp v222, v86 row_shl:1 row_mask:0xf bank_mask:0xf
	v_mov_b32_dpp v230, v83 row_shr:1 row_mask:0xf bank_mask:0xf
	v_mov_b32_dpp v225, v83 row_shl:1 row_mask:0xf bank_mask:0xf
	v_mov_b32_dpp v178, v87 row_shr:1 row_mask:0xf bank_mask:0xf
	v_mov_b32_dpp v177, v87 row_shl:1 row_mask:0xf bank_mask:0xf
	s_waitcnt vmcnt(0)
	s_and_saveexec_b64 s[56:57], s[78:79]
	s_cbranch_execz .LBB0_309
	v_pk_mul_f32 v[232:233], v[82:83], v[162:163]
	v_pk_mul_f32 v[234:235], v[80:81], v[160:161]
	v_cmp_eq_u32_e64 s[20:21], 0, v220
	v_mov_b32_e32 v236, v234
	v_mov_b32_e32 v237, v232
	v_cndmask_b32_e64 v239, v231, 0, s[20:21]
	v_cmp_eq_u32_e64 s[18:19], s52, v220
	v_mov_b32_e32 v232, v235
	v_cndmask_b32_e64 v238, v227, 0, s[20:21]
	v_cndmask_b32_e64 v235, v230, 0, s[20:21]
	v_mov_b32_e32 v230, v152
	v_mov_b32_e32 v231, v154
	v_cndmask_b32_e64 v234, v229, 0, s[20:21]
	v_pk_fma_f32 v[230:231], v[230:231], v[238:239], v[236:237]
	v_cndmask_b32_e64 v227, v228, 0, s[18:19]
	v_cndmask_b32_e64 v226, v226, 0, s[18:19]
	v_mov_b32_e32 v228, v148
	v_mov_b32_e32 v229, v150
	v_pk_fma_f32 v[226:227], v[228:229], v[226:227], v[230:231]
	v_mov_b32_e32 v228, v144
	v_mov_b32_e32 v229, v146
	v_pk_add_f32 v[226:227], v[228:229], v[226:227]
	v_mov_b32_e32 v230, v153
	v_mul_f32_e32 v220, 0x3d372713, v227
	v_mul_f32_e32 v228, 0x3d372713, v226
	v_mul_f32_e32 v220, v227, v220
	v_mul_f32_e32 v228, v226, v228
	v_fma_f32 v220, v227, v220, v227
	v_fma_f32 v228, v226, v228, v226
	v_mul_f32_e32 v220, 0x3fcc422a, v220
	v_mul_f32_e32 v228, 0x3fcc422a, v228
	v_mul_f32_e32 v220, 0xbfb8aa3b, v220
	v_mul_f32_e32 v228, 0xbfb8aa3b, v228
	v_exp_f32_e32 v220, v220
	v_exp_f32_e32 v228, v228
	v_mov_b32_e32 v231, v155
	v_pk_fma_f32 v[230:231], v[230:231], v[234:235], v[232:233]
	v_add_f32_e32 v220, 1.0, v220
	v_add_f32_e32 v228, 1.0, v228
	v_rcp_f32_e32 v229, v220
	v_rcp_f32_e32 v228, v228
	v_cndmask_b32_e64 v225, v225, 0, s[18:19]
	v_cndmask_b32_e64 v224, v224, 0, s[18:19]
	v_mov_b32_e32 v232, v149
	v_mov_b32_e32 v233, v151
	v_pk_fma_f32 v[224:225], v[232:233], v[224:225], v[230:231]
	v_mov_b32_e32 v230, v145
	v_mov_b32_e32 v231, v147
	v_pk_add_f32 v[224:225], v[230:231], v[224:225]
	v_pk_mul_f32 v[226:227], v[226:227], v[228:229]
	v_mul_f32_e32 v220, 0x3d372713, v224
	v_cndmask_b32_e64 v229, v223, 0, s[20:21]
	v_cndmask_b32_e64 v223, v222, 0, s[18:19]
	v_cndmask_b32_e64 v222, v179, 0, s[18:19]
	v_mul_f32_e32 v179, 0x3d372713, v225
	v_mul_f32_e32 v220, v224, v220
	v_mul_f32_e32 v179, v225, v179
	v_fma_f32 v220, v224, v220, v224
	v_fma_f32 v179, v225, v179, v225
	v_mul_f32_e32 v220, 0x3fcc422a, v220
	v_mul_f32_e32 v179, 0x3fcc422a, v179
	v_mul_f32_e32 v220, 0xbfb8aa3b, v220
	v_mul_f32_e32 v179, 0xbfb8aa3b, v179
	v_exp_f32_e32 v220, v220
	v_exp_f32_e32 v179, v179
	v_cndmask_b32_e64 v228, v221, 0, s[20:21]
	v_pk_mul_f32 v[240:241], v[86:87], v[158:159]
	v_add_f32_e32 v220, 1.0, v220
	v_add_f32_e32 v179, 1.0, v179
	v_rcp_f32_e32 v220, v220
	v_rcp_f32_e32 v221, v179
	v_pk_mul_f32 v[242:243], v[84:85], v[156:157]
	v_mov_b32_e32 v245, v240
	v_mov_b32_e32 v240, v243
	v_pk_mul_f32 v[220:221], v[224:225], v[220:221]
	v_cndmask_b32_e64 v179, v178, 0, s[20:21]
	v_cndmask_b32_e64 v178, v176, 0, s[20:21]
	v_mov_b32_e32 v224, v141
	v_mov_b32_e32 v225, v143
	v_mov_b32_e32 v244, v242
	v_mov_b32_e32 v230, v140
	v_mov_b32_e32 v231, v142
	v_pk_fma_f32 v[178:179], v[224:225], v[178:179], v[240:241]
; __device__ __forceinline__ unsigned pack2(float lo, float hi) { return (unsigned)f2bf(lo) | ((unsigned)f2bf(hi) << 16); }
; __device__ __forceinline__ float sigmoidf_(float x) { return __builtin_amdgcn_rcpf(1.0f + __expf(-x)); }
;     __device__ __forceinline__ void operator()(const f32x4 (&acc)[2][2][4][2], const Unit& u, int wr, int wc, int fr, int fq) const {
;     ...
;                 for (int m = 0; m < 4; ++m) { const int r = 16 * m + fr, t = tb + r, pos = t & (L - 1);
;                     const bool hp = pos != 0, hn = pos != L - 1, valid = (r >= 1) & (r <= 62) & (t < TCH);
;                     float out[4];
; #pragma unroll
;                     for (int e = 0; e < 4; ++e) {
;                         const float xg = acc[ai][bj][m][0][e], xv = acc[ai][bj][m][1][e];
;                         float pg = dppf(m > 0 ? dppf(0.f, acc[ai][bj][m > 0 ? m - 1 : 0][0][e], 2) : 0.f, xg, 0);
;                         float ng = dppf(m < 3 ? dppf(0.f, acc[ai][bj][m < 3 ? m + 1 : 3][0][e], 3) : 0.f, xg, 1);
;                         float pv = dppf(m > 0 ? dppf(0.f, acc[ai][bj][m > 0 ? m - 1 : 0][1][e], 2) : 0.f, xv, 0);
;                         float nv = dppf(m < 3 ? dppf(0.f, acc[ai][bj][m < 3 ? m + 1 : 3][1][e], 3) : 0.f, xv, 1);
;                         if (!hp) { pg = 0.f; pv = 0.f; }
;                         if (!hn) { ng = 0.f; nv = 0.f; }
;                         const float hg = wg0[e] * pg + wg1[e] * xg + wg2[e] * ng + bgv[e], hv = wv0[e] * pv + wv1[e] * xv + wv2[e] * nv + bvv[e];
;                         out[e] = hg * sigmoidf_(1.5957691216f * (hg + 0.044715f * hg * hg * hg)) * hv; }
;                     if (valid) { uint2 o; o.x = pack2(out[0], out[1]); o.y = pack2(out[2], out[3]); *(uint2*)(ws + (unsigned)OFF_S + ((unsigned)t * (unsigned)DFF + (unsigned)J) * 2u) = o; }
	v_cndmask_b32_e64 v177, v177, 0, s[18:19]
	v_cndmask_b32_e64 v176, v3, 0, s[18:19]
	v_mov_b32_e32 v224, v137
	v_mov_b32_e32 v225, v139
	v_pk_fma_f32 v[228:229], v[230:231], v[228:229], v[244:245]
	v_mov_b32_e32 v230, v136
	v_mov_b32_e32 v231, v138
	v_pk_fma_f32 v[176:177], v[224:225], v[176:177], v[178:179]
	v_mov_b32_e32 v178, v133
	v_mov_b32_e32 v179, v135
	v_pk_fma_f32 v[222:223], v[230:231], v[222:223], v[228:229]
	v_mov_b32_e32 v228, v132
	v_mov_b32_e32 v229, v134
	v_pk_add_f32 v[176:177], v[178:179], v[176:177]
	v_pk_add_f32 v[222:223], v[228:229], v[222:223]
	v_pk_mul_f32 v[176:177], v[176:177], v[220:221]
	v_pk_mul_f32 v[222:223], v[222:223], v[226:227]
	v_and_b32_sdwa v179, v177, v185 dst_sel:DWORD dst_unused:UNUSED_PAD src0_sel:WORD_1 src1_sel:DWORD
	v_and_b32_sdwa v220, v176, v185 dst_sel:DWORD dst_unused:UNUSED_PAD src0_sel:WORD_1 src1_sel:DWORD
	v_and_b32_sdwa v3, v223, v185 dst_sel:DWORD dst_unused:UNUSED_PAD src0_sel:WORD_1 src1_sel:DWORD
	v_and_b32_sdwa v178, v222, v185 dst_sel:DWORD dst_unused:UNUSED_PAD src0_sel:WORD_1 src1_sel:DWORD
	v_add3_u32 v177, v177, v179, s46
	v_add3_u32 v176, v176, v220, s46
	v_add3_u32 v178, v222, v178, s46
	v_add3_u32 v3, v223, v3, s46
	v_and_b32_e32 v177, 0xffff0000, v177
	v_and_b32_e32 v176, 0xffff0000, v176
	v_readlane_b32 s18, v249, 20
	v_add_lshl_u32 v219, v219, v2, 1
	v_or_b32_sdwa v177, v177, v3 dst_sel:DWORD dst_unused:UNUSED_PAD src0_sel:DWORD src1_sel:WORD_1
	v_or_b32_sdwa v176, v176, v178 dst_sel:DWORD dst_unused:UNUSED_PAD src0_sel:DWORD src1_sel:WORD_1
	v_readlane_b32 s19, v249, 21
	s_nop 4
	global_store_dwordx2 v219, v[176:177], s[18:19]
.LBB0_309:
	s_or_b64 exec, exec, s[56:57]
	v_mov_b32_dpp v225, v80 row_ror:1 row_mask:0xf bank_mask:0xf
	v_mov_b32_dpp v223, v96 row_ror:15 row_mask:0xf bank_mask:0xf
	v_mov_b32_dpp v219, v84 row_ror:1 row_mask:0xf bank_mask:0xf
	v_mov_b32_dpp v179, v100 row_ror:15 row_mask:0xf bank_mask:0xf
	v_mov_b32_dpp v227, v81 row_ror:1 row_mask:0xf bank_mask:0xf
	v_mov_b32_dpp v222, v97 row_ror:15 row_mask:0xf bank_mask:0xf
	v_mov_b32_dpp v176, v85 row_ror:1 row_mask:0xf bank_mask:0xf
	v_mov_b32_dpp v3, v101 row_ror:15 row_mask:0xf bank_mask:0xf
	v_mov_b32_dpp v229, v82 row_ror:1 row_mask:0xf bank_mask:0xf
	v_mov_b32_dpp v226, v98 row_ror:15 row_mask:0xf bank_mask:0xf
	v_mov_b32_dpp v221, v86 row_ror:1 row_mask:0xf bank_mask:0xf
	v_mov_b32_dpp v220, v102 row_ror:15 row_mask:0xf bank_mask:0xf
	v_mov_b32_dpp v228, v83 row_ror:1 row_mask:0xf bank_mask:0xf
	v_mov_b32_dpp v224, v99 row_ror:15 row_mask:0xf bank_mask:0xf
	v_mov_b32_dpp v178, v87 row_ror:1 row_mask:0xf bank_mask:0xf
	v_mov_b32_dpp v177, v103 row_ror:15 row_mask:0xf bank_mask:0xf
	v_mov_b32_dpp v225, v88 row_shr:1 row_mask:0xf bank_mask:0xf
	v_mov_b32_dpp v223, v88 row_shl:1 row_mask:0xf bank_mask:0xf
	v_mov_b32_dpp v219, v92 row_shr:1 row_mask:0xf bank_mask:0xf
	v_mov_b32_dpp v179, v92 row_shl:1 row_mask:0xf bank_mask:0xf
	v_mov_b32_dpp v227, v89 row_shr:1 row_mask:0xf bank_mask:0xf
	v_mov_b32_dpp v222, v89 row_shl:1 row_mask:0xf bank_mask:0xf
	v_mov_b32_dpp v176, v93 row_shr:1 row_mask:0xf bank_mask:0xf
	v_mov_b32_dpp v3, v93 row_shl:1 row_mask:0xf bank_mask:0xf
	v_mov_b32_dpp v229, v90 row_shr:1 row_mask:0xf bank_mask:0xf
	v_mov_b32_dpp v226, v90 row_shl:1 row_mask:0xf bank_mask:0xf
	v_mov_b32_dpp v221, v94 row_shr:1 row_mask:0xf bank_mask:0xf
	v_mov_b32_dpp v220, v94 row_shl:1 row_mask:0xf bank_mask:0xf
	v_mov_b32_dpp v228, v91 row_shr:1 row_mask:0xf bank_mask:0xf
	v_mov_b32_dpp v224, v91 row_shl:1 row_mask:0xf bank_mask:0xf
	v_mov_b32_dpp v178, v95 row_shr:1 row_mask:0xf bank_mask:0xf
	v_mov_b32_dpp v177, v95 row_shl:1 row_mask:0xf bank_mask:0xf
	s_and_saveexec_b64 s[20:21], s[16:17]
	s_cbranch_execz .LBB0_311
	v_pk_mul_f32 v[230:231], v[90:91], v[162:163]
	v_pk_mul_f32 v[232:233], v[88:89], v[160:161]
	v_cmp_eq_u32_e64 s[18:19], 0, v218
	v_mov_b32_e32 v234, v232
	v_mov_b32_e32 v235, v230
	v_cndmask_b32_e64 v237, v229, 0, s[18:19]
	v_cmp_eq_u32_e64 s[16:17], s52, v218
	v_mov_b32_e32 v230, v233
	v_cndmask_b32_e64 v236, v225, 0, s[18:19]
	v_cndmask_b32_e64 v233, v228, 0, s[18:19]
	v_mov_b32_e32 v228, v152
	v_mov_b32_e32 v229, v154
	v_cndmask_b32_e64 v232, v227, 0, s[18:19]
	v_pk_fma_f32 v[228:229], v[228:229], v[236:237], v[234:235]
	v_cndmask_b32_e64 v227, v226, 0, s[16:17]
	v_cndmask_b32_e64 v226, v223, 0, s[16:17]
	v_mov_b32_e32 v234, v148
	v_mov_b32_e32 v235, v150
	v_pk_fma_f32 v[226:227], v[234:235], v[226:227], v[228:229]
	v_mov_b32_e32 v228, v144
	v_mov_b32_e32 v229, v146
	v_pk_add_f32 v[226:227], v[228:229], v[226:227]
	v_cndmask_b32_e64 v225, v224, 0, s[16:17]
	v_mul_f32_e32 v218, 0x3d372713, v227
	v_cndmask_b32_e64 v224, v222, 0, s[16:17]
	v_mul_f32_e32 v222, 0x3d372713, v226
	v_mul_f32_e32 v218, v227, v218
	v_mul_f32_e32 v222, v226, v222
	v_fma_f32 v218, v227, v218, v227
	v_fma_f32 v222, v226, v222, v226
	v_mul_f32_e32 v218, 0x3fcc422a, v218
	v_mul_f32_e32 v222, 0x3fcc422a, v222
	v_mul_f32_e32 v218, 0xbfb8aa3b, v218
	v_mul_f32_e32 v222, 0xbfb8aa3b, v222
	v_exp_f32_e32 v218, v218
	v_exp_f32_e32 v222, v222
	v_mov_b32_e32 v228, v153
	v_mov_b32_e32 v229, v155
	v_add_f32_e32 v218, 1.0, v218
	v_add_f32_e32 v222, 1.0, v222
	v_rcp_f32_e32 v223, v218
	v_rcp_f32_e32 v222, v222
	v_pk_fma_f32 v[228:229], v[228:229], v[232:233], v[230:231]
	v_mov_b32_e32 v230, v149
	v_mov_b32_e32 v231, v151
	v_pk_fma_f32 v[224:225], v[230:231], v[224:225], v[228:229]
	v_mov_b32_e32 v228, v145
	v_mov_b32_e32 v229, v147
	v_pk_add_f32 v[224:225], v[228:229], v[224:225]
	v_pk_mul_f32 v[222:223], v[226:227], v[222:223]
	v_mul_f32_e32 v218, 0x3d372713, v224
	v_cndmask_b32_e64 v227, v221, 0, s[18:19]
; __device__ __forceinline__ unsigned pack2(float lo, float hi) { return (unsigned)f2bf(lo) | ((unsigned)f2bf(hi) << 16); }
; __device__ __forceinline__ float sigmoidf_(float x) { return __builtin_amdgcn_rcpf(1.0f + __expf(-x)); }
;     __device__ __forceinline__ void operator()(const f32x4 (&acc)[2][2][4][2], const Unit& u, int wr, int wc, int fr, int fq) const {
;     ...
;                 for (int m = 0; m < 4; ++m) { const int r = 16 * m + fr, t = tb + r, pos = t & (L - 1);
;                     const bool hp = pos != 0, hn = pos != L - 1, valid = (r >= 1) & (r <= 62) & (t < TCH);
;                     float out[4];
; #pragma unroll
;                     for (int e = 0; e < 4; ++e) {
;                         const float xg = acc[ai][bj][m][0][e], xv = acc[ai][bj][m][1][e];
;                         float pg = dppf(m > 0 ? dppf(0.f, acc[ai][bj][m > 0 ? m - 1 : 0][0][e], 2) : 0.f, xg, 0);
;                         float ng = dppf(m < 3 ? dppf(0.f, acc[ai][bj][m < 3 ? m + 1 : 3][0][e], 3) : 0.f, xg, 1);
;                         float pv = dppf(m > 0 ? dppf(0.f, acc[ai][bj][m > 0 ? m - 1 : 0][1][e], 2) : 0.f, xv, 0);
;                         float nv = dppf(m < 3 ? dppf(0.f, acc[ai][bj][m < 3 ? m + 1 : 3][1][e], 3) : 0.f, xv, 1);
;                         if (!hp) { pg = 0.f; pv = 0.f; }
;                         if (!hn) { ng = 0.f; nv = 0.f; }
;                         const float hg = wg0[e] * pg + wg1[e] * xg + wg2[e] * ng + bgv[e], hv = wv0[e] * pv + wv1[e] * xv + wv2[e] * nv + bvv[e];
;                         out[e] = hg * sigmoidf_(1.5957691216f * (hg + 0.044715f * hg * hg * hg)) * hv; }
;                     if (valid) { uint2 o; o.x = pack2(out[0], out[1]); o.y = pack2(out[2], out[3]); *(uint2*)(ws + (unsigned)OFF_S + ((unsigned)t * (unsigned)DFF + (unsigned)J) * 2u) = o; }
	v_cndmask_b32_e64 v221, v220, 0, s[16:17]
	v_cndmask_b32_e64 v220, v179, 0, s[16:17]
	v_mul_f32_e32 v179, 0x3d372713, v225
	v_mul_f32_e32 v218, v224, v218
	v_mul_f32_e32 v179, v225, v179
	v_fma_f32 v218, v224, v218, v224
	v_fma_f32 v179, v225, v179, v225
	v_mul_f32_e32 v218, 0x3fcc422a, v218
	v_mul_f32_e32 v179, 0x3fcc422a, v179
	v_mul_f32_e32 v218, 0xbfb8aa3b, v218
	v_mul_f32_e32 v179, 0xbfb8aa3b, v179
	v_exp_f32_e32 v218, v218
	v_exp_f32_e32 v179, v179
	v_pk_mul_f32 v[238:239], v[94:95], v[158:159]
	v_pk_mul_f32 v[240:241], v[92:93], v[156:157]
	v_mov_b32_e32 v243, v238
	v_mov_b32_e32 v242, v240
	v_cndmask_b32_e64 v226, v219, 0, s[18:19]
	v_mov_b32_e32 v228, v140
	v_mov_b32_e32 v229, v142
	v_pk_fma_f32 v[226:227], v[228:229], v[226:227], v[242:243]
	v_mov_b32_e32 v228, v136
	v_mov_b32_e32 v229, v138
	v_add_f32_e32 v218, 1.0, v218
	v_pk_fma_f32 v[220:221], v[228:229], v[220:221], v[226:227]
	v_mov_b32_e32 v226, v132
	v_mov_b32_e32 v227, v134
	v_add_f32_e32 v179, 1.0, v179
	v_rcp_f32_e32 v218, v218
	v_pk_add_f32 v[220:221], v[226:227], v[220:221]
	v_rcp_f32_e32 v219, v179
	v_mov_b32_e32 v238, v241
	v_pk_mul_f32 v[220:221], v[220:221], v[222:223]
	v_cndmask_b32_e64 v179, v178, 0, s[18:19]
	v_cndmask_b32_e64 v178, v176, 0, s[18:19]
	v_mov_b32_e32 v222, v141
	v_mov_b32_e32 v223, v143
	v_pk_fma_f32 v[178:179], v[222:223], v[178:179], v[238:239]
	v_cndmask_b32_e64 v177, v177, 0, s[16:17]
	v_cndmask_b32_e64 v176, v3, 0, s[16:17]
	v_mov_b32_e32 v222, v137
	v_mov_b32_e32 v223, v139
	v_pk_fma_f32 v[176:177], v[222:223], v[176:177], v[178:179]
	v_mov_b32_e32 v178, v133
	v_mov_b32_e32 v179, v135
	v_pk_mul_f32 v[218:219], v[224:225], v[218:219]
	v_pk_add_f32 v[176:177], v[178:179], v[176:177]
	v_and_b32_sdwa v3, v221, v185 dst_sel:DWORD dst_unused:UNUSED_PAD src0_sel:WORD_1 src1_sel:DWORD
	v_pk_mul_f32 v[176:177], v[176:177], v[218:219]
	v_and_b32_sdwa v178, v220, v185 dst_sel:DWORD dst_unused:UNUSED_PAD src0_sel:WORD_1 src1_sel:DWORD
	v_and_b32_sdwa v179, v177, v185 dst_sel:DWORD dst_unused:UNUSED_PAD src0_sel:WORD_1 src1_sel:DWORD
	v_and_b32_sdwa v218, v176, v185 dst_sel:DWORD dst_unused:UNUSED_PAD src0_sel:WORD_1 src1_sel:DWORD
	v_add3_u32 v177, v177, v179, s46
	v_add3_u32 v176, v176, v218, s46
	v_add3_u32 v178, v220, v178, s46
	v_add3_u32 v3, v221, v3, s46
	v_and_b32_e32 v177, 0xffff0000, v177
	v_and_b32_e32 v176, 0xffff0000, v176
	v_readlane_b32 s16, v249, 20
	v_add_lshl_u32 v217, v217, v2, 1
	v_or_b32_sdwa v177, v177, v3 dst_sel:DWORD dst_unused:UNUSED_PAD src0_sel:DWORD src1_sel:WORD_1
	v_or_b32_sdwa v176, v176, v178 dst_sel:DWORD dst_unused:UNUSED_PAD src0_sel:DWORD src1_sel:WORD_1
	v_readlane_b32 s17, v249, 21
	s_nop 4
	global_store_dwordx2 v217, v[176:177], s[16:17]
.LBB0_311:
	s_or_b64 exec, exec, s[20:21]
	v_mov_b32_dpp v223, v88 row_ror:1 row_mask:0xf bank_mask:0xf
	v_mov_b32_dpp v221, v104 row_ror:15 row_mask:0xf bank_mask:0xf
	v_mov_b32_dpp v217, v92 row_ror:1 row_mask:0xf bank_mask:0xf
	v_mov_b32_dpp v179, v108 row_ror:15 row_mask:0xf bank_mask:0xf
	v_mov_b32_dpp v225, v89 row_ror:1 row_mask:0xf bank_mask:0xf
	v_mov_b32_dpp v220, v105 row_ror:15 row_mask:0xf bank_mask:0xf
	v_mov_b32_dpp v176, v93 row_ror:1 row_mask:0xf bank_mask:0xf
	v_mov_b32_dpp v3, v109 row_ror:15 row_mask:0xf bank_mask:0xf
	v_mov_b32_dpp v227, v90 row_ror:1 row_mask:0xf bank_mask:0xf
	v_mov_b32_dpp v224, v106 row_ror:15 row_mask:0xf bank_mask:0xf
	v_mov_b32_dpp v219, v94 row_ror:1 row_mask:0xf bank_mask:0xf
	v_mov_b32_dpp v218, v110 row_ror:15 row_mask:0xf bank_mask:0xf
	v_mov_b32_dpp v226, v91 row_ror:1 row_mask:0xf bank_mask:0xf
	v_mov_b32_dpp v222, v107 row_ror:15 row_mask:0xf bank_mask:0xf
	v_mov_b32_dpp v178, v95 row_ror:1 row_mask:0xf bank_mask:0xf
	v_mov_b32_dpp v177, v111 row_ror:15 row_mask:0xf bank_mask:0xf
	v_mov_b32_dpp v223, v96 row_shr:1 row_mask:0xf bank_mask:0xf
	v_mov_b32_dpp v221, v96 row_shl:1 row_mask:0xf bank_mask:0xf
	v_mov_b32_dpp v217, v100 row_shr:1 row_mask:0xf bank_mask:0xf
	v_mov_b32_dpp v179, v100 row_shl:1 row_mask:0xf bank_mask:0xf
	v_mov_b32_dpp v225, v97 row_shr:1 row_mask:0xf bank_mask:0xf
	v_mov_b32_dpp v220, v97 row_shl:1 row_mask:0xf bank_mask:0xf
	v_mov_b32_dpp v176, v101 row_shr:1 row_mask:0xf bank_mask:0xf
	v_mov_b32_dpp v3, v101 row_shl:1 row_mask:0xf bank_mask:0xf
	v_mov_b32_dpp v227, v98 row_shr:1 row_mask:0xf bank_mask:0xf
	v_mov_b32_dpp v224, v98 row_shl:1 row_mask:0xf bank_mask:0xf
	v_mov_b32_dpp v219, v102 row_shr:1 row_mask:0xf bank_mask:0xf
	v_mov_b32_dpp v218, v102 row_shl:1 row_mask:0xf bank_mask:0xf
	v_mov_b32_dpp v226, v99 row_shr:1 row_mask:0xf bank_mask:0xf
	v_mov_b32_dpp v222, v99 row_shl:1 row_mask:0xf bank_mask:0xf
	v_mov_b32_dpp v178, v103 row_shr:1 row_mask:0xf bank_mask:0xf
	v_mov_b32_dpp v177, v103 row_shl:1 row_mask:0xf bank_mask:0xf
	s_and_saveexec_b64 s[18:19], s[14:15]
	s_cbranch_execz .LBB0_313
; __device__ __forceinline__ unsigned pack2(float lo, float hi) { return (unsigned)f2bf(lo) | ((unsigned)f2bf(hi) << 16); }
; __device__ __forceinline__ float sigmoidf_(float x) { return __builtin_amdgcn_rcpf(1.0f + __expf(-x)); }
;     __device__ __forceinline__ void operator()(const f32x4 (&acc)[2][2][4][2], const Unit& u, int wr, int wc, int fr, int fq) const {
;     ...
;                 for (int m = 0; m < 4; ++m) { const int r = 16 * m + fr, t = tb + r, pos = t & (L - 1);
;                     const bool hp = pos != 0, hn = pos != L - 1, valid = (r >= 1) & (r <= 62) & (t < TCH);
;                     float out[4];
; #pragma unroll
;                     for (int e = 0; e < 4; ++e) {
;                         const float xg = acc[ai][bj][m][0][e], xv = acc[ai][bj][m][1][e];
;                         float pg = dppf(m > 0 ? dppf(0.f, acc[ai][bj][m > 0 ? m - 1 : 0][0][e], 2) : 0.f, xg, 0);
;                         float ng = dppf(m < 3 ? dppf(0.f, acc[ai][bj][m < 3 ? m + 1 : 3][0][e], 3) : 0.f, xg, 1);
;                         float pv = dppf(m > 0 ? dppf(0.f, acc[ai][bj][m > 0 ? m - 1 : 0][1][e], 2) : 0.f, xv, 0);
;                         float nv = dppf(m < 3 ? dppf(0.f, acc[ai][bj][m < 3 ? m + 1 : 3][1][e], 3) : 0.f, xv, 1);
;                         if (!hp) { pg = 0.f; pv = 0.f; }
;                         if (!hn) { ng = 0.f; nv = 0.f; }
;                         const float hg = wg0[e] * pg + wg1[e] * xg + wg2[e] * ng + bgv[e], hv = wv0[e] * pv + wv1[e] * xv + wv2[e] * nv + bvv[e];
;                         out[e] = hg * sigmoidf_(1.5957691216f * (hg + 0.044715f * hg * hg * hg)) * hv; }
;                     if (valid) { uint2 o; o.x = pack2(out[0], out[1]); o.y = pack2(out[2], out[3]); *(uint2*)(ws + (unsigned)OFF_S + ((unsigned)t * (unsigned)DFF + (unsigned)J) * 2u) = o; }
	v_pk_mul_f32 v[228:229], v[98:99], v[162:163]
	v_pk_mul_f32 v[230:231], v[96:97], v[160:161]
	v_cmp_eq_u32_e64 s[16:17], 0, v216
	v_mov_b32_e32 v232, v230
	v_mov_b32_e32 v233, v228
	v_cndmask_b32_e64 v235, v227, 0, s[16:17]
	v_cmp_eq_u32_e64 s[14:15], s52, v216
	v_mov_b32_e32 v228, v231
	v_cndmask_b32_e64 v234, v223, 0, s[16:17]
	v_cndmask_b32_e64 v231, v226, 0, s[16:17]
	v_mov_b32_e32 v226, v152
	v_mov_b32_e32 v227, v154
	v_cndmask_b32_e64 v230, v225, 0, s[16:17]
	v_pk_fma_f32 v[226:227], v[226:227], v[234:235], v[232:233]
	v_cndmask_b32_e64 v225, v224, 0, s[14:15]
	v_cndmask_b32_e64 v224, v221, 0, s[14:15]
	v_mov_b32_e32 v232, v148
	v_mov_b32_e32 v233, v150
	v_pk_fma_f32 v[224:225], v[232:233], v[224:225], v[226:227]
	v_mov_b32_e32 v226, v144
	v_mov_b32_e32 v227, v146
	v_pk_add_f32 v[224:225], v[226:227], v[224:225]
	v_cndmask_b32_e64 v223, v222, 0, s[14:15]
	v_mul_f32_e32 v216, 0x3d372713, v225
	v_cndmask_b32_e64 v222, v220, 0, s[14:15]
	v_mul_f32_e32 v220, 0x3d372713, v224
	v_mul_f32_e32 v216, v225, v216
	v_mul_f32_e32 v220, v224, v220
	v_fma_f32 v216, v225, v216, v225
	v_fma_f32 v220, v224, v220, v224
	v_mul_f32_e32 v216, 0x3fcc422a, v216
	v_mul_f32_e32 v220, 0x3fcc422a, v220
	v_mul_f32_e32 v216, 0xbfb8aa3b, v216
	v_mul_f32_e32 v220, 0xbfb8aa3b, v220
	v_exp_f32_e32 v216, v216
	v_exp_f32_e32 v220, v220
	v_mov_b32_e32 v226, v153
	v_mov_b32_e32 v227, v155
	v_add_f32_e32 v216, 1.0, v216
	v_add_f32_e32 v220, 1.0, v220
	v_rcp_f32_e32 v221, v216
	v_rcp_f32_e32 v220, v220
	v_pk_fma_f32 v[226:227], v[226:227], v[230:231], v[228:229]
	v_mov_b32_e32 v228, v149
	v_mov_b32_e32 v229, v151
	v_pk_fma_f32 v[222:223], v[228:229], v[222:223], v[226:227]
	v_mov_b32_e32 v226, v145
	v_mov_b32_e32 v227, v147
	v_pk_add_f32 v[222:223], v[226:227], v[222:223]
	v_pk_mul_f32 v[220:221], v[224:225], v[220:221]
	v_mul_f32_e32 v216, 0x3d372713, v222
	v_cndmask_b32_e64 v225, v219, 0, s[16:17]
	v_cndmask_b32_e64 v219, v218, 0, s[14:15]
	v_cndmask_b32_e64 v218, v179, 0, s[14:15]
	v_mul_f32_e32 v179, 0x3d372713, v223
	v_mul_f32_e32 v216, v222, v216
	v_mul_f32_e32 v179, v223, v179
	v_fma_f32 v216, v222, v216, v222
	v_fma_f32 v179, v223, v179, v223
	v_mul_f32_e32 v216, 0x3fcc422a, v216
	v_mul_f32_e32 v179, 0x3fcc422a, v179
	v_mul_f32_e32 v216, 0xbfb8aa3b, v216
	v_mul_f32_e32 v179, 0xbfb8aa3b, v179
	v_exp_f32_e32 v216, v216
	v_exp_f32_e32 v179, v179
	v_pk_mul_f32 v[236:237], v[102:103], v[158:159]
	v_pk_mul_f32 v[238:239], v[100:101], v[156:157]
	v_mov_b32_e32 v241, v236
	v_mov_b32_e32 v240, v238
	v_cndmask_b32_e64 v224, v217, 0, s[16:17]
	v_mov_b32_e32 v226, v140
	v_mov_b32_e32 v227, v142
	v_pk_fma_f32 v[224:225], v[226:227], v[224:225], v[240:241]
	v_mov_b32_e32 v226, v136
	v_mov_b32_e32 v227, v138
	v_add_f32_e32 v216, 1.0, v216
	v_pk_fma_f32 v[218:219], v[226:227], v[218:219], v[224:225]
	v_mov_b32_e32 v224, v132
	v_mov_b32_e32 v225, v134
	v_add_f32_e32 v179, 1.0, v179
	v_rcp_f32_e32 v216, v216
	v_pk_add_f32 v[218:219], v[224:225], v[218:219]
	v_rcp_f32_e32 v217, v179
	v_mov_b32_e32 v236, v239
	v_pk_mul_f32 v[218:219], v[218:219], v[220:221]
	v_cndmask_b32_e64 v179, v178, 0, s[16:17]
	v_cndmask_b32_e64 v178, v176, 0, s[16:17]
	v_mov_b32_e32 v220, v141
	v_mov_b32_e32 v221, v143
	v_pk_fma_f32 v[178:179], v[220:221], v[178:179], v[236:237]
	v_cndmask_b32_e64 v177, v177, 0, s[14:15]
	v_cndmask_b32_e64 v176, v3, 0, s[14:15]
	v_mov_b32_e32 v220, v137
	v_mov_b32_e32 v221, v139
	v_pk_fma_f32 v[176:177], v[220:221], v[176:177], v[178:179]
	v_mov_b32_e32 v178, v133
	v_mov_b32_e32 v179, v135
	v_pk_mul_f32 v[216:217], v[222:223], v[216:217]
	v_pk_add_f32 v[176:177], v[178:179], v[176:177]
	v_and_b32_sdwa v3, v219, v185 dst_sel:DWORD dst_unused:UNUSED_PAD src0_sel:WORD_1 src1_sel:DWORD
	v_pk_mul_f32 v[176:177], v[176:177], v[216:217]
	v_and_b32_sdwa v178, v218, v185 dst_sel:DWORD dst_unused:UNUSED_PAD src0_sel:WORD_1 src1_sel:DWORD
	v_and_b32_sdwa v179, v177, v185 dst_sel:DWORD dst_unused:UNUSED_PAD src0_sel:WORD_1 src1_sel:DWORD
	v_and_b32_sdwa v216, v176, v185 dst_sel:DWORD dst_unused:UNUSED_PAD src0_sel:WORD_1 src1_sel:DWORD
	v_add3_u32 v177, v177, v179, s46
	v_add3_u32 v176, v176, v216, s46
	v_add3_u32 v178, v218, v178, s46
	v_add3_u32 v3, v219, v3, s46
	v_and_b32_e32 v177, 0xffff0000, v177
	v_and_b32_e32 v176, 0xffff0000, v176
	v_readlane_b32 s14, v249, 20
	v_add_lshl_u32 v215, v215, v2, 1
	v_or_b32_sdwa v177, v177, v3 dst_sel:DWORD dst_unused:UNUSED_PAD src0_sel:DWORD src1_sel:WORD_1
	v_or_b32_sdwa v176, v176, v178 dst_sel:DWORD dst_unused:UNUSED_PAD src0_sel:DWORD src1_sel:WORD_1
	v_readlane_b32 s15, v249, 21
	s_nop 4
	global_store_dwordx2 v215, v[176:177], s[14:15]
; __device__ __forceinline__ unsigned pack2(float lo, float hi) { return (unsigned)f2bf(lo) | ((unsigned)f2bf(hi) << 16); }
; __device__ __forceinline__ float sigmoidf_(float x) { return __builtin_amdgcn_rcpf(1.0f + __expf(-x)); }
;     __device__ __forceinline__ void operator()(const f32x4 (&acc)[2][2][4][2], const Unit& u, int wr, int wc, int fr, int fq) const {
;     ...
;             for (int ai = 0; ai < 2; ++ai) { const int tb = u.pm * 248 + 62 * (ai * 2 + wr) - 1;
; #pragma unroll
;                 for (int m = 0; m < 4; ++m) { const int r = 16 * m + fr, t = tb + r, pos = t & (L - 1);
;                     const bool hp = pos != 0, hn = pos != L - 1, valid = (r >= 1) & (r <= 62) & (t < TCH);
;                     float out[4];
; #pragma unroll
;                     for (int e = 0; e < 4; ++e) {
;                         const float xg = acc[ai][bj][m][0][e], xv = acc[ai][bj][m][1][e];
;                         float pg = dppf(m > 0 ? dppf(0.f, acc[ai][bj][m > 0 ? m - 1 : 0][0][e], 2) : 0.f, xg, 0);
;                         float ng = dppf(m < 3 ? dppf(0.f, acc[ai][bj][m < 3 ? m + 1 : 3][0][e], 3) : 0.f, xg, 1);
;                         float pv = dppf(m > 0 ? dppf(0.f, acc[ai][bj][m > 0 ? m - 1 : 0][1][e], 2) : 0.f, xv, 0);
;                         float nv = dppf(m < 3 ? dppf(0.f, acc[ai][bj][m < 3 ? m + 1 : 3][1][e], 3) : 0.f, xv, 1);
;                         if (!hp) { pg = 0.f; pv = 0.f; }
;                         if (!hn) { ng = 0.f; nv = 0.f; }
;                         const float hg = wg0[e] * pg + wg1[e] * xg + wg2[e] * ng + bgv[e], hv = wv0[e] * pv + wv1[e] * xv + wv2[e] * nv + bvv[e];
;                         out[e] = hg * sigmoidf_(1.5957691216f * (hg + 0.044715f * hg * hg * hg)) * hv; }
;                     if (valid) { uint2 o; o.x = pack2(out[0], out[1]); o.y = pack2(out[2], out[3]); *(uint2*)(ws + (unsigned)OFF_S + ((unsigned)t * (unsigned)DFF + (unsigned)J) * 2u) = o; }
;                     __builtin_amdgcn_sched_barrier(0); } } }
.LBB0_313:
	s_or_b64 exec, exec, s[18:19]
	v_mov_b32_dpp v221, v96 row_ror:1 row_mask:0xf bank_mask:0xf
	v_mov_b32_e32 v220, 0
	v_mov_b32_dpp v215, v100 row_ror:1 row_mask:0xf bank_mask:0xf
	v_mov_b32_e32 v179, 0
	v_mov_b32_dpp v223, v97 row_ror:1 row_mask:0xf bank_mask:0xf
	v_mov_b32_e32 v218, 0
	v_mov_b32_dpp v176, v101 row_ror:1 row_mask:0xf bank_mask:0xf
	v_mov_b32_e32 v3, 0
	v_mov_b32_dpp v225, v98 row_ror:1 row_mask:0xf bank_mask:0xf
	v_mov_b32_e32 v222, 0
	v_mov_b32_dpp v217, v102 row_ror:1 row_mask:0xf bank_mask:0xf
	v_mov_b32_e32 v216, 0
	v_mov_b32_dpp v224, v99 row_ror:1 row_mask:0xf bank_mask:0xf
	v_mov_b32_e32 v219, 0
	v_mov_b32_dpp v178, v103 row_ror:1 row_mask:0xf bank_mask:0xf
	v_mov_b32_e32 v177, 0
	v_mov_b32_dpp v221, v104 row_shr:1 row_mask:0xf bank_mask:0xf
	v_mov_b32_dpp v220, v104 row_shl:1 row_mask:0xf bank_mask:0xf
	v_mov_b32_dpp v215, v108 row_shr:1 row_mask:0xf bank_mask:0xf
	v_mov_b32_dpp v179, v108 row_shl:1 row_mask:0xf bank_mask:0xf
	v_mov_b32_dpp v223, v105 row_shr:1 row_mask:0xf bank_mask:0xf
	v_mov_b32_dpp v218, v105 row_shl:1 row_mask:0xf bank_mask:0xf
	v_mov_b32_dpp v176, v109 row_shr:1 row_mask:0xf bank_mask:0xf
	v_mov_b32_dpp v3, v109 row_shl:1 row_mask:0xf bank_mask:0xf
	v_mov_b32_dpp v225, v106 row_shr:1 row_mask:0xf bank_mask:0xf
	v_mov_b32_dpp v222, v106 row_shl:1 row_mask:0xf bank_mask:0xf
	v_mov_b32_dpp v217, v110 row_shr:1 row_mask:0xf bank_mask:0xf
	v_mov_b32_dpp v216, v110 row_shl:1 row_mask:0xf bank_mask:0xf
	v_mov_b32_dpp v224, v107 row_shr:1 row_mask:0xf bank_mask:0xf
	v_mov_b32_dpp v219, v107 row_shl:1 row_mask:0xf bank_mask:0xf
	v_mov_b32_dpp v178, v111 row_shr:1 row_mask:0xf bank_mask:0xf
	v_mov_b32_dpp v177, v111 row_shl:1 row_mask:0xf bank_mask:0xf
	s_and_saveexec_b64 s[18:19], s[68:69]
	s_cbranch_execz .LBB0_315
	v_pk_mul_f32 v[226:227], v[106:107], v[162:163]
	v_pk_mul_f32 v[228:229], v[104:105], v[160:161]
	v_cmp_eq_u32_e64 s[16:17], 0, v214
	v_mov_b32_e32 v230, v228
	v_mov_b32_e32 v231, v226
	v_cndmask_b32_e64 v233, v225, 0, s[16:17]
	v_cmp_eq_u32_e64 s[14:15], s52, v214
	v_mov_b32_e32 v226, v229
	v_cndmask_b32_e64 v232, v221, 0, s[16:17]
	v_cndmask_b32_e64 v229, v224, 0, s[16:17]
	v_mov_b32_e32 v224, v152
	v_mov_b32_e32 v225, v154
	v_cndmask_b32_e64 v228, v223, 0, s[16:17]
	v_pk_fma_f32 v[224:225], v[224:225], v[232:233], v[230:231]
	v_cndmask_b32_e64 v221, v222, 0, s[14:15]
	v_cndmask_b32_e64 v220, v220, 0, s[14:15]
	v_mov_b32_e32 v222, v148
	v_mov_b32_e32 v223, v150
	v_pk_fma_f32 v[220:221], v[222:223], v[220:221], v[224:225]
	v_mov_b32_e32 v222, v144
	v_mov_b32_e32 v223, v146
	v_pk_add_f32 v[220:221], v[222:223], v[220:221]
	v_mov_b32_e32 v224, v153
	v_mul_f32_e32 v214, 0x3d372713, v221
	v_mul_f32_e32 v222, 0x3d372713, v220
	v_mul_f32_e32 v214, v221, v214
	v_mul_f32_e32 v222, v220, v222
	v_fma_f32 v214, v221, v214, v221
	v_fma_f32 v222, v220, v222, v220
	v_mul_f32_e32 v214, 0x3fcc422a, v214
	v_mul_f32_e32 v222, 0x3fcc422a, v222
	v_mul_f32_e32 v214, 0xbfb8aa3b, v214
	v_mul_f32_e32 v222, 0xbfb8aa3b, v222
	v_exp_f32_e32 v214, v214
	v_exp_f32_e32 v222, v222
	v_mov_b32_e32 v225, v155
	v_pk_fma_f32 v[224:225], v[224:225], v[228:229], v[226:227]
	v_add_f32_e32 v214, 1.0, v214
	v_add_f32_e32 v222, 1.0, v222
	v_rcp_f32_e32 v223, v214
	v_rcp_f32_e32 v222, v222
	v_cndmask_b32_e64 v219, v219, 0, s[14:15]
	v_cndmask_b32_e64 v218, v218, 0, s[14:15]
	v_mov_b32_e32 v226, v149
	v_mov_b32_e32 v227, v151
	v_pk_fma_f32 v[218:219], v[226:227], v[218:219], v[224:225]
	v_mov_b32_e32 v224, v145
	v_mov_b32_e32 v225, v147
	v_pk_add_f32 v[218:219], v[224:225], v[218:219]
	v_pk_mul_f32 v[220:221], v[220:221], v[222:223]
	v_mul_f32_e32 v214, 0x3d372713, v218
	v_cndmask_b32_e64 v223, v217, 0, s[16:17]
	v_cndmask_b32_e64 v217, v216, 0, s[14:15]
	v_cndmask_b32_e64 v216, v179, 0, s[14:15]
	v_mul_f32_e32 v179, 0x3d372713, v219
	v_mul_f32_e32 v214, v218, v214
	v_mul_f32_e32 v179, v219, v179
	v_fma_f32 v214, v218, v214, v218
	v_fma_f32 v179, v219, v179, v219
	v_mul_f32_e32 v214, 0x3fcc422a, v214
	v_mul_f32_e32 v179, 0x3fcc422a, v179
	v_mul_f32_e32 v214, 0xbfb8aa3b, v214
	v_mul_f32_e32 v179, 0xbfb8aa3b, v179
	v_exp_f32_e32 v214, v214
	v_exp_f32_e32 v179, v179
	v_cndmask_b32_e64 v222, v215, 0, s[16:17]
	v_pk_mul_f32 v[234:235], v[110:111], v[158:159]
	v_add_f32_e32 v214, 1.0, v214
	v_add_f32_e32 v179, 1.0, v179
	v_rcp_f32_e32 v214, v214
	v_rcp_f32_e32 v215, v179
	v_pk_mul_f32 v[236:237], v[108:109], v[156:157]
	v_mov_b32_e32 v239, v234
	v_mov_b32_e32 v234, v237
	v_pk_mul_f32 v[214:215], v[218:219], v[214:215]
	v_cndmask_b32_e64 v179, v178, 0, s[16:17]
	v_cndmask_b32_e64 v178, v176, 0, s[16:17]
	v_mov_b32_e32 v218, v141
	v_mov_b32_e32 v219, v143
	v_mov_b32_e32 v238, v236
	v_mov_b32_e32 v224, v140
	v_mov_b32_e32 v225, v142
	v_pk_fma_f32 v[178:179], v[218:219], v[178:179], v[234:235]
	v_cndmask_b32_e64 v177, v177, 0, s[14:15]
	v_cndmask_b32_e64 v176, v3, 0, s[14:15]
	v_mov_b32_e32 v218, v137
	v_mov_b32_e32 v219, v139
	v_pk_fma_f32 v[222:223], v[224:225], v[222:223], v[238:239]
	v_mov_b32_e32 v224, v136
	v_mov_b32_e32 v225, v138
	v_pk_fma_f32 v[176:177], v[218:219], v[176:177], v[178:179]
	v_mov_b32_e32 v178, v133
	v_mov_b32_e32 v179, v135
	v_pk_fma_f32 v[216:217], v[224:225], v[216:217], v[222:223]
	v_mov_b32_e32 v222, v132
	v_mov_b32_e32 v223, v134
	v_pk_add_f32 v[176:177], v[178:179], v[176:177]
	v_pk_add_f32 v[216:217], v[222:223], v[216:217]
	v_pk_mul_f32 v[176:177], v[176:177], v[214:215]
	v_pk_mul_f32 v[216:217], v[216:217], v[220:221]
	v_and_b32_sdwa v179, v177, v185 dst_sel:DWORD dst_unused:UNUSED_PAD src0_sel:WORD_1 src1_sel:DWORD
	v_and_b32_sdwa v214, v176, v185 dst_sel:DWORD dst_unused:UNUSED_PAD src0_sel:WORD_1 src1_sel:DWORD
	v_and_b32_sdwa v3, v217, v185 dst_sel:DWORD dst_unused:UNUSED_PAD src0_sel:WORD_1 src1_sel:DWORD
	v_and_b32_sdwa v178, v216, v185 dst_sel:DWORD dst_unused:UNUSED_PAD src0_sel:WORD_1 src1_sel:DWORD
	v_add3_u32 v177, v177, v179, s46
	v_add3_u32 v176, v176, v214, s46
	v_add3_u32 v178, v216, v178, s46
	v_add3_u32 v3, v217, v3, s46
	v_and_b32_e32 v177, 0xffff0000, v177
	v_and_b32_e32 v176, 0xffff0000, v176
	v_readlane_b32 s14, v249, 20
	v_add_lshl_u32 v213, v213, v2, 1
	v_or_b32_sdwa v177, v177, v3 dst_sel:DWORD dst_unused:UNUSED_PAD src0_sel:DWORD src1_sel:WORD_1
	v_or_b32_sdwa v176, v176, v178 dst_sel:DWORD dst_unused:UNUSED_PAD src0_sel:DWORD src1_sel:WORD_1
	v_readlane_b32 s15, v249, 21
	s_nop 4
	global_store_dwordx2 v213, v[176:177], s[14:15]
; __device__ __forceinline__ unsigned pack2(float lo, float hi) { return (unsigned)f2bf(lo) | ((unsigned)f2bf(hi) << 16); }
; __device__ __forceinline__ float sigmoidf_(float x) { return __builtin_amdgcn_rcpf(1.0f + __expf(-x)); }
;     __device__ __forceinline__ void operator()(const f32x4 (&acc)[2][2][4][2], const Unit& u, int wr, int wc, int fr, int fq) const {
;     ...
;             for (int ai = 0; ai < 2; ++ai) { const int tb = u.pm * 248 + 62 * (ai * 2 + wr) - 1;
; #pragma unroll
;                 for (int m = 0; m < 4; ++m) { const int r = 16 * m + fr, t = tb + r, pos = t & (L - 1);
;                     const bool hp = pos != 0, hn = pos != L - 1, valid = (r >= 1) & (r <= 62) & (t < TCH);
;                     float out[4];
; #pragma unroll
;                     for (int e = 0; e < 4; ++e) {
;                         const float xg = acc[ai][bj][m][0][e], xv = acc[ai][bj][m][1][e];
;                         float pg = dppf(m > 0 ? dppf(0.f, acc[ai][bj][m > 0 ? m - 1 : 0][0][e], 2) : 0.f, xg, 0);
;                         float ng = dppf(m < 3 ? dppf(0.f, acc[ai][bj][m < 3 ? m + 1 : 3][0][e], 3) : 0.f, xg, 1);
;                         float pv = dppf(m > 0 ? dppf(0.f, acc[ai][bj][m > 0 ? m - 1 : 0][1][e], 2) : 0.f, xv, 0);
;                         float nv = dppf(m < 3 ? dppf(0.f, acc[ai][bj][m < 3 ? m + 1 : 3][1][e], 3) : 0.f, xv, 1);
;                         if (!hp) { pg = 0.f; pv = 0.f; }
;                         if (!hn) { ng = 0.f; nv = 0.f; }
;                         const float hg = wg0[e] * pg + wg1[e] * xg + wg2[e] * ng + bgv[e], hv = wv0[e] * pv + wv1[e] * xv + wv2[e] * nv + bvv[e];
;                         out[e] = hg * sigmoidf_(1.5957691216f * (hg + 0.044715f * hg * hg * hg)) * hv; }
;                     if (valid) { uint2 o; o.x = pack2(out[0], out[1]); o.y = pack2(out[2], out[3]); *(uint2*)(ws + (unsigned)OFF_S + ((unsigned)t * (unsigned)DFF + (unsigned)J) * 2u) = o; }
;                     __builtin_amdgcn_sched_barrier(0); } } }
.LBB0_315:
	s_or_b64 exec, exec, s[18:19]
	v_mov_b32_e32 v219, 0
	v_mov_b32_dpp v218, v12 row_ror:15 row_mask:0xf bank_mask:0xf
	v_mov_b32_e32 v213, 0
	v_mov_b32_dpp v179, v16 row_ror:15 row_mask:0xf bank_mask:0xf
	v_mov_b32_e32 v221, 0
	v_mov_b32_dpp v216, v13 row_ror:15 row_mask:0xf bank_mask:0xf
	v_mov_b32_e32 v176, 0
	v_mov_b32_dpp v3, v17 row_ror:15 row_mask:0xf bank_mask:0xf
	v_mov_b32_e32 v223, 0
	v_mov_b32_dpp v220, v14 row_ror:15 row_mask:0xf bank_mask:0xf
	v_mov_b32_e32 v215, 0
	v_mov_b32_dpp v214, v18 row_ror:15 row_mask:0xf bank_mask:0xf
	v_mov_b32_e32 v222, 0
	v_mov_b32_dpp v217, v15 row_ror:15 row_mask:0xf bank_mask:0xf
	v_mov_b32_e32 v178, 0
	v_mov_b32_dpp v177, v19 row_ror:15 row_mask:0xf bank_mask:0xf
	v_mov_b32_dpp v219, v4 row_shr:1 row_mask:0xf bank_mask:0xf
	v_mov_b32_dpp v218, v4 row_shl:1 row_mask:0xf bank_mask:0xf
	v_mov_b32_dpp v213, v8 row_shr:1 row_mask:0xf bank_mask:0xf
	v_mov_b32_dpp v179, v8 row_shl:1 row_mask:0xf bank_mask:0xf
	v_mov_b32_dpp v221, v5 row_shr:1 row_mask:0xf bank_mask:0xf
	v_mov_b32_dpp v216, v5 row_shl:1 row_mask:0xf bank_mask:0xf
	v_mov_b32_dpp v176, v9 row_shr:1 row_mask:0xf bank_mask:0xf
	v_mov_b32_dpp v3, v9 row_shl:1 row_mask:0xf bank_mask:0xf
	v_mov_b32_dpp v223, v6 row_shr:1 row_mask:0xf bank_mask:0xf
	v_mov_b32_dpp v220, v6 row_shl:1 row_mask:0xf bank_mask:0xf
	v_mov_b32_dpp v215, v10 row_shr:1 row_mask:0xf bank_mask:0xf
	v_mov_b32_dpp v214, v10 row_shl:1 row_mask:0xf bank_mask:0xf
	v_mov_b32_dpp v222, v7 row_shr:1 row_mask:0xf bank_mask:0xf
	v_mov_b32_dpp v217, v7 row_shl:1 row_mask:0xf bank_mask:0xf
	v_mov_b32_dpp v178, v11 row_shr:1 row_mask:0xf bank_mask:0xf
	v_mov_b32_dpp v177, v11 row_shl:1 row_mask:0xf bank_mask:0xf
	s_and_saveexec_b64 s[18:19], s[66:67]
	s_cbranch_execz .LBB0_317
	v_pk_mul_f32 v[224:225], v[6:7], v[162:163]
	v_pk_mul_f32 v[226:227], v[4:5], v[160:161]
	v_cmp_eq_u32_e64 s[16:17], 0, v212
	v_mov_b32_e32 v228, v226
	v_mov_b32_e32 v229, v224
	v_cndmask_b32_e64 v231, v223, 0, s[16:17]
	v_cmp_eq_u32_e64 s[14:15], s52, v212
	v_mov_b32_e32 v224, v227
	v_cndmask_b32_e64 v230, v219, 0, s[16:17]
	v_cndmask_b32_e64 v227, v222, 0, s[16:17]
	v_mov_b32_e32 v222, v152
	v_mov_b32_e32 v223, v154
	v_cndmask_b32_e64 v226, v221, 0, s[16:17]
	v_pk_fma_f32 v[222:223], v[222:223], v[230:231], v[228:229]
	v_cndmask_b32_e64 v219, v220, 0, s[14:15]
	v_cndmask_b32_e64 v218, v218, 0, s[14:15]
	v_mov_b32_e32 v220, v148
	v_mov_b32_e32 v221, v150
	v_pk_fma_f32 v[218:219], v[220:221], v[218:219], v[222:223]
	v_mov_b32_e32 v220, v144
	v_mov_b32_e32 v221, v146
	v_pk_add_f32 v[218:219], v[220:221], v[218:219]
	v_mov_b32_e32 v222, v153
	v_mul_f32_e32 v212, 0x3d372713, v219
	v_mul_f32_e32 v220, 0x3d372713, v218
	v_mul_f32_e32 v212, v219, v212
	v_mul_f32_e32 v220, v218, v220
	v_fma_f32 v212, v219, v212, v219
	v_fma_f32 v220, v218, v220, v218
	v_mul_f32_e32 v212, 0x3fcc422a, v212
	v_mul_f32_e32 v220, 0x3fcc422a, v220
	v_mul_f32_e32 v212, 0xbfb8aa3b, v212
	v_mul_f32_e32 v220, 0xbfb8aa3b, v220
	v_exp_f32_e32 v212, v212
	v_exp_f32_e32 v220, v220
	v_mov_b32_e32 v223, v155
	v_pk_fma_f32 v[222:223], v[222:223], v[226:227], v[224:225]
	v_add_f32_e32 v212, 1.0, v212
	v_add_f32_e32 v220, 1.0, v220
	v_rcp_f32_e32 v221, v212
	v_rcp_f32_e32 v220, v220
	v_cndmask_b32_e64 v217, v217, 0, s[14:15]
	v_cndmask_b32_e64 v216, v216, 0, s[14:15]
	v_mov_b32_e32 v224, v149
	v_mov_b32_e32 v225, v151
	v_pk_fma_f32 v[216:217], v[224:225], v[216:217], v[222:223]
	v_mov_b32_e32 v222, v145
	v_mov_b32_e32 v223, v147
	v_pk_add_f32 v[216:217], v[222:223], v[216:217]
	v_pk_mul_f32 v[218:219], v[218:219], v[220:221]
	v_mul_f32_e32 v212, 0x3d372713, v216
	v_cndmask_b32_e64 v221, v215, 0, s[16:17]
	v_cndmask_b32_e64 v215, v214, 0, s[14:15]
	v_cndmask_b32_e64 v214, v179, 0, s[14:15]
	v_mul_f32_e32 v179, 0x3d372713, v217
	v_mul_f32_e32 v212, v216, v212
	v_mul_f32_e32 v179, v217, v179
	v_fma_f32 v212, v216, v212, v216
	v_fma_f32 v179, v217, v179, v217
	v_mul_f32_e32 v212, 0x3fcc422a, v212
	v_mul_f32_e32 v179, 0x3fcc422a, v179
	v_mul_f32_e32 v212, 0xbfb8aa3b, v212
	v_mul_f32_e32 v179, 0xbfb8aa3b, v179
	v_exp_f32_e32 v212, v212
	v_exp_f32_e32 v179, v179
	v_cndmask_b32_e64 v220, v213, 0, s[16:17]
	v_pk_mul_f32 v[232:233], v[10:11], v[158:159]
	v_add_f32_e32 v212, 1.0, v212
	v_add_f32_e32 v179, 1.0, v179
	v_rcp_f32_e32 v212, v212
	v_rcp_f32_e32 v213, v179
	v_pk_mul_f32 v[234:235], v[8:9], v[156:157]
	v_mov_b32_e32 v237, v232
	v_mov_b32_e32 v232, v235
	v_pk_mul_f32 v[212:213], v[216:217], v[212:213]
	v_cndmask_b32_e64 v179, v178, 0, s[16:17]
	v_cndmask_b32_e64 v178, v176, 0, s[16:17]
	v_mov_b32_e32 v216, v141
	v_mov_b32_e32 v217, v143
	v_mov_b32_e32 v236, v234
	v_mov_b32_e32 v222, v140
	v_mov_b32_e32 v223, v142
	v_pk_fma_f32 v[178:179], v[216:217], v[178:179], v[232:233]
	v_cndmask_b32_e64 v177, v177, 0, s[14:15]
	v_cndmask_b32_e64 v176, v3, 0, s[14:15]
	v_mov_b32_e32 v216, v137
	v_mov_b32_e32 v217, v139
	v_pk_fma_f32 v[220:221], v[222:223], v[220:221], v[236:237]
	v_mov_b32_e32 v222, v136
	v_mov_b32_e32 v223, v138
	v_pk_fma_f32 v[176:177], v[216:217], v[176:177], v[178:179]
	v_mov_b32_e32 v178, v133
	v_mov_b32_e32 v179, v135
	v_pk_fma_f32 v[214:215], v[222:223], v[214:215], v[220:221]
	v_mov_b32_e32 v220, v132
	v_mov_b32_e32 v221, v134
	v_pk_add_f32 v[176:177], v[178:179], v[176:177]
	v_pk_add_f32 v[214:215], v[220:221], v[214:215]
	v_pk_mul_f32 v[176:177], v[176:177], v[212:213]
	v_pk_mul_f32 v[214:215], v[214:215], v[218:219]
	v_and_b32_sdwa v179, v177, v185 dst_sel:DWORD dst_unused:UNUSED_PAD src0_sel:WORD_1 src1_sel:DWORD
	v_and_b32_sdwa v212, v176, v185 dst_sel:DWORD dst_unused:UNUSED_PAD src0_sel:WORD_1 src1_sel:DWORD
	v_and_b32_sdwa v3, v215, v185 dst_sel:DWORD dst_unused:UNUSED_PAD src0_sel:WORD_1 src1_sel:DWORD
	v_and_b32_sdwa v178, v214, v185 dst_sel:DWORD dst_unused:UNUSED_PAD src0_sel:WORD_1 src1_sel:DWORD
	v_add3_u32 v177, v177, v179, s46
	v_add3_u32 v176, v176, v212, s46
	v_add3_u32 v178, v214, v178, s46
	v_add3_u32 v3, v215, v3, s46
	v_and_b32_e32 v177, 0xffff0000, v177
	v_and_b32_e32 v176, 0xffff0000, v176
	v_readlane_b32 s14, v249, 20
	v_add_lshl_u32 v211, v211, v2, 1
	v_or_b32_sdwa v177, v177, v3 dst_sel:DWORD dst_unused:UNUSED_PAD src0_sel:DWORD src1_sel:WORD_1
	v_or_b32_sdwa v176, v176, v178 dst_sel:DWORD dst_unused:UNUSED_PAD src0_sel:DWORD src1_sel:WORD_1
	v_readlane_b32 s15, v249, 21
	s_nop 4
	global_store_dwordx2 v211, v[176:177], s[14:15]
; __device__ __forceinline__ unsigned pack2(float lo, float hi) { return (unsigned)f2bf(lo) | ((unsigned)f2bf(hi) << 16); }
; __device__ __forceinline__ float sigmoidf_(float x) { return __builtin_amdgcn_rcpf(1.0f + __expf(-x)); }
;     __device__ __forceinline__ void operator()(const f32x4 (&acc)[2][2][4][2], const Unit& u, int wr, int wc, int fr, int fq) const {
;     ...
;             for (int ai = 0; ai < 2; ++ai) { const int tb = u.pm * 248 + 62 * (ai * 2 + wr) - 1;
; #pragma unroll
;                 for (int m = 0; m < 4; ++m) { const int r = 16 * m + fr, t = tb + r, pos = t & (L - 1);
;                     const bool hp = pos != 0, hn = pos != L - 1, valid = (r >= 1) & (r <= 62) & (t < TCH);
;                     float out[4];
; #pragma unroll
;                     for (int e = 0; e < 4; ++e) {
;                         const float xg = acc[ai][bj][m][0][e], xv = acc[ai][bj][m][1][e];
;                         float pg = dppf(m > 0 ? dppf(0.f, acc[ai][bj][m > 0 ? m - 1 : 0][0][e], 2) : 0.f, xg, 0);
;                         float ng = dppf(m < 3 ? dppf(0.f, acc[ai][bj][m < 3 ? m + 1 : 3][0][e], 3) : 0.f, xg, 1);
;                         float pv = dppf(m > 0 ? dppf(0.f, acc[ai][bj][m > 0 ? m - 1 : 0][1][e], 2) : 0.f, xv, 0);
;                         float nv = dppf(m < 3 ? dppf(0.f, acc[ai][bj][m < 3 ? m + 1 : 3][1][e], 3) : 0.f, xv, 1);
;                         if (!hp) { pg = 0.f; pv = 0.f; }
;                         if (!hn) { ng = 0.f; nv = 0.f; }
;                         const float hg = wg0[e] * pg + wg1[e] * xg + wg2[e] * ng + bgv[e], hv = wv0[e] * pv + wv1[e] * xv + wv2[e] * nv + bvv[e];
;                         out[e] = hg * sigmoidf_(1.5957691216f * (hg + 0.044715f * hg * hg * hg)) * hv; }
;                     if (valid) { uint2 o; o.x = pack2(out[0], out[1]); o.y = pack2(out[2], out[3]); *(uint2*)(ws + (unsigned)OFF_S + ((unsigned)t * (unsigned)DFF + (unsigned)J) * 2u) = o; }
;                     __builtin_amdgcn_sched_barrier(0); } } }
.LBB0_317:
	s_or_b64 exec, exec, s[18:19]
	v_mov_b32_dpp v217, v4 row_ror:1 row_mask:0xf bank_mask:0xf
	v_mov_b32_dpp v215, v20 row_ror:15 row_mask:0xf bank_mask:0xf
	v_mov_b32_dpp v211, v8 row_ror:1 row_mask:0xf bank_mask:0xf
	v_mov_b32_dpp v179, v24 row_ror:15 row_mask:0xf bank_mask:0xf
	v_mov_b32_dpp v219, v5 row_ror:1 row_mask:0xf bank_mask:0xf
	v_mov_b32_dpp v214, v21 row_ror:15 row_mask:0xf bank_mask:0xf
	v_mov_b32_dpp v176, v9 row_ror:1 row_mask:0xf bank_mask:0xf
	v_mov_b32_dpp v3, v25 row_ror:15 row_mask:0xf bank_mask:0xf
	v_mov_b32_dpp v221, v6 row_ror:1 row_mask:0xf bank_mask:0xf
	v_mov_b32_dpp v218, v22 row_ror:15 row_mask:0xf bank_mask:0xf
	v_mov_b32_dpp v213, v10 row_ror:1 row_mask:0xf bank_mask:0xf
	v_mov_b32_dpp v212, v26 row_ror:15 row_mask:0xf bank_mask:0xf
	v_mov_b32_dpp v220, v7 row_ror:1 row_mask:0xf bank_mask:0xf
	v_mov_b32_dpp v216, v23 row_ror:15 row_mask:0xf bank_mask:0xf
	v_mov_b32_dpp v178, v11 row_ror:1 row_mask:0xf bank_mask:0xf
	v_mov_b32_dpp v177, v27 row_ror:15 row_mask:0xf bank_mask:0xf
	v_mov_b32_dpp v217, v12 row_shr:1 row_mask:0xf bank_mask:0xf
	v_mov_b32_dpp v215, v12 row_shl:1 row_mask:0xf bank_mask:0xf
	v_mov_b32_dpp v211, v16 row_shr:1 row_mask:0xf bank_mask:0xf
	v_mov_b32_dpp v179, v16 row_shl:1 row_mask:0xf bank_mask:0xf
	v_mov_b32_dpp v219, v13 row_shr:1 row_mask:0xf bank_mask:0xf
	v_mov_b32_dpp v214, v13 row_shl:1 row_mask:0xf bank_mask:0xf
	v_mov_b32_dpp v176, v17 row_shr:1 row_mask:0xf bank_mask:0xf
	v_mov_b32_dpp v3, v17 row_shl:1 row_mask:0xf bank_mask:0xf
	v_mov_b32_dpp v221, v14 row_shr:1 row_mask:0xf bank_mask:0xf
	v_mov_b32_dpp v218, v14 row_shl:1 row_mask:0xf bank_mask:0xf
	v_mov_b32_dpp v213, v18 row_shr:1 row_mask:0xf bank_mask:0xf
	v_mov_b32_dpp v212, v18 row_shl:1 row_mask:0xf bank_mask:0xf
	v_mov_b32_dpp v220, v15 row_shr:1 row_mask:0xf bank_mask:0xf
	v_mov_b32_dpp v216, v15 row_shl:1 row_mask:0xf bank_mask:0xf
	v_mov_b32_dpp v178, v19 row_shr:1 row_mask:0xf bank_mask:0xf
	v_mov_b32_dpp v177, v19 row_shl:1 row_mask:0xf bank_mask:0xf
	s_and_saveexec_b64 s[16:17], s[12:13]
	s_cbranch_execz .LBB0_319
	v_pk_mul_f32 v[222:223], v[14:15], v[162:163]
	v_pk_mul_f32 v[224:225], v[12:13], v[160:161]
	v_cmp_eq_u32_e64 s[14:15], 0, v210
	v_mov_b32_e32 v226, v224
	v_mov_b32_e32 v227, v222
	v_cndmask_b32_e64 v229, v221, 0, s[14:15]
	v_cmp_eq_u32_e64 s[12:13], s52, v210
	v_mov_b32_e32 v222, v225
	v_cndmask_b32_e64 v228, v217, 0, s[14:15]
	v_cndmask_b32_e64 v225, v220, 0, s[14:15]
	v_mov_b32_e32 v220, v152
	v_mov_b32_e32 v221, v154
	v_cndmask_b32_e64 v224, v219, 0, s[14:15]
	v_pk_fma_f32 v[220:221], v[220:221], v[228:229], v[226:227]
	v_cndmask_b32_e64 v219, v218, 0, s[12:13]
	v_cndmask_b32_e64 v218, v215, 0, s[12:13]
	v_mov_b32_e32 v226, v148
	v_mov_b32_e32 v227, v150
	v_pk_fma_f32 v[218:219], v[226:227], v[218:219], v[220:221]
	v_mov_b32_e32 v220, v144
	v_mov_b32_e32 v221, v146
	v_pk_add_f32 v[218:219], v[220:221], v[218:219]
	v_cndmask_b32_e64 v217, v216, 0, s[12:13]
	v_mul_f32_e32 v210, 0x3d372713, v219
	v_cndmask_b32_e64 v216, v214, 0, s[12:13]
	v_mul_f32_e32 v214, 0x3d372713, v218
	v_mul_f32_e32 v210, v219, v210
	v_mul_f32_e32 v214, v218, v214
	v_fma_f32 v210, v219, v210, v219
	v_fma_f32 v214, v218, v214, v218
	v_mul_f32_e32 v210, 0x3fcc422a, v210
	v_mul_f32_e32 v214, 0x3fcc422a, v214
	v_mul_f32_e32 v210, 0xbfb8aa3b, v210
	v_mul_f32_e32 v214, 0xbfb8aa3b, v214
	v_exp_f32_e32 v210, v210
	v_exp_f32_e32 v214, v214
	v_mov_b32_e32 v220, v153
	v_mov_b32_e32 v221, v155
	v_add_f32_e32 v210, 1.0, v210
	v_add_f32_e32 v214, 1.0, v214
	v_rcp_f32_e32 v215, v210
	v_rcp_f32_e32 v214, v214
	v_pk_fma_f32 v[220:221], v[220:221], v[224:225], v[222:223]
	v_mov_b32_e32 v222, v149
	v_mov_b32_e32 v223, v151
	v_pk_fma_f32 v[216:217], v[222:223], v[216:217], v[220:221]
	v_mov_b32_e32 v220, v145
	v_mov_b32_e32 v221, v147
	v_pk_add_f32 v[216:217], v[220:221], v[216:217]
	v_pk_mul_f32 v[214:215], v[218:219], v[214:215]
	v_mul_f32_e32 v210, 0x3d372713, v216
	v_cndmask_b32_e64 v219, v213, 0, s[14:15]
	v_cndmask_b32_e64 v213, v212, 0, s[12:13]
	v_cndmask_b32_e64 v212, v179, 0, s[12:13]
	v_mul_f32_e32 v179, 0x3d372713, v217
	v_mul_f32_e32 v210, v216, v210
	v_mul_f32_e32 v179, v217, v179
	v_fma_f32 v210, v216, v210, v216
	v_fma_f32 v179, v217, v179, v217
	v_mul_f32_e32 v210, 0x3fcc422a, v210
	v_mul_f32_e32 v179, 0x3fcc422a, v179
	v_mul_f32_e32 v210, 0xbfb8aa3b, v210
	v_mul_f32_e32 v179, 0xbfb8aa3b, v179
	v_exp_f32_e32 v210, v210
	v_exp_f32_e32 v179, v179
	v_pk_mul_f32 v[230:231], v[18:19], v[158:159]
	v_pk_mul_f32 v[232:233], v[16:17], v[156:157]
	v_mov_b32_e32 v235, v230
	v_mov_b32_e32 v234, v232
	v_cndmask_b32_e64 v218, v211, 0, s[14:15]
	v_mov_b32_e32 v220, v140
	v_mov_b32_e32 v221, v142
	v_pk_fma_f32 v[218:219], v[220:221], v[218:219], v[234:235]
	v_mov_b32_e32 v220, v136
	v_mov_b32_e32 v221, v138
	v_add_f32_e32 v210, 1.0, v210
	v_pk_fma_f32 v[212:213], v[220:221], v[212:213], v[218:219]
	v_mov_b32_e32 v218, v132
	v_mov_b32_e32 v219, v134
	v_add_f32_e32 v179, 1.0, v179
	v_rcp_f32_e32 v210, v210
	v_pk_add_f32 v[212:213], v[218:219], v[212:213]
	v_rcp_f32_e32 v211, v179
	v_mov_b32_e32 v230, v233
	v_pk_mul_f32 v[212:213], v[212:213], v[214:215]
	v_cndmask_b32_e64 v179, v178, 0, s[14:15]
	v_cndmask_b32_e64 v178, v176, 0, s[14:15]
	v_mov_b32_e32 v214, v141
	v_mov_b32_e32 v215, v143
	v_pk_fma_f32 v[178:179], v[214:215], v[178:179], v[230:231]
	v_cndmask_b32_e64 v177, v177, 0, s[12:13]
	v_cndmask_b32_e64 v176, v3, 0, s[12:13]
	v_mov_b32_e32 v214, v137
	v_mov_b32_e32 v215, v139
	v_pk_fma_f32 v[176:177], v[214:215], v[176:177], v[178:179]
	v_mov_b32_e32 v178, v133
	v_mov_b32_e32 v179, v135
	v_pk_mul_f32 v[210:211], v[216:217], v[210:211]
	v_pk_add_f32 v[176:177], v[178:179], v[176:177]
	v_and_b32_sdwa v3, v213, v185 dst_sel:DWORD dst_unused:UNUSED_PAD src0_sel:WORD_1 src1_sel:DWORD
	v_pk_mul_f32 v[176:177], v[176:177], v[210:211]
	v_and_b32_sdwa v178, v212, v185 dst_sel:DWORD dst_unused:UNUSED_PAD src0_sel:WORD_1 src1_sel:DWORD
	v_and_b32_sdwa v179, v177, v185 dst_sel:DWORD dst_unused:UNUSED_PAD src0_sel:WORD_1 src1_sel:DWORD
	v_and_b32_sdwa v210, v176, v185 dst_sel:DWORD dst_unused:UNUSED_PAD src0_sel:WORD_1 src1_sel:DWORD
	v_add3_u32 v177, v177, v179, s46
	v_add3_u32 v176, v176, v210, s46
	v_add3_u32 v178, v212, v178, s46
	v_add3_u32 v3, v213, v3, s46
	v_and_b32_e32 v177, 0xffff0000, v177
	v_and_b32_e32 v176, 0xffff0000, v176
	v_readlane_b32 s12, v249, 20
	v_add_lshl_u32 v209, v209, v2, 1
	v_or_b32_sdwa v177, v177, v3 dst_sel:DWORD dst_unused:UNUSED_PAD src0_sel:DWORD src1_sel:WORD_1
	v_or_b32_sdwa v176, v176, v178 dst_sel:DWORD dst_unused:UNUSED_PAD src0_sel:DWORD src1_sel:WORD_1
	v_readlane_b32 s13, v249, 21
	s_nop 4
	global_store_dwordx2 v209, v[176:177], s[12:13]
; __device__ __forceinline__ unsigned pack2(float lo, float hi) { return (unsigned)f2bf(lo) | ((unsigned)f2bf(hi) << 16); }
; __device__ __forceinline__ float sigmoidf_(float x) { return __builtin_amdgcn_rcpf(1.0f + __expf(-x)); }
;     __device__ __forceinline__ void operator()(const f32x4 (&acc)[2][2][4][2], const Unit& u, int wr, int wc, int fr, int fq) const {
;     ...
;             for (int ai = 0; ai < 2; ++ai) { const int tb = u.pm * 248 + 62 * (ai * 2 + wr) - 1;
; #pragma unroll
;                 for (int m = 0; m < 4; ++m) { const int r = 16 * m + fr, t = tb + r, pos = t & (L - 1);
;                     const bool hp = pos != 0, hn = pos != L - 1, valid = (r >= 1) & (r <= 62) & (t < TCH);
;                     float out[4];
; #pragma unroll
;                     for (int e = 0; e < 4; ++e) {
;                         const float xg = acc[ai][bj][m][0][e], xv = acc[ai][bj][m][1][e];
;                         float pg = dppf(m > 0 ? dppf(0.f, acc[ai][bj][m > 0 ? m - 1 : 0][0][e], 2) : 0.f, xg, 0);
;                         float ng = dppf(m < 3 ? dppf(0.f, acc[ai][bj][m < 3 ? m + 1 : 3][0][e], 3) : 0.f, xg, 1);
;                         float pv = dppf(m > 0 ? dppf(0.f, acc[ai][bj][m > 0 ? m - 1 : 0][1][e], 2) : 0.f, xv, 0);
;                         float nv = dppf(m < 3 ? dppf(0.f, acc[ai][bj][m < 3 ? m + 1 : 3][1][e], 3) : 0.f, xv, 1);
;                         if (!hp) { pg = 0.f; pv = 0.f; }
;                         if (!hn) { ng = 0.f; nv = 0.f; }
;                         const float hg = wg0[e] * pg + wg1[e] * xg + wg2[e] * ng + bgv[e], hv = wv0[e] * pv + wv1[e] * xv + wv2[e] * nv + bvv[e];
;                         out[e] = hg * sigmoidf_(1.5957691216f * (hg + 0.044715f * hg * hg * hg)) * hv; }
;                     if (valid) { uint2 o; o.x = pack2(out[0], out[1]); o.y = pack2(out[2], out[3]); *(uint2*)(ws + (unsigned)OFF_S + ((unsigned)t * (unsigned)DFF + (unsigned)J) * 2u) = o; }
;                     __builtin_amdgcn_sched_barrier(0); } } }
.LBB0_319:
	s_or_b64 exec, exec, s[16:17]
	v_mov_b32_dpp v215, v12 row_ror:1 row_mask:0xf bank_mask:0xf
	v_mov_b32_dpp v213, v28 row_ror:15 row_mask:0xf bank_mask:0xf
	v_mov_b32_dpp v209, v16 row_ror:1 row_mask:0xf bank_mask:0xf
	v_mov_b32_dpp v179, v32 row_ror:15 row_mask:0xf bank_mask:0xf
	v_mov_b32_dpp v217, v13 row_ror:1 row_mask:0xf bank_mask:0xf
	v_mov_b32_dpp v212, v29 row_ror:15 row_mask:0xf bank_mask:0xf
	v_mov_b32_dpp v176, v17 row_ror:1 row_mask:0xf bank_mask:0xf
	v_mov_b32_dpp v3, v33 row_ror:15 row_mask:0xf bank_mask:0xf
	v_mov_b32_dpp v219, v14 row_ror:1 row_mask:0xf bank_mask:0xf
	v_mov_b32_dpp v216, v30 row_ror:15 row_mask:0xf bank_mask:0xf
	v_mov_b32_dpp v211, v18 row_ror:1 row_mask:0xf bank_mask:0xf
	v_mov_b32_dpp v210, v34 row_ror:15 row_mask:0xf bank_mask:0xf
	v_mov_b32_dpp v218, v15 row_ror:1 row_mask:0xf bank_mask:0xf
	v_mov_b32_dpp v214, v31 row_ror:15 row_mask:0xf bank_mask:0xf
	v_mov_b32_dpp v178, v19 row_ror:1 row_mask:0xf bank_mask:0xf
	v_mov_b32_dpp v177, v35 row_ror:15 row_mask:0xf bank_mask:0xf
	v_mov_b32_dpp v215, v20 row_shr:1 row_mask:0xf bank_mask:0xf
	v_mov_b32_dpp v213, v20 row_shl:1 row_mask:0xf bank_mask:0xf
	v_mov_b32_dpp v209, v24 row_shr:1 row_mask:0xf bank_mask:0xf
	v_mov_b32_dpp v179, v24 row_shl:1 row_mask:0xf bank_mask:0xf
	v_mov_b32_dpp v217, v21 row_shr:1 row_mask:0xf bank_mask:0xf
	v_mov_b32_dpp v212, v21 row_shl:1 row_mask:0xf bank_mask:0xf
	v_mov_b32_dpp v176, v25 row_shr:1 row_mask:0xf bank_mask:0xf
	v_mov_b32_dpp v3, v25 row_shl:1 row_mask:0xf bank_mask:0xf
	v_mov_b32_dpp v219, v22 row_shr:1 row_mask:0xf bank_mask:0xf
	v_mov_b32_dpp v216, v22 row_shl:1 row_mask:0xf bank_mask:0xf
	v_mov_b32_dpp v211, v26 row_shr:1 row_mask:0xf bank_mask:0xf
	v_mov_b32_dpp v210, v26 row_shl:1 row_mask:0xf bank_mask:0xf
	v_mov_b32_dpp v218, v23 row_shr:1 row_mask:0xf bank_mask:0xf
	v_mov_b32_dpp v214, v23 row_shl:1 row_mask:0xf bank_mask:0xf
	v_mov_b32_dpp v178, v27 row_shr:1 row_mask:0xf bank_mask:0xf
	v_mov_b32_dpp v177, v27 row_shl:1 row_mask:0xf bank_mask:0xf
	s_and_saveexec_b64 s[14:15], vcc
	s_cbranch_execz .LBB0_321
	v_pk_mul_f32 v[220:221], v[22:23], v[162:163]
	v_pk_mul_f32 v[222:223], v[20:21], v[160:161]
	v_cmp_eq_u32_e64 s[12:13], 0, v208
	v_mov_b32_e32 v224, v222
	v_mov_b32_e32 v225, v220
	v_cndmask_b32_e64 v227, v219, 0, s[12:13]
	v_cmp_eq_u32_e32 vcc, s52, v208
	v_mov_b32_e32 v220, v223
	v_cndmask_b32_e64 v226, v215, 0, s[12:13]
	v_cndmask_b32_e64 v223, v218, 0, s[12:13]
	v_mov_b32_e32 v218, v152
	v_mov_b32_e32 v219, v154
	v_cndmask_b32_e64 v222, v217, 0, s[12:13]
	v_pk_fma_f32 v[218:219], v[218:219], v[226:227], v[224:225]
	v_cndmask_b32_e64 v217, v216, 0, vcc
	v_cndmask_b32_e64 v216, v213, 0, vcc
	v_mov_b32_e32 v224, v148
	v_mov_b32_e32 v225, v150
	v_pk_fma_f32 v[216:217], v[224:225], v[216:217], v[218:219]
	v_mov_b32_e32 v218, v144
	v_mov_b32_e32 v219, v146
	v_pk_add_f32 v[216:217], v[218:219], v[216:217]
	v_cndmask_b32_e64 v215, v214, 0, vcc
	v_mul_f32_e32 v208, 0x3d372713, v217
	v_cndmask_b32_e64 v214, v212, 0, vcc
	v_mul_f32_e32 v212, 0x3d372713, v216
	v_mul_f32_e32 v208, v217, v208
	v_mul_f32_e32 v212, v216, v212
	v_fma_f32 v208, v217, v208, v217
	v_fma_f32 v212, v216, v212, v216
	v_mul_f32_e32 v208, 0x3fcc422a, v208
	v_mul_f32_e32 v212, 0x3fcc422a, v212
	v_mul_f32_e32 v208, 0xbfb8aa3b, v208
	v_mul_f32_e32 v212, 0xbfb8aa3b, v212
	v_exp_f32_e32 v208, v208
	v_exp_f32_e32 v212, v212
	v_mov_b32_e32 v218, v153
	v_mov_b32_e32 v219, v155
	v_add_f32_e32 v208, 1.0, v208
	v_add_f32_e32 v212, 1.0, v212
	v_rcp_f32_e32 v213, v208
	v_rcp_f32_e32 v212, v212
	v_pk_fma_f32 v[218:219], v[218:219], v[222:223], v[220:221]
	v_mov_b32_e32 v220, v149
	v_mov_b32_e32 v221, v151
	v_pk_fma_f32 v[214:215], v[220:221], v[214:215], v[218:219]
	v_mov_b32_e32 v218, v145
	v_mov_b32_e32 v219, v147
	v_pk_add_f32 v[214:215], v[218:219], v[214:215]
	v_pk_mul_f32 v[212:213], v[216:217], v[212:213]
	v_mul_f32_e32 v208, 0x3d372713, v214
	v_cndmask_b32_e64 v217, v211, 0, s[12:13]
	v_cndmask_b32_e64 v211, v210, 0, vcc
	v_cndmask_b32_e64 v210, v179, 0, vcc
	v_mul_f32_e32 v179, 0x3d372713, v215
	v_mul_f32_e32 v208, v214, v208
	v_mul_f32_e32 v179, v215, v179
	v_fma_f32 v208, v214, v208, v214
	v_fma_f32 v179, v215, v179, v215
	v_mul_f32_e32 v208, 0x3fcc422a, v208
	v_mul_f32_e32 v179, 0x3fcc422a, v179
	v_mul_f32_e32 v208, 0xbfb8aa3b, v208
	v_mul_f32_e32 v179, 0xbfb8aa3b, v179
	v_exp_f32_e32 v208, v208
	v_exp_f32_e32 v179, v179
	v_pk_mul_f32 v[228:229], v[26:27], v[158:159]
	v_pk_mul_f32 v[230:231], v[24:25], v[156:157]
	v_mov_b32_e32 v233, v228
	v_mov_b32_e32 v232, v230
	v_cndmask_b32_e64 v216, v209, 0, s[12:13]
	v_mov_b32_e32 v218, v140
	v_mov_b32_e32 v219, v142
	v_pk_fma_f32 v[216:217], v[218:219], v[216:217], v[232:233]
	v_mov_b32_e32 v218, v136
	v_mov_b32_e32 v219, v138
	v_add_f32_e32 v208, 1.0, v208
	v_pk_fma_f32 v[210:211], v[218:219], v[210:211], v[216:217]
	v_mov_b32_e32 v216, v132
	v_mov_b32_e32 v217, v134
	v_add_f32_e32 v179, 1.0, v179
	v_rcp_f32_e32 v208, v208
	v_pk_add_f32 v[210:211], v[216:217], v[210:211]
	v_rcp_f32_e32 v209, v179
	v_mov_b32_e32 v228, v231
	v_pk_mul_f32 v[210:211], v[210:211], v[212:213]
	v_cndmask_b32_e64 v179, v178, 0, s[12:13]
	v_cndmask_b32_e64 v178, v176, 0, s[12:13]
	v_mov_b32_e32 v212, v141
	v_mov_b32_e32 v213, v143
	v_pk_fma_f32 v[178:179], v[212:213], v[178:179], v[228:229]
	v_cndmask_b32_e64 v177, v177, 0, vcc
	v_cndmask_b32_e64 v176, v3, 0, vcc
	v_mov_b32_e32 v212, v137
	v_mov_b32_e32 v213, v139
	v_pk_fma_f32 v[176:177], v[212:213], v[176:177], v[178:179]
	v_mov_b32_e32 v178, v133
	v_mov_b32_e32 v179, v135
	v_pk_mul_f32 v[208:209], v[214:215], v[208:209]
	v_pk_add_f32 v[176:177], v[178:179], v[176:177]
	v_and_b32_sdwa v3, v211, v185 dst_sel:DWORD dst_unused:UNUSED_PAD src0_sel:WORD_1 src1_sel:DWORD
	v_pk_mul_f32 v[176:177], v[176:177], v[208:209]
	v_and_b32_sdwa v178, v210, v185 dst_sel:DWORD dst_unused:UNUSED_PAD src0_sel:WORD_1 src1_sel:DWORD
	v_and_b32_sdwa v179, v177, v185 dst_sel:DWORD dst_unused:UNUSED_PAD src0_sel:WORD_1 src1_sel:DWORD
	v_and_b32_sdwa v208, v176, v185 dst_sel:DWORD dst_unused:UNUSED_PAD src0_sel:WORD_1 src1_sel:DWORD
	v_add3_u32 v177, v177, v179, s46
	v_add3_u32 v176, v176, v208, s46
	v_add3_u32 v178, v210, v178, s46
	v_add3_u32 v3, v211, v3, s46
	v_and_b32_e32 v177, 0xffff0000, v177
	v_and_b32_e32 v176, 0xffff0000, v176
	v_readlane_b32 s12, v249, 20
	v_add_lshl_u32 v207, v207, v2, 1
	v_or_b32_sdwa v177, v177, v3 dst_sel:DWORD dst_unused:UNUSED_PAD src0_sel:DWORD src1_sel:WORD_1
	v_or_b32_sdwa v176, v176, v178 dst_sel:DWORD dst_unused:UNUSED_PAD src0_sel:DWORD src1_sel:WORD_1
	v_readlane_b32 s13, v249, 21
	s_nop 4
	global_store_dwordx2 v207, v[176:177], s[12:13]
; __device__ __forceinline__ unsigned pack2(float lo, float hi) { return (unsigned)f2bf(lo) | ((unsigned)f2bf(hi) << 16); }
; __device__ __forceinline__ float sigmoidf_(float x) { return __builtin_amdgcn_rcpf(1.0f + __expf(-x)); }
;     __device__ __forceinline__ void operator()(const f32x4 (&acc)[2][2][4][2], const Unit& u, int wr, int wc, int fr, int fq) const {
;     ...
;             for (int ai = 0; ai < 2; ++ai) { const int tb = u.pm * 248 + 62 * (ai * 2 + wr) - 1;
; #pragma unroll
;                 for (int m = 0; m < 4; ++m) { const int r = 16 * m + fr, t = tb + r, pos = t & (L - 1);
;                     const bool hp = pos != 0, hn = pos != L - 1, valid = (r >= 1) & (r <= 62) & (t < TCH);
;                     float out[4];
; #pragma unroll
;                     for (int e = 0; e < 4; ++e) {
;                         const float xg = acc[ai][bj][m][0][e], xv = acc[ai][bj][m][1][e];
;                         float pg = dppf(m > 0 ? dppf(0.f, acc[ai][bj][m > 0 ? m - 1 : 0][0][e], 2) : 0.f, xg, 0);
;                         float ng = dppf(m < 3 ? dppf(0.f, acc[ai][bj][m < 3 ? m + 1 : 3][0][e], 3) : 0.f, xg, 1);
;                         float pv = dppf(m > 0 ? dppf(0.f, acc[ai][bj][m > 0 ? m - 1 : 0][1][e], 2) : 0.f, xv, 0);
;                         float nv = dppf(m < 3 ? dppf(0.f, acc[ai][bj][m < 3 ? m + 1 : 3][1][e], 3) : 0.f, xv, 1);
;                         if (!hp) { pg = 0.f; pv = 0.f; }
;                         if (!hn) { ng = 0.f; nv = 0.f; }
;                         const float hg = wg0[e] * pg + wg1[e] * xg + wg2[e] * ng + bgv[e], hv = wv0[e] * pv + wv1[e] * xv + wv2[e] * nv + bvv[e];
;                         out[e] = hg * sigmoidf_(1.5957691216f * (hg + 0.044715f * hg * hg * hg)) * hv; }
;                     if (valid) { uint2 o; o.x = pack2(out[0], out[1]); o.y = pack2(out[2], out[3]); *(uint2*)(ws + (unsigned)OFF_S + ((unsigned)t * (unsigned)DFF + (unsigned)J) * 2u) = o; }
;                     __builtin_amdgcn_sched_barrier(0); } } }
.LBB0_321:
	s_or_b64 exec, exec, s[14:15]
	v_mov_b32_dpp v213, v20 row_ror:1 row_mask:0xf bank_mask:0xf
	v_mov_b32_e32 v212, 0
	v_mov_b32_dpp v207, v24 row_ror:1 row_mask:0xf bank_mask:0xf
	v_mov_b32_e32 v178, 0
	v_mov_b32_dpp v211, v21 row_ror:1 row_mask:0xf bank_mask:0xf
	v_mov_b32_e32 v210, 0
	v_mov_b32_dpp v176, v25 row_ror:1 row_mask:0xf bank_mask:0xf
	v_mov_b32_e32 v3, 0
	v_mov_b32_dpp v217, v22 row_ror:1 row_mask:0xf bank_mask:0xf
	v_mov_b32_e32 v216, 0
	v_mov_b32_dpp v209, v26 row_ror:1 row_mask:0xf bank_mask:0xf
	v_mov_b32_e32 v208, 0
	v_mov_b32_dpp v215, v23 row_ror:1 row_mask:0xf bank_mask:0xf
	v_mov_b32_e32 v214, 0
	v_mov_b32_dpp v179, v27 row_ror:1 row_mask:0xf bank_mask:0xf
	v_mov_b32_e32 v177, 0
	v_mov_b32_dpp v213, v28 row_shr:1 row_mask:0xf bank_mask:0xf
	v_mov_b32_dpp v212, v28 row_shl:1 row_mask:0xf bank_mask:0xf
	v_mov_b32_dpp v207, v32 row_shr:1 row_mask:0xf bank_mask:0xf
	v_mov_b32_dpp v178, v32 row_shl:1 row_mask:0xf bank_mask:0xf
	v_mov_b32_dpp v211, v29 row_shr:1 row_mask:0xf bank_mask:0xf
	v_mov_b32_dpp v210, v29 row_shl:1 row_mask:0xf bank_mask:0xf
	v_mov_b32_dpp v176, v33 row_shr:1 row_mask:0xf bank_mask:0xf
	v_mov_b32_dpp v3, v33 row_shl:1 row_mask:0xf bank_mask:0xf
	v_mov_b32_dpp v217, v30 row_shr:1 row_mask:0xf bank_mask:0xf
	v_mov_b32_dpp v216, v30 row_shl:1 row_mask:0xf bank_mask:0xf
	v_mov_b32_dpp v209, v34 row_shr:1 row_mask:0xf bank_mask:0xf
	v_mov_b32_dpp v208, v34 row_shl:1 row_mask:0xf bank_mask:0xf
	v_mov_b32_dpp v215, v31 row_shr:1 row_mask:0xf bank_mask:0xf
	v_mov_b32_dpp v214, v31 row_shl:1 row_mask:0xf bank_mask:0xf
	v_mov_b32_dpp v179, v35 row_shr:1 row_mask:0xf bank_mask:0xf
	v_mov_b32_dpp v177, v35 row_shl:1 row_mask:0xf bank_mask:0xf
	s_and_saveexec_b64 s[14:15], s[64:65]
	s_cbranch_execz .LBB0_323
	v_pk_mul_f32 v[162:163], v[30:31], v[162:163]
	v_pk_mul_f32 v[160:161], v[28:29], v[160:161]
	v_cmp_eq_u32_e32 vcc, 0, v206
	v_mov_b32_e32 v218, v160
	v_mov_b32_e32 v219, v162
	v_cndmask_b32_e64 v221, v217, 0, vcc
	v_mov_b32_e32 v162, v161
	v_cndmask_b32_e64 v220, v213, 0, vcc
	v_mov_b32_e32 v160, v152
	v_mov_b32_e32 v161, v154
	v_cmp_eq_u32_e64 s[12:13], s52, v206
	v_pk_fma_f32 v[160:161], v[160:161], v[220:221], v[218:219]
	v_mov_b32_e32 v217, v150
	v_cndmask_b32_e64 v213, v216, 0, s[12:13]
	v_cndmask_b32_e64 v212, v212, 0, s[12:13]
	v_mov_b32_e32 v216, v148
	v_pk_fma_f32 v[160:161], v[216:217], v[212:213], v[160:161]
	v_mov_b32_e32 v212, v144
	v_mov_b32_e32 v213, v146
	v_pk_add_f32 v[160:161], v[212:213], v[160:161]
	v_pk_mul_f32 v[158:159], v[34:35], v[158:159]
	v_mul_f32_e32 v144, 0x3d372713, v161
	v_mul_f32_e32 v144, v161, v144
	v_fma_f32 v144, v161, v144, v161
	v_mul_f32_e32 v144, 0x3fcc422a, v144
	v_mul_f32_e32 v144, 0xbfb8aa3b, v144
	v_exp_f32_e32 v144, v144
	v_pk_mul_f32 v[156:157], v[32:33], v[156:157]
	v_mov_b32_e32 v223, v158
	v_mov_b32_e32 v222, v156
	v_cndmask_b32_e64 v156, v211, 0, vcc
	v_mov_b32_e32 v158, v157
	v_cndmask_b32_e64 v157, v215, 0, vcc
	v_mov_b32_e32 v154, v153
	v_pk_fma_f32 v[152:153], v[154:155], v[156:157], v[162:163]
	v_cndmask_b32_e64 v155, v214, 0, s[12:13]
	v_cndmask_b32_e64 v154, v210, 0, s[12:13]
	v_mov_b32_e32 v150, v149
	v_add_f32_e32 v144, 1.0, v144
	v_pk_fma_f32 v[148:149], v[150:151], v[154:155], v[152:153]
	v_mov_b32_e32 v146, v145
	v_rcp_f32_e32 v211, v144
	v_pk_add_f32 v[144:145], v[146:147], v[148:149]
	v_add_lshl_u32 v0, v0, v2, 1
	v_mul_f32_e32 v146, 0x3d372713, v144
	v_mul_f32_e32 v146, v144, v146
	v_fma_f32 v146, v144, v146, v144
	v_mul_f32_e32 v146, 0x3fcc422a, v146
	v_mul_f32_e32 v146, 0xbfb8aa3b, v146
	v_exp_f32_e32 v146, v146
	v_mul_f32_e32 v147, 0x3d372713, v160
	v_mul_f32_e32 v147, v160, v147
	v_fma_f32 v147, v160, v147, v160
	v_add_f32_e32 v2, 1.0, v146
	v_rcp_f32_e32 v146, v2
	v_mul_f32_e32 v2, 0x3d372713, v145
	v_mul_f32_e32 v2, v145, v2
	v_fma_f32 v2, v145, v2, v145
	v_mul_f32_e32 v147, 0x3fcc422a, v147
	v_mul_f32_e32 v2, 0x3fcc422a, v2
	v_mul_f32_e32 v147, 0xbfb8aa3b, v147
	v_mul_f32_e32 v2, 0xbfb8aa3b, v2
	v_exp_f32_e32 v147, v147
	v_exp_f32_e32 v2, v2
	v_cndmask_b32_e64 v151, v209, 0, vcc
	v_cndmask_b32_e64 v150, v207, 0, vcc
	v_add_f32_e32 v147, 1.0, v147
	v_add_f32_e32 v2, 1.0, v2
	v_rcp_f32_e32 v210, v147
	v_rcp_f32_e32 v147, v2
	v_mov_b32_e32 v152, v140
	v_mov_b32_e32 v153, v142
	v_mov_b32_e32 v142, v141
	v_pk_mul_f32 v[144:145], v[144:145], v[146:147]
	v_cndmask_b32_e64 v147, v179, 0, vcc
	v_cndmask_b32_e64 v146, v176, 0, vcc
	v_pk_fma_f32 v[150:151], v[152:153], v[150:151], v[222:223]
	v_cndmask_b32_e64 v153, v208, 0, s[12:13]
	v_cndmask_b32_e64 v152, v178, 0, s[12:13]
	v_mov_b32_e32 v154, v136
	v_mov_b32_e32 v155, v138
	v_pk_fma_f32 v[140:141], v[142:143], v[146:147], v[158:159]
	v_cndmask_b32_e64 v143, v177, 0, s[12:13]
	v_cndmask_b32_e64 v142, v3, 0, s[12:13]
	v_mov_b32_e32 v138, v137
	v_pk_fma_f32 v[150:151], v[154:155], v[152:153], v[150:151]
	v_mov_b32_e32 v153, v134
	v_pk_fma_f32 v[2:3], v[138:139], v[142:143], v[140:141]
	v_mov_b32_e32 v134, v133
	v_mov_b32_e32 v152, v132
	v_pk_add_f32 v[2:3], v[134:135], v[2:3]
	v_pk_mul_f32 v[148:149], v[160:161], v[210:211]
	v_pk_add_f32 v[150:151], v[152:153], v[150:151]
	v_pk_mul_f32 v[2:3], v[2:3], v[144:145]
	v_pk_mul_f32 v[148:149], v[150:151], v[148:149]
	v_and_b32_sdwa v134, v3, v185 dst_sel:DWORD dst_unused:UNUSED_PAD src0_sel:WORD_1 src1_sel:DWORD
	v_and_b32_sdwa v135, v2, v185 dst_sel:DWORD dst_unused:UNUSED_PAD src0_sel:WORD_1 src1_sel:DWORD
	v_and_b32_sdwa v132, v149, v185 dst_sel:DWORD dst_unused:UNUSED_PAD src0_sel:WORD_1 src1_sel:DWORD
	v_and_b32_sdwa v133, v148, v185 dst_sel:DWORD dst_unused:UNUSED_PAD src0_sel:WORD_1 src1_sel:DWORD
	v_add3_u32 v3, v3, v134, s46
	v_add3_u32 v2, v2, v135, s46
	v_add3_u32 v133, v148, v133, s46
	v_add3_u32 v132, v149, v132, s46
	v_and_b32_e32 v3, 0xffff0000, v3
	v_and_b32_e32 v2, 0xffff0000, v2
	v_readlane_b32 s12, v249, 20
	v_or_b32_sdwa v3, v3, v132 dst_sel:DWORD dst_unused:UNUSED_PAD src0_sel:DWORD src1_sel:WORD_1
	v_or_b32_sdwa v2, v2, v133 dst_sel:DWORD dst_unused:UNUSED_PAD src0_sel:DWORD src1_sel:WORD_1
	v_readlane_b32 s13, v249, 21
	s_nop 4
	global_store_dwordx2 v0, v[2:3], s[12:13]
